# GEMM K-loops: per-segment s_setprio flips deleted and the redundant lgkmcnt(0) after the pre-MFMA barrier dropped (already waited before the barrier)
# baseline (speedup 1.0000x reference)
;     __host__ __device__ bool next(int i, Unit& u) const { const long L = (long)i * G + c; if (L >= maxL) return false; return unit_of(L, u); }
;     __device__ __forceinline__ const char* a_base(const Gemm& g, const Unit& u, size_t tstep) const { return (const char*)g.A + (size_t)u.pm * tstep; }
;     __device__ __forceinline__ const char* b_base(const Gemm& g, const Unit& u, size_t tstep) const { return (const char*)g.Bt + (size_t)u.pn * tstep; }
; #define PG8_STAGE(bufoff, gbase, voff) do { _Pragma("unroll") for (int _i = 0; _i < 2; ++_i) \
;         __builtin_amdgcn_global_load_lds((const unsigned*)((const char*)(gbase) + (voff)[_i]), (PG8_LAS unsigned*)(lds + (bufoff) + ldsw + _i * 8192), 16, 0, 0); } while (0)
; #define PG8_WAIT_V(n) asm volatile("s_waitcnt vmcnt(" #n ")" ::: "memory")
; #define PG8_WAIT_L(n) asm volatile("s_waitcnt lgkmcnt(" #n ")" ::: "memory")
; template <class Epi, class Sched, bool ALIGN_EPI = false, bool SP2 = false>
; __device__ __forceinline__ void gemm_phase(PG8_LAS unsigned char* lds, const Gemm g, const Sched& S, const Epi& E, const int wave_id_in) {
;     ...
;         const bool has_next = S.next(ui + 1, nxt);
;         const char* nA = has_next ? S.a_base(g, nxt, tstep) : cA; const char* nB = has_next ? S.b_base(g, nxt, tstep) : cB;
;         for (int t = 0; t < nt; t += 2) {
;             const bool last = (t == nt - 2);
;             const char* a1 = cA + (size_t)(t + 1) * kstep;
;             const char* a2 = last ? nA : cA + (size_t)(t + 2) * kstep; const char* b2 = last ? nB : cB + (size_t)(t + 2) * kstep;
;             const char* a3 = a2 + kstep; const char* b3 = b2 + kstep;
;             if (last && has_next) S.a_ready(nxt);
;             if constexpr (SP2) {
;             PG8_LDB(B0, 0, 0); PG8_LDB(B1, 0, 1); PG8_SCHED; PG8_LDA(At, 0, 0); PG8_STAGE(PG8_SA(1, 1), a1 + hstep, voffA);
;             PG8_WAIT_V(8); PG8_WAIT_L(0); PG8_BAR; __builtin_amdgcn_s_setprio(1); PG8_MMA(0, 0, At, B0); PG8_MMA(0, 1, At, B1); __builtin_amdgcn_s_setprio(0); PG8_BAR; PG8_SCHED;
;             PG8_LDA(At, 0, 1); PG8_STAGE(PG8_SB(0, 0), b2, voffB); PG8_STAGE(PG8_SB(0, 1), b2 + hstep, voffB); PG8_STAGE(PG8_SA(0, 0), a2, voffA);
;             PG8_WAIT_V(8); PG8_WAIT_L(0); PG8_BAR; __builtin_amdgcn_s_setprio(1); PG8_MMA(1, 0, At, B0); PG8_MMA(1, 1, At, B1); __builtin_amdgcn_s_setprio(0); PG8_BAR; PG8_SCHED;
.LBB0_131:
	s_ashr_i32 s57, s56, 31
	s_lshl_b64 s[38:39], s[56:57], 20
	s_add_u32 s60, s47, s38
	s_addc_u32 s61, s49, s39
	s_and_b64 s[38:39], s[58:59], exec
	s_cselect_b32 s25, s61, s7
	s_cselect_b32 s26, s60, s6
	s_ashr_i32 s55, s54, 31
	s_lshl_b64 s[38:39], s[54:55], 20
	s_add_u32 s62, s75, s38
	s_addc_u32 s63, s78, s39
	s_and_b64 s[38:39], s[58:59], exec
	s_cselect_b32 s38, s63, s69
	s_cselect_b32 s39, s62, s68
	s_add_u32 s6, s6, 0x80080
	s_addc_u32 s7, s7, 0
	s_add_u32 s42, s68, 0x100
	s_addc_u32 s43, s69, 0
	s_mov_b32 s55, -2
	ds_read_b128 v[128:131], v221
	ds_read_b128 v[132:135], v221 offset:1024
	ds_read_b128 v[136:139], v221 offset:2048
	ds_read_b128 v[140:143], v221 offset:3072
	ds_read_b128 v[144:147], v222
	ds_read_b128 v[148:151], v222 offset:1024
	ds_read_b128 v[152:155], v222 offset:2048
	ds_read_b128 v[156:159], v222 offset:3072
	s_add_u32 s40, s6, 0xfff80080
	s_addc_u32 s41, s7, -1
	s_cmp_eq_u32 s55, 28
	s_cselect_b32 s71, s25, s41
	s_cselect_b32 s70, s26, s40
	s_cselect_b32 s69, s38, s43
	s_cselect_b32 s68, s39, s42
	v_lshl_add_u64 v[192:193], s[6:7], 0, v[206:207]
	s_add_i32 m0, s65, 0xc000
	ds_read_b128 v[160:163], v223
	ds_read_b128 v[164:167], v223 offset:1024
	ds_read_b128 v[168:171], v223 offset:2048
	ds_read_b128 v[172:175], v223 offset:3072
	ds_read_b128 v[176:179], v223 offset:4096
	ds_read_b128 v[180:183], v223 offset:5120
	ds_read_b128 v[184:187], v223 offset:6144
	ds_read_b128 v[188:191], v223 offset:7168
	global_load_lds_dwordx4 v[192:193], off
	v_lshl_add_u64 v[192:193], s[6:7], 0, v[208:209]
	s_add_i32 m0, s65, 0xe000
	s_nop 0
	global_load_lds_dwordx4 v[192:193], off
	s_waitcnt vmcnt(8)
	s_waitcnt lgkmcnt(0)
	s_barrier
	v_mfma_f32_16x16x32_bf16 v[124:127], v[128:131], v[160:163], 0
	v_mfma_f32_16x16x32_bf16 v[120:123], v[136:139], v[160:163], 0
	v_mfma_f32_16x16x32_bf16 v[108:111], v[128:131], v[168:171], 0
	v_mfma_f32_16x16x32_bf16 v[104:107], v[136:139], v[168:171], 0
	v_mfma_f32_16x16x32_bf16 v[92:95], v[128:131], v[176:179], 0
	v_mfma_f32_16x16x32_bf16 v[88:91], v[136:139], v[176:179], 0
	v_mfma_f32_16x16x32_bf16 v[76:79], v[128:131], v[184:187], 0
	v_mfma_f32_16x16x32_bf16 v[72:75], v[136:139], v[184:187], 0
	v_mfma_f32_16x16x32_bf16 v[116:119], v[144:147], v[160:163], 0
	v_mfma_f32_16x16x32_bf16 v[112:115], v[152:155], v[160:163], 0
	v_mfma_f32_16x16x32_bf16 v[100:103], v[144:147], v[168:171], 0
	v_mfma_f32_16x16x32_bf16 v[96:99], v[152:155], v[168:171], 0
	v_mfma_f32_16x16x32_bf16 v[84:87], v[144:147], v[176:179], 0
	v_mfma_f32_16x16x32_bf16 v[80:83], v[152:155], v[176:179], 0
	v_mfma_f32_16x16x32_bf16 v[68:71], v[144:147], v[184:187], 0
	v_mfma_f32_16x16x32_bf16 v[64:67], v[152:155], v[184:187], 0
	v_mfma_f32_16x16x32_bf16 v[124:127], v[132:135], v[164:167], v[124:127]
	v_mfma_f32_16x16x32_bf16 v[120:123], v[140:143], v[164:167], v[120:123]
	v_mfma_f32_16x16x32_bf16 v[108:111], v[132:135], v[172:175], v[108:111]
	v_mfma_f32_16x16x32_bf16 v[104:107], v[140:143], v[172:175], v[104:107]
	v_mfma_f32_16x16x32_bf16 v[92:95], v[132:135], v[180:183], v[92:95]
	v_mfma_f32_16x16x32_bf16 v[88:91], v[140:143], v[180:183], v[88:91]
	v_mfma_f32_16x16x32_bf16 v[76:79], v[132:135], v[188:191], v[76:79]
	v_mfma_f32_16x16x32_bf16 v[72:75], v[140:143], v[188:191], v[72:75]
	v_mfma_f32_16x16x32_bf16 v[116:119], v[148:151], v[164:167], v[116:119]
	v_mfma_f32_16x16x32_bf16 v[112:115], v[156:159], v[164:167], v[112:115]
	v_mfma_f32_16x16x32_bf16 v[100:103], v[148:151], v[172:175], v[100:103]
	v_mfma_f32_16x16x32_bf16 v[96:99], v[156:159], v[172:175], v[96:99]
	v_mfma_f32_16x16x32_bf16 v[84:87], v[148:151], v[180:183], v[84:87]
	v_mfma_f32_16x16x32_bf16 v[80:83], v[156:159], v[180:183], v[80:83]
	v_mfma_f32_16x16x32_bf16 v[68:71], v[148:151], v[188:191], v[68:71]
	v_mfma_f32_16x16x32_bf16 v[64:67], v[156:159], v[188:191], v[64:67]
	s_barrier
	s_add_i32 s40, s93, s80
	v_lshl_add_u64 v[192:193], s[68:69], 0, v[200:201]
	s_mov_b32 m0, s40
	ds_read_b128 v[160:163], v223 offset:16384
	ds_read_b128 v[164:167], v223 offset:17408
	ds_read_b128 v[168:171], v223 offset:18432
	ds_read_b128 v[172:175], v223 offset:19456
	ds_read_b128 v[176:179], v223 offset:20480
	ds_read_b128 v[180:183], v223 offset:21504
	ds_read_b128 v[184:187], v223 offset:22528
	ds_read_b128 v[188:191], v223 offset:23552
	global_load_lds_dwordx4 v[192:193], off
	s_add_i32 m0, s40, 0x2000
	s_add_u32 s72, s68, 0x80000
	v_lshl_add_u64 v[194:195], s[68:69], 0, v[202:203]
	s_addc_u32 s73, s69, 0
	s_add_i32 s40, s94, s80
	global_load_lds_dwordx4 v[194:195], off
	v_lshl_add_u64 v[196:197], s[72:73], 0, v[200:201]
	s_mov_b32 m0, s40
	v_lshl_add_u64 v[198:199], s[70:71], 0, v[202:203]
	global_load_lds_dwordx4 v[196:197], off
	v_lshl_add_u64 v[196:197], s[72:73], 0, v[202:203]
	s_add_i32 m0, s40, 0x2000
	s_nop 0
	global_load_lds_dwordx4 v[196:197], off
	v_lshl_add_u64 v[196:197], s[70:71], 0, v[200:201]
	s_mov_b32 m0, s65
	s_nop 0
	global_load_lds_dwordx4 v[196:197], off
	s_mov_b32 m0, s67
	s_nop 0
	global_load_lds_dwordx4 v[198:199], off
	s_waitcnt vmcnt(8)
	s_waitcnt lgkmcnt(0)
	s_barrier
; #define PG8_STAGE(bufoff, gbase, voff) do { _Pragma("unroll") for (int _i = 0; _i < 2; ++_i) \
;         __builtin_amdgcn_global_load_lds((const unsigned*)((const char*)(gbase) + (voff)[_i]), (PG8_LAS unsigned*)(lds + (bufoff) + ldsw + _i * 8192), 16, 0, 0); } while (0)
; #define PG8_LDA(dst, b, h) do { _Pragma("unroll") for (int m = 0; m < 4; ++m) _Pragma("unroll") for (int k = 0; k < 2; ++k) dst[m][k] = *(const PG8_LAS bf16x8*)(lds + PG8_SA(b, h) + aoff + m * 2048 + k * 1024); } while (0)
; #define PG8_LDB(dst, b, h) do { _Pragma("unroll") for (int n = 0; n < 2; ++n) _Pragma("unroll") for (int k = 0; k < 2; ++k) dst[n][k] = *(const PG8_LAS bf16x8*)(lds + PG8_SB(b, h) + boff + n * 2048 + k * 1024); } while (0)
; #define PG8_MMA(ai, bj, At, Bt) do { _Pragma("unroll") for (int m = 0; m < 4; ++m) _Pragma("unroll") for (int n = 0; n < 2; ++n) _Pragma("unroll") for (int k = 0; k < 2; ++k) \
;         acc[ai][bj][m][n] = __builtin_amdgcn_mfma_f32_16x16x32_bf16(Bt[n][k], At[m][k], acc[ai][bj][m][n], 0, 0, 0); } while (0)
; #define PG8_WAIT_V(n) asm volatile("s_waitcnt vmcnt(" #n ")" ::: "memory")
; #define PG8_WAIT_L(n) asm volatile("s_waitcnt lgkmcnt(" #n ")" ::: "memory")
; #define PG8_BAR __builtin_amdgcn_s_barrier()
; #define PG8_SCHED __builtin_amdgcn_sched_barrier(0)
; template <class Epi, class Sched, bool ALIGN_EPI = false, bool SP2 = false>
; __device__ __forceinline__ void gemm_phase(PG8_LAS unsigned char* lds, const Gemm g, const Sched& S, const Epi& E, const int wave_id_in) {
;     ...
;             PG8_WAIT_V(8); PG8_WAIT_L(0); PG8_BAR; __builtin_amdgcn_s_setprio(1); PG8_MMA(1, 0, At, B0); PG8_MMA(1, 1, At, B1); __builtin_amdgcn_s_setprio(0); PG8_BAR; PG8_SCHED;
;             PG8_LDB(B0, 1, 0); PG8_LDB(B1, 1, 1); PG8_SCHED; PG8_LDA(At, 1, 0); PG8_STAGE(PG8_SA(0, 1), a2 + hstep, voffA);
;             PG8_WAIT_V(8); PG8_WAIT_L(0); PG8_BAR; __builtin_amdgcn_s_setprio(1); PG8_MMA(0, 0, At, B0); PG8_MMA(0, 1, At, B1); __builtin_amdgcn_s_setprio(0); PG8_BAR; PG8_SCHED;
	v_mfma_f32_16x16x32_bf16 v[60:63], v[128:131], v[160:163], 0
	v_mfma_f32_16x16x32_bf16 v[56:59], v[136:139], v[160:163], 0
	v_mfma_f32_16x16x32_bf16 v[44:47], v[128:131], v[168:171], 0
	v_mfma_f32_16x16x32_bf16 v[40:43], v[136:139], v[168:171], 0
	v_mfma_f32_16x16x32_bf16 v[28:31], v[128:131], v[176:179], 0
	v_mfma_f32_16x16x32_bf16 v[24:27], v[136:139], v[176:179], 0
	v_mfma_f32_16x16x32_bf16 v[12:15], v[128:131], v[184:187], 0
	v_mfma_f32_16x16x32_bf16 v[8:11], v[136:139], v[184:187], 0
	v_mfma_f32_16x16x32_bf16 v[52:55], v[144:147], v[160:163], 0
	v_mfma_f32_16x16x32_bf16 v[48:51], v[152:155], v[160:163], 0
	v_mfma_f32_16x16x32_bf16 v[36:39], v[144:147], v[168:171], 0
	v_mfma_f32_16x16x32_bf16 v[32:35], v[152:155], v[168:171], 0
	v_mfma_f32_16x16x32_bf16 v[20:23], v[144:147], v[176:179], 0
	v_mfma_f32_16x16x32_bf16 v[16:19], v[152:155], v[176:179], 0
	v_mfma_f32_16x16x32_bf16 v[4:7], v[144:147], v[184:187], 0
	v_mfma_f32_16x16x32_bf16 v[0:3], v[152:155], v[184:187], 0
	v_mfma_f32_16x16x32_bf16 v[60:63], v[132:135], v[164:167], v[60:63]
	v_mfma_f32_16x16x32_bf16 v[56:59], v[140:143], v[164:167], v[56:59]
	v_mfma_f32_16x16x32_bf16 v[44:47], v[132:135], v[172:175], v[44:47]
	v_mfma_f32_16x16x32_bf16 v[40:43], v[140:143], v[172:175], v[40:43]
	v_mfma_f32_16x16x32_bf16 v[28:31], v[132:135], v[180:183], v[28:31]
	v_mfma_f32_16x16x32_bf16 v[24:27], v[140:143], v[180:183], v[24:27]
	v_mfma_f32_16x16x32_bf16 v[12:15], v[132:135], v[188:191], v[12:15]
	v_mfma_f32_16x16x32_bf16 v[8:11], v[140:143], v[188:191], v[8:11]
	v_mfma_f32_16x16x32_bf16 v[52:55], v[148:151], v[164:167], v[52:55]
	v_mfma_f32_16x16x32_bf16 v[48:51], v[156:159], v[164:167], v[48:51]
	v_mfma_f32_16x16x32_bf16 v[36:39], v[148:151], v[172:175], v[36:39]
	v_mfma_f32_16x16x32_bf16 v[32:35], v[156:159], v[172:175], v[32:35]
	v_mfma_f32_16x16x32_bf16 v[20:23], v[148:151], v[180:183], v[20:23]
	v_mfma_f32_16x16x32_bf16 v[16:19], v[156:159], v[180:183], v[16:19]
	v_mfma_f32_16x16x32_bf16 v[4:7], v[148:151], v[188:191], v[4:7]
	v_mfma_f32_16x16x32_bf16 v[0:3], v[156:159], v[188:191], v[0:3]
	s_barrier
	s_add_i32 s40, 0, 0x18000
	s_add_i32 s41, 0, 0x1c000
	v_add_u32_e32 v140, s40, v220
	v_add_u32_e32 v156, s41, v220
	ds_read_b128 v[128:131], v140
	ds_read_b128 v[132:135], v140 offset:1024
	ds_read_b128 v[136:139], v140 offset:2048
	ds_read_b128 v[140:143], v140 offset:3072
	ds_read_b128 v[144:147], v156
	ds_read_b128 v[148:151], v156 offset:1024
	ds_read_b128 v[152:155], v156 offset:2048
	ds_read_b128 v[156:159], v156 offset:3072
	s_add_u32 s70, s70, 0x80000
	s_addc_u32 s71, s71, 0
	s_mov_b32 m0, s81
	v_lshl_add_u64 v[214:215], s[70:71], 0, v[200:201]
	ds_read_b128 v[160:163], v223 offset:32768
	ds_read_b128 v[164:167], v223 offset:33792
	ds_read_b128 v[168:171], v223 offset:34816
	ds_read_b128 v[172:175], v223 offset:35840
	ds_read_b128 v[176:179], v223 offset:36864
	ds_read_b128 v[180:183], v223 offset:37888
	ds_read_b128 v[184:187], v223 offset:38912
	ds_read_b128 v[188:191], v223 offset:39936
	global_load_lds_dwordx4 v[214:215], off
	v_lshl_add_u64 v[214:215], s[70:71], 0, v[202:203]
	s_mov_b32 m0, s82
	s_nop 0
	global_load_lds_dwordx4 v[214:215], off
	s_waitcnt vmcnt(8)
	s_waitcnt lgkmcnt(0)
	s_barrier
	v_mfma_f32_16x16x32_bf16 v[124:127], v[128:131], v[160:163], v[124:127]
	v_mfma_f32_16x16x32_bf16 v[120:123], v[136:139], v[160:163], v[120:123]
	v_mfma_f32_16x16x32_bf16 v[108:111], v[128:131], v[168:171], v[108:111]
	v_mfma_f32_16x16x32_bf16 v[104:107], v[136:139], v[168:171], v[104:107]
	v_mfma_f32_16x16x32_bf16 v[92:95], v[128:131], v[176:179], v[92:95]
	v_mfma_f32_16x16x32_bf16 v[88:91], v[136:139], v[176:179], v[88:91]
	v_mfma_f32_16x16x32_bf16 v[76:79], v[128:131], v[184:187], v[76:79]
	v_mfma_f32_16x16x32_bf16 v[72:75], v[136:139], v[184:187], v[72:75]
	v_mfma_f32_16x16x32_bf16 v[116:119], v[144:147], v[160:163], v[116:119]
	v_mfma_f32_16x16x32_bf16 v[112:115], v[152:155], v[160:163], v[112:115]
	v_mfma_f32_16x16x32_bf16 v[100:103], v[144:147], v[168:171], v[100:103]
	v_mfma_f32_16x16x32_bf16 v[96:99], v[152:155], v[168:171], v[96:99]
	v_mfma_f32_16x16x32_bf16 v[84:87], v[144:147], v[176:179], v[84:87]
	v_mfma_f32_16x16x32_bf16 v[80:83], v[152:155], v[176:179], v[80:83]
	v_mfma_f32_16x16x32_bf16 v[68:71], v[144:147], v[184:187], v[68:71]
	v_mfma_f32_16x16x32_bf16 v[64:67], v[152:155], v[184:187], v[64:67]
	v_mfma_f32_16x16x32_bf16 v[124:127], v[132:135], v[164:167], v[124:127]
	v_mfma_f32_16x16x32_bf16 v[120:123], v[140:143], v[164:167], v[120:123]
	v_mfma_f32_16x16x32_bf16 v[108:111], v[132:135], v[172:175], v[108:111]
	v_mfma_f32_16x16x32_bf16 v[104:107], v[140:143], v[172:175], v[104:107]
	v_mfma_f32_16x16x32_bf16 v[92:95], v[132:135], v[180:183], v[92:95]
	v_mfma_f32_16x16x32_bf16 v[88:91], v[140:143], v[180:183], v[88:91]
	v_mfma_f32_16x16x32_bf16 v[76:79], v[132:135], v[188:191], v[76:79]
	v_mfma_f32_16x16x32_bf16 v[72:75], v[140:143], v[188:191], v[72:75]
	v_mfma_f32_16x16x32_bf16 v[116:119], v[148:151], v[164:167], v[116:119]
	v_mfma_f32_16x16x32_bf16 v[112:115], v[156:159], v[164:167], v[112:115]
	v_mfma_f32_16x16x32_bf16 v[100:103], v[148:151], v[172:175], v[100:103]
	v_mfma_f32_16x16x32_bf16 v[96:99], v[156:159], v[172:175], v[96:99]
	v_mfma_f32_16x16x32_bf16 v[84:87], v[148:151], v[180:183], v[84:87]
	v_mfma_f32_16x16x32_bf16 v[80:83], v[156:159], v[180:183], v[80:83]
	v_mfma_f32_16x16x32_bf16 v[68:71], v[148:151], v[188:191], v[68:71]
	v_mfma_f32_16x16x32_bf16 v[64:67], v[156:159], v[188:191], v[64:67]
	s_barrier
; #define PG8_STAGE(bufoff, gbase, voff) do { _Pragma("unroll") for (int _i = 0; _i < 2; ++_i) \
;         __builtin_amdgcn_global_load_lds((const unsigned*)((const char*)(gbase) + (voff)[_i]), (PG8_LAS unsigned*)(lds + (bufoff) + ldsw + _i * 8192), 16, 0, 0); } while (0)
; #define PG8_LDA(dst, b, h) do { _Pragma("unroll") for (int m = 0; m < 4; ++m) _Pragma("unroll") for (int k = 0; k < 2; ++k) dst[m][k] = *(const PG8_LAS bf16x8*)(lds + PG8_SA(b, h) + aoff + m * 2048 + k * 1024); } while (0)
; #define PG8_LDB(dst, b, h) do { _Pragma("unroll") for (int n = 0; n < 2; ++n) _Pragma("unroll") for (int k = 0; k < 2; ++k) dst[n][k] = *(const PG8_LAS bf16x8*)(lds + PG8_SB(b, h) + boff + n * 2048 + k * 1024); } while (0)
; #define PG8_MMA(ai, bj, At, Bt) do { _Pragma("unroll") for (int m = 0; m < 4; ++m) _Pragma("unroll") for (int n = 0; n < 2; ++n) _Pragma("unroll") for (int k = 0; k < 2; ++k) \
;         acc[ai][bj][m][n] = __builtin_amdgcn_mfma_f32_16x16x32_bf16(Bt[n][k], At[m][k], acc[ai][bj][m][n], 0, 0, 0); } while (0)
; #define PG8_WAIT_V(n) asm volatile("s_waitcnt vmcnt(" #n ")" ::: "memory")
; #define PG8_WAIT_L(n) asm volatile("s_waitcnt lgkmcnt(" #n ")" ::: "memory")
; #define PG8_BAR __builtin_amdgcn_s_barrier()
; #define PG8_SCHED __builtin_amdgcn_sched_barrier(0)
; template <class Epi, class Sched, bool ALIGN_EPI = false, bool SP2 = false>
; __device__ __forceinline__ void gemm_phase(PG8_LAS unsigned char* lds, const Gemm g, const Sched& S, const Epi& E, const int wave_id_in) {
;     ...
;             PG8_LDB(B0, 0, 0); PG8_LDB(B1, 0, 1); PG8_SCHED; PG8_LDA(At, 0, 0); PG8_STAGE(PG8_SA(1, 1), a1 + hstep, voffA);
;             PG8_WAIT_V(8); PG8_WAIT_L(0); PG8_BAR; __builtin_amdgcn_s_setprio(1); PG8_MMA(0, 0, At, B0); PG8_MMA(0, 1, At, B1); __builtin_amdgcn_s_setprio(0); PG8_BAR; PG8_SCHED;
;     ...
;             PG8_LDA(At, 1, 1); PG8_STAGE(PG8_SB(1, 0), b3, voffB); PG8_STAGE(PG8_SB(1, 1), b3 + hstep, voffB); PG8_STAGE(PG8_SA(1, 0), a3, voffA);
;             PG8_WAIT_V(8); PG8_WAIT_L(0); PG8_BAR; __builtin_amdgcn_s_setprio(1); PG8_MMA(1, 0, At, B0); PG8_MMA(1, 1, At, B1); __builtin_amdgcn_s_setprio(0); PG8_BAR; PG8_SCHED;
	s_add_i32 s40, s40, s80
	v_lshl_add_u64 v[192:193], v[192:193], 0, s[30:31]
	s_mov_b32 m0, s40
	ds_read_b128 v[160:163], v223 offset:49152
	ds_read_b128 v[164:167], v223 offset:50176
	ds_read_b128 v[168:171], v223 offset:51200
	ds_read_b128 v[172:175], v223 offset:52224
	ds_read_b128 v[176:179], v223 offset:53248
	ds_read_b128 v[180:183], v223 offset:54272
	ds_read_b128 v[184:187], v223 offset:55296
	ds_read_b128 v[188:191], v223 offset:56320
	global_load_lds_dwordx4 v[192:193], off
	s_add_i32 m0, s40, 0x2000
	s_add_u32 s68, s68, 0x80080
	v_lshl_add_u64 v[192:193], v[194:195], 0, s[30:31]
	s_addc_u32 s69, s69, 0
	s_add_i32 s40, s41, s80
	global_load_lds_dwordx4 v[192:193], off
	v_lshl_add_u64 v[192:193], s[68:69], 0, v[200:201]
	s_mov_b32 m0, s40
	s_nop 0
	global_load_lds_dwordx4 v[192:193], off
	v_lshl_add_u64 v[192:193], s[68:69], 0, v[202:203]
	s_add_i32 m0, s40, 0x2000
	s_nop 0
	global_load_lds_dwordx4 v[192:193], off
	v_lshl_add_u64 v[192:193], v[196:197], 0, s[30:31]
	s_mov_b32 m0, s86
	s_nop 0
	global_load_lds_dwordx4 v[192:193], off
	v_lshl_add_u64 v[192:193], v[198:199], 0, s[30:31]
	s_mov_b32 m0, s87
	s_nop 0
	global_load_lds_dwordx4 v[192:193], off
	s_waitcnt vmcnt(8)
	s_waitcnt lgkmcnt(0)
	s_barrier
	v_mfma_f32_16x16x32_bf16 v[60:63], v[128:131], v[160:163], v[60:63]
	v_mfma_f32_16x16x32_bf16 v[56:59], v[136:139], v[160:163], v[56:59]
	v_mfma_f32_16x16x32_bf16 v[44:47], v[128:131], v[168:171], v[44:47]
	v_mfma_f32_16x16x32_bf16 v[40:43], v[136:139], v[168:171], v[40:43]
	v_mfma_f32_16x16x32_bf16 v[28:31], v[128:131], v[176:179], v[28:31]
	v_mfma_f32_16x16x32_bf16 v[24:27], v[136:139], v[176:179], v[24:27]
	v_mfma_f32_16x16x32_bf16 v[12:15], v[128:131], v[184:187], v[12:15]
	v_mfma_f32_16x16x32_bf16 v[8:11], v[136:139], v[184:187], v[8:11]
	v_mfma_f32_16x16x32_bf16 v[52:55], v[144:147], v[160:163], v[52:55]
	v_mfma_f32_16x16x32_bf16 v[48:51], v[152:155], v[160:163], v[48:51]
	v_mfma_f32_16x16x32_bf16 v[36:39], v[144:147], v[168:171], v[36:39]
	v_mfma_f32_16x16x32_bf16 v[32:35], v[152:155], v[168:171], v[32:35]
	v_mfma_f32_16x16x32_bf16 v[20:23], v[144:147], v[176:179], v[20:23]
	v_mfma_f32_16x16x32_bf16 v[16:19], v[152:155], v[176:179], v[16:19]
	v_mfma_f32_16x16x32_bf16 v[4:7], v[144:147], v[184:187], v[4:7]
	v_mfma_f32_16x16x32_bf16 v[0:3], v[152:155], v[184:187], v[0:3]
	v_mfma_f32_16x16x32_bf16 v[60:63], v[132:135], v[164:167], v[60:63]
	v_mfma_f32_16x16x32_bf16 v[56:59], v[140:143], v[164:167], v[56:59]
	v_mfma_f32_16x16x32_bf16 v[44:47], v[132:135], v[172:175], v[44:47]
	v_mfma_f32_16x16x32_bf16 v[40:43], v[140:143], v[172:175], v[40:43]
	v_mfma_f32_16x16x32_bf16 v[28:31], v[132:135], v[180:183], v[28:31]
	v_mfma_f32_16x16x32_bf16 v[24:27], v[140:143], v[180:183], v[24:27]
	v_mfma_f32_16x16x32_bf16 v[12:15], v[132:135], v[188:191], v[12:15]
	v_mfma_f32_16x16x32_bf16 v[8:11], v[140:143], v[188:191], v[8:11]
	v_mfma_f32_16x16x32_bf16 v[52:55], v[148:151], v[164:167], v[52:55]
	v_mfma_f32_16x16x32_bf16 v[48:51], v[156:159], v[164:167], v[48:51]
	v_mfma_f32_16x16x32_bf16 v[36:39], v[148:151], v[172:175], v[36:39]
	v_mfma_f32_16x16x32_bf16 v[32:35], v[156:159], v[172:175], v[32:35]
	v_mfma_f32_16x16x32_bf16 v[20:23], v[148:151], v[180:183], v[20:23]
	v_mfma_f32_16x16x32_bf16 v[16:19], v[156:159], v[180:183], v[16:19]
	v_mfma_f32_16x16x32_bf16 v[4:7], v[148:151], v[188:191], v[4:7]
	v_mfma_f32_16x16x32_bf16 v[0:3], v[156:159], v[188:191], v[0:3]
	s_barrier
	s_add_i32 s55, s55, 2
	s_add_u32 s6, s6, 0x100
	s_addc_u32 s7, s7, 0
	s_add_u32 s42, s42, 0x100
	s_addc_u32 s43, s43, 0
	s_cmp_gt_u32 s55, 29
	s_cbranch_scc0 .LBB0_132
	s_branch .Lpeel_exit_inproj
.LBB0_132:
	ds_read_b128 v[128:131], v221
	ds_read_b128 v[132:135], v221 offset:1024
	ds_read_b128 v[136:139], v221 offset:2048
	ds_read_b128 v[140:143], v221 offset:3072
	ds_read_b128 v[144:147], v222
	ds_read_b128 v[148:151], v222 offset:1024
	ds_read_b128 v[152:155], v222 offset:2048
	ds_read_b128 v[156:159], v222 offset:3072
	s_add_u32 s40, s6, 0xfff80080
	s_addc_u32 s41, s7, -1
	s_cmp_eq_u32 s55, 28
	s_cselect_b32 s71, s25, s41
	s_cselect_b32 s70, s26, s40
	s_cselect_b32 s69, s38, s43
	s_cselect_b32 s68, s39, s42
	v_lshl_add_u64 v[192:193], s[6:7], 0, v[206:207]
	s_add_i32 m0, s65, 0xc000
	ds_read_b128 v[160:163], v223
	ds_read_b128 v[164:167], v223 offset:1024
	ds_read_b128 v[168:171], v223 offset:2048
	ds_read_b128 v[172:175], v223 offset:3072
	ds_read_b128 v[176:179], v223 offset:4096
	ds_read_b128 v[180:183], v223 offset:5120
	ds_read_b128 v[184:187], v223 offset:6144
	ds_read_b128 v[188:191], v223 offset:7168
	global_load_lds_dwordx4 v[192:193], off
	v_lshl_add_u64 v[192:193], s[6:7], 0, v[208:209]
	s_add_i32 m0, s65, 0xe000
	s_nop 0
	global_load_lds_dwordx4 v[192:193], off
	s_waitcnt vmcnt(8)
	s_waitcnt lgkmcnt(0)
	s_barrier
; #define PG8_STAGE(bufoff, gbase, voff) do { _Pragma("unroll") for (int _i = 0; _i < 2; ++_i) \
;         __builtin_amdgcn_global_load_lds((const unsigned*)((const char*)(gbase) + (voff)[_i]), (PG8_LAS unsigned*)(lds + (bufoff) + ldsw + _i * 8192), 16, 0, 0); } while (0)
; #define PG8_LDA(dst, b, h) do { _Pragma("unroll") for (int m = 0; m < 4; ++m) _Pragma("unroll") for (int k = 0; k < 2; ++k) dst[m][k] = *(const PG8_LAS bf16x8*)(lds + PG8_SA(b, h) + aoff + m * 2048 + k * 1024); } while (0)
; #define PG8_LDB(dst, b, h) do { _Pragma("unroll") for (int n = 0; n < 2; ++n) _Pragma("unroll") for (int k = 0; k < 2; ++k) dst[n][k] = *(const PG8_LAS bf16x8*)(lds + PG8_SB(b, h) + boff + n * 2048 + k * 1024); } while (0)
; #define PG8_MMA(ai, bj, At, Bt) do { _Pragma("unroll") for (int m = 0; m < 4; ++m) _Pragma("unroll") for (int n = 0; n < 2; ++n) _Pragma("unroll") for (int k = 0; k < 2; ++k) \
;         acc[ai][bj][m][n] = __builtin_amdgcn_mfma_f32_16x16x32_bf16(Bt[n][k], At[m][k], acc[ai][bj][m][n], 0, 0, 0); } while (0)
; #define PG8_WAIT_V(n) asm volatile("s_waitcnt vmcnt(" #n ")" ::: "memory")
; #define PG8_WAIT_L(n) asm volatile("s_waitcnt lgkmcnt(" #n ")" ::: "memory")
; #define PG8_BAR __builtin_amdgcn_s_barrier()
; #define PG8_SCHED __builtin_amdgcn_sched_barrier(0)
; template <class Epi, class Sched, bool ALIGN_EPI = false, bool SP2 = false>
; __device__ __forceinline__ void gemm_phase(PG8_LAS unsigned char* lds, const Gemm g, const Sched& S, const Epi& E, const int wave_id_in) {
;     ...
;             PG8_WAIT_V(8); PG8_WAIT_L(0); PG8_BAR; __builtin_amdgcn_s_setprio(1); PG8_MMA(0, 0, At, B0); PG8_MMA(0, 1, At, B1); __builtin_amdgcn_s_setprio(0); PG8_BAR; PG8_SCHED;
;             PG8_LDA(At, 0, 1); PG8_STAGE(PG8_SB(0, 0), b2, voffB); PG8_STAGE(PG8_SB(0, 1), b2 + hstep, voffB); PG8_STAGE(PG8_SA(0, 0), a2, voffA);
;             PG8_WAIT_V(8); PG8_WAIT_L(0); PG8_BAR; __builtin_amdgcn_s_setprio(1); PG8_MMA(1, 0, At, B0); PG8_MMA(1, 1, At, B1); __builtin_amdgcn_s_setprio(0); PG8_BAR; PG8_SCHED;
;             PG8_LDB(B0, 1, 0); PG8_LDB(B1, 1, 1); PG8_SCHED; PG8_LDA(At, 1, 0); PG8_STAGE(PG8_SA(0, 1), a2 + hstep, voffA);
;             PG8_WAIT_V(8); PG8_WAIT_L(0); PG8_BAR; __builtin_amdgcn_s_setprio(1); PG8_MMA(0, 0, At, B0); PG8_MMA(0, 1, At, B1); __builtin_amdgcn_s_setprio(0); PG8_BAR; PG8_SCHED;
	v_mfma_f32_16x16x32_bf16 v[124:127], v[128:131], v[160:163], v[124:127]
	v_mfma_f32_16x16x32_bf16 v[120:123], v[136:139], v[160:163], v[120:123]
	v_mfma_f32_16x16x32_bf16 v[108:111], v[128:131], v[168:171], v[108:111]
	v_mfma_f32_16x16x32_bf16 v[104:107], v[136:139], v[168:171], v[104:107]
	v_mfma_f32_16x16x32_bf16 v[92:95], v[128:131], v[176:179], v[92:95]
	v_mfma_f32_16x16x32_bf16 v[88:91], v[136:139], v[176:179], v[88:91]
	v_mfma_f32_16x16x32_bf16 v[76:79], v[128:131], v[184:187], v[76:79]
	v_mfma_f32_16x16x32_bf16 v[72:75], v[136:139], v[184:187], v[72:75]
	v_mfma_f32_16x16x32_bf16 v[116:119], v[144:147], v[160:163], v[116:119]
	v_mfma_f32_16x16x32_bf16 v[112:115], v[152:155], v[160:163], v[112:115]
	v_mfma_f32_16x16x32_bf16 v[100:103], v[144:147], v[168:171], v[100:103]
	v_mfma_f32_16x16x32_bf16 v[96:99], v[152:155], v[168:171], v[96:99]
	v_mfma_f32_16x16x32_bf16 v[84:87], v[144:147], v[176:179], v[84:87]
	v_mfma_f32_16x16x32_bf16 v[80:83], v[152:155], v[176:179], v[80:83]
	v_mfma_f32_16x16x32_bf16 v[68:71], v[144:147], v[184:187], v[68:71]
	v_mfma_f32_16x16x32_bf16 v[64:67], v[152:155], v[184:187], v[64:67]
	v_mfma_f32_16x16x32_bf16 v[124:127], v[132:135], v[164:167], v[124:127]
	v_mfma_f32_16x16x32_bf16 v[120:123], v[140:143], v[164:167], v[120:123]
	v_mfma_f32_16x16x32_bf16 v[108:111], v[132:135], v[172:175], v[108:111]
	v_mfma_f32_16x16x32_bf16 v[104:107], v[140:143], v[172:175], v[104:107]
	v_mfma_f32_16x16x32_bf16 v[92:95], v[132:135], v[180:183], v[92:95]
	v_mfma_f32_16x16x32_bf16 v[88:91], v[140:143], v[180:183], v[88:91]
	v_mfma_f32_16x16x32_bf16 v[76:79], v[132:135], v[188:191], v[76:79]
	v_mfma_f32_16x16x32_bf16 v[72:75], v[140:143], v[188:191], v[72:75]
	v_mfma_f32_16x16x32_bf16 v[116:119], v[148:151], v[164:167], v[116:119]
	v_mfma_f32_16x16x32_bf16 v[112:115], v[156:159], v[164:167], v[112:115]
	v_mfma_f32_16x16x32_bf16 v[100:103], v[148:151], v[172:175], v[100:103]
	v_mfma_f32_16x16x32_bf16 v[96:99], v[156:159], v[172:175], v[96:99]
	v_mfma_f32_16x16x32_bf16 v[84:87], v[148:151], v[180:183], v[84:87]
	v_mfma_f32_16x16x32_bf16 v[80:83], v[156:159], v[180:183], v[80:83]
	v_mfma_f32_16x16x32_bf16 v[68:71], v[148:151], v[188:191], v[68:71]
	v_mfma_f32_16x16x32_bf16 v[64:67], v[156:159], v[188:191], v[64:67]
	s_barrier
	s_add_i32 s40, s93, s80
	v_lshl_add_u64 v[192:193], s[68:69], 0, v[200:201]
	s_mov_b32 m0, s40
	ds_read_b128 v[160:163], v223 offset:16384
	ds_read_b128 v[164:167], v223 offset:17408
	ds_read_b128 v[168:171], v223 offset:18432
	ds_read_b128 v[172:175], v223 offset:19456
	ds_read_b128 v[176:179], v223 offset:20480
	ds_read_b128 v[180:183], v223 offset:21504
	ds_read_b128 v[184:187], v223 offset:22528
	ds_read_b128 v[188:191], v223 offset:23552
	global_load_lds_dwordx4 v[192:193], off
	s_add_i32 m0, s40, 0x2000
	s_add_u32 s72, s68, 0x80000
	v_lshl_add_u64 v[194:195], s[68:69], 0, v[202:203]
	s_addc_u32 s73, s69, 0
	s_add_i32 s40, s94, s80
	global_load_lds_dwordx4 v[194:195], off
	v_lshl_add_u64 v[196:197], s[72:73], 0, v[200:201]
	s_mov_b32 m0, s40
	v_lshl_add_u64 v[198:199], s[70:71], 0, v[202:203]
	global_load_lds_dwordx4 v[196:197], off
	v_lshl_add_u64 v[196:197], s[72:73], 0, v[202:203]
	s_add_i32 m0, s40, 0x2000
	s_nop 0
	global_load_lds_dwordx4 v[196:197], off
	v_lshl_add_u64 v[196:197], s[70:71], 0, v[200:201]
	s_mov_b32 m0, s65
	s_nop 0
	global_load_lds_dwordx4 v[196:197], off
	s_mov_b32 m0, s67
	s_nop 0
	global_load_lds_dwordx4 v[198:199], off
	s_waitcnt vmcnt(8)
	s_waitcnt lgkmcnt(0)
	s_barrier
	v_mfma_f32_16x16x32_bf16 v[60:63], v[128:131], v[160:163], v[60:63]
	v_mfma_f32_16x16x32_bf16 v[56:59], v[136:139], v[160:163], v[56:59]
	v_mfma_f32_16x16x32_bf16 v[44:47], v[128:131], v[168:171], v[44:47]
	v_mfma_f32_16x16x32_bf16 v[40:43], v[136:139], v[168:171], v[40:43]
	v_mfma_f32_16x16x32_bf16 v[28:31], v[128:131], v[176:179], v[28:31]
	v_mfma_f32_16x16x32_bf16 v[24:27], v[136:139], v[176:179], v[24:27]
	v_mfma_f32_16x16x32_bf16 v[12:15], v[128:131], v[184:187], v[12:15]
	v_mfma_f32_16x16x32_bf16 v[8:11], v[136:139], v[184:187], v[8:11]
	v_mfma_f32_16x16x32_bf16 v[52:55], v[144:147], v[160:163], v[52:55]
	v_mfma_f32_16x16x32_bf16 v[48:51], v[152:155], v[160:163], v[48:51]
	v_mfma_f32_16x16x32_bf16 v[36:39], v[144:147], v[168:171], v[36:39]
	v_mfma_f32_16x16x32_bf16 v[32:35], v[152:155], v[168:171], v[32:35]
	v_mfma_f32_16x16x32_bf16 v[20:23], v[144:147], v[176:179], v[20:23]
	v_mfma_f32_16x16x32_bf16 v[16:19], v[152:155], v[176:179], v[16:19]
	v_mfma_f32_16x16x32_bf16 v[4:7], v[144:147], v[184:187], v[4:7]
	v_mfma_f32_16x16x32_bf16 v[0:3], v[152:155], v[184:187], v[0:3]
	v_mfma_f32_16x16x32_bf16 v[60:63], v[132:135], v[164:167], v[60:63]
	v_mfma_f32_16x16x32_bf16 v[56:59], v[140:143], v[164:167], v[56:59]
	v_mfma_f32_16x16x32_bf16 v[44:47], v[132:135], v[172:175], v[44:47]
	v_mfma_f32_16x16x32_bf16 v[40:43], v[140:143], v[172:175], v[40:43]
	v_mfma_f32_16x16x32_bf16 v[28:31], v[132:135], v[180:183], v[28:31]
	v_mfma_f32_16x16x32_bf16 v[24:27], v[140:143], v[180:183], v[24:27]
	v_mfma_f32_16x16x32_bf16 v[12:15], v[132:135], v[188:191], v[12:15]
	v_mfma_f32_16x16x32_bf16 v[8:11], v[140:143], v[188:191], v[8:11]
	v_mfma_f32_16x16x32_bf16 v[52:55], v[148:151], v[164:167], v[52:55]
	v_mfma_f32_16x16x32_bf16 v[48:51], v[156:159], v[164:167], v[48:51]
	v_mfma_f32_16x16x32_bf16 v[36:39], v[148:151], v[172:175], v[36:39]
	v_mfma_f32_16x16x32_bf16 v[32:35], v[156:159], v[172:175], v[32:35]
	v_mfma_f32_16x16x32_bf16 v[20:23], v[148:151], v[180:183], v[20:23]
	v_mfma_f32_16x16x32_bf16 v[16:19], v[156:159], v[180:183], v[16:19]
	v_mfma_f32_16x16x32_bf16 v[4:7], v[148:151], v[188:191], v[4:7]
	v_mfma_f32_16x16x32_bf16 v[0:3], v[156:159], v[188:191], v[0:3]
	s_barrier
; #define PG8_STAGE(bufoff, gbase, voff) do { _Pragma("unroll") for (int _i = 0; _i < 2; ++_i) \
;         __builtin_amdgcn_global_load_lds((const unsigned*)((const char*)(gbase) + (voff)[_i]), (PG8_LAS unsigned*)(lds + (bufoff) + ldsw + _i * 8192), 16, 0, 0); } while (0)
; #define PG8_LDA(dst, b, h) do { _Pragma("unroll") for (int m = 0; m < 4; ++m) _Pragma("unroll") for (int k = 0; k < 2; ++k) dst[m][k] = *(const PG8_LAS bf16x8*)(lds + PG8_SA(b, h) + aoff + m * 2048 + k * 1024); } while (0)
; #define PG8_MMA(ai, bj, At, Bt) do { _Pragma("unroll") for (int m = 0; m < 4; ++m) _Pragma("unroll") for (int n = 0; n < 2; ++n) _Pragma("unroll") for (int k = 0; k < 2; ++k) \
;         acc[ai][bj][m][n] = __builtin_amdgcn_mfma_f32_16x16x32_bf16(Bt[n][k], At[m][k], acc[ai][bj][m][n], 0, 0, 0); } while (0)
; #define PG8_WAIT_V(n) asm volatile("s_waitcnt vmcnt(" #n ")" ::: "memory")
; #define PG8_WAIT_L(n) asm volatile("s_waitcnt lgkmcnt(" #n ")" ::: "memory")
; #define PG8_BAR __builtin_amdgcn_s_barrier()
; #define PG8_SCHED __builtin_amdgcn_sched_barrier(0)
; template <class Epi, class Sched, bool ALIGN_EPI = false, bool SP2 = false>
; __device__ __forceinline__ void gemm_phase(PG8_LAS unsigned char* lds, const Gemm g, const Sched& S, const Epi& E, const int wave_id_in) {
;     ...
;             PG8_WAIT_V(8); PG8_WAIT_L(0); PG8_BAR; __builtin_amdgcn_s_setprio(1); PG8_MMA(0, 0, At, B0); PG8_MMA(0, 1, At, B1); __builtin_amdgcn_s_setprio(0); PG8_BAR; PG8_SCHED;
;             PG8_LDA(At, 1, 1); PG8_STAGE(PG8_SB(1, 0), b3, voffB); PG8_STAGE(PG8_SB(1, 1), b3 + hstep, voffB); PG8_STAGE(PG8_SA(1, 0), a3, voffA);
;             PG8_WAIT_V(8); PG8_WAIT_L(0); PG8_BAR; __builtin_amdgcn_s_setprio(1); PG8_MMA(1, 0, At, B0); PG8_MMA(1, 1, At, B1); __builtin_amdgcn_s_setprio(0); PG8_BAR; PG8_SCHED;
	s_add_i32 s40, 0, 0x18000
	s_add_i32 s41, 0, 0x1c000
	v_add_u32_e32 v140, s40, v220
	v_add_u32_e32 v156, s41, v220
	ds_read_b128 v[128:131], v140
	ds_read_b128 v[132:135], v140 offset:1024
	ds_read_b128 v[136:139], v140 offset:2048
	ds_read_b128 v[140:143], v140 offset:3072
	ds_read_b128 v[144:147], v156
	ds_read_b128 v[148:151], v156 offset:1024
	ds_read_b128 v[152:155], v156 offset:2048
	ds_read_b128 v[156:159], v156 offset:3072
	s_add_u32 s70, s70, 0x80000
	s_addc_u32 s71, s71, 0
	s_mov_b32 m0, s81
	v_lshl_add_u64 v[214:215], s[70:71], 0, v[200:201]
	ds_read_b128 v[160:163], v223 offset:32768
	ds_read_b128 v[164:167], v223 offset:33792
	ds_read_b128 v[168:171], v223 offset:34816
	ds_read_b128 v[172:175], v223 offset:35840
	ds_read_b128 v[176:179], v223 offset:36864
	ds_read_b128 v[180:183], v223 offset:37888
	ds_read_b128 v[184:187], v223 offset:38912
	ds_read_b128 v[188:191], v223 offset:39936
	global_load_lds_dwordx4 v[214:215], off
	v_lshl_add_u64 v[214:215], s[70:71], 0, v[202:203]
	s_mov_b32 m0, s82
	s_nop 0
	global_load_lds_dwordx4 v[214:215], off
	s_waitcnt vmcnt(8)
	s_waitcnt lgkmcnt(0)
	s_barrier
	v_mfma_f32_16x16x32_bf16 v[124:127], v[128:131], v[160:163], v[124:127]
	v_mfma_f32_16x16x32_bf16 v[120:123], v[136:139], v[160:163], v[120:123]
	v_mfma_f32_16x16x32_bf16 v[108:111], v[128:131], v[168:171], v[108:111]
	v_mfma_f32_16x16x32_bf16 v[104:107], v[136:139], v[168:171], v[104:107]
	v_mfma_f32_16x16x32_bf16 v[92:95], v[128:131], v[176:179], v[92:95]
	v_mfma_f32_16x16x32_bf16 v[88:91], v[136:139], v[176:179], v[88:91]
	v_mfma_f32_16x16x32_bf16 v[76:79], v[128:131], v[184:187], v[76:79]
	v_mfma_f32_16x16x32_bf16 v[72:75], v[136:139], v[184:187], v[72:75]
	v_mfma_f32_16x16x32_bf16 v[116:119], v[144:147], v[160:163], v[116:119]
	v_mfma_f32_16x16x32_bf16 v[112:115], v[152:155], v[160:163], v[112:115]
	v_mfma_f32_16x16x32_bf16 v[100:103], v[144:147], v[168:171], v[100:103]
	v_mfma_f32_16x16x32_bf16 v[96:99], v[152:155], v[168:171], v[96:99]
	v_mfma_f32_16x16x32_bf16 v[84:87], v[144:147], v[176:179], v[84:87]
	v_mfma_f32_16x16x32_bf16 v[80:83], v[152:155], v[176:179], v[80:83]
	v_mfma_f32_16x16x32_bf16 v[68:71], v[144:147], v[184:187], v[68:71]
	v_mfma_f32_16x16x32_bf16 v[64:67], v[152:155], v[184:187], v[64:67]
	v_mfma_f32_16x16x32_bf16 v[124:127], v[132:135], v[164:167], v[124:127]
	v_mfma_f32_16x16x32_bf16 v[120:123], v[140:143], v[164:167], v[120:123]
	v_mfma_f32_16x16x32_bf16 v[108:111], v[132:135], v[172:175], v[108:111]
	v_mfma_f32_16x16x32_bf16 v[104:107], v[140:143], v[172:175], v[104:107]
	v_mfma_f32_16x16x32_bf16 v[92:95], v[132:135], v[180:183], v[92:95]
	v_mfma_f32_16x16x32_bf16 v[88:91], v[140:143], v[180:183], v[88:91]
	v_mfma_f32_16x16x32_bf16 v[76:79], v[132:135], v[188:191], v[76:79]
	v_mfma_f32_16x16x32_bf16 v[72:75], v[140:143], v[188:191], v[72:75]
	v_mfma_f32_16x16x32_bf16 v[116:119], v[148:151], v[164:167], v[116:119]
	v_mfma_f32_16x16x32_bf16 v[112:115], v[156:159], v[164:167], v[112:115]
	v_mfma_f32_16x16x32_bf16 v[100:103], v[148:151], v[172:175], v[100:103]
	v_mfma_f32_16x16x32_bf16 v[96:99], v[156:159], v[172:175], v[96:99]
	v_mfma_f32_16x16x32_bf16 v[84:87], v[148:151], v[180:183], v[84:87]
	v_mfma_f32_16x16x32_bf16 v[80:83], v[156:159], v[180:183], v[80:83]
	v_mfma_f32_16x16x32_bf16 v[68:71], v[148:151], v[188:191], v[68:71]
	v_mfma_f32_16x16x32_bf16 v[64:67], v[156:159], v[188:191], v[64:67]
	s_barrier
	s_add_i32 s40, s40, s80
	v_lshl_add_u64 v[192:193], v[192:193], 0, s[30:31]
	s_mov_b32 m0, s40
	ds_read_b128 v[160:163], v223 offset:49152
	ds_read_b128 v[164:167], v223 offset:50176
	ds_read_b128 v[168:171], v223 offset:51200
	ds_read_b128 v[172:175], v223 offset:52224
	ds_read_b128 v[176:179], v223 offset:53248
	ds_read_b128 v[180:183], v223 offset:54272
	ds_read_b128 v[184:187], v223 offset:55296
	ds_read_b128 v[188:191], v223 offset:56320
	global_load_lds_dwordx4 v[192:193], off
	s_add_i32 m0, s40, 0x2000
	s_add_u32 s68, s68, 0x80080
	v_lshl_add_u64 v[192:193], v[194:195], 0, s[30:31]
	s_addc_u32 s69, s69, 0
	s_add_i32 s40, s41, s80
	global_load_lds_dwordx4 v[192:193], off
	v_lshl_add_u64 v[192:193], s[68:69], 0, v[200:201]
	s_mov_b32 m0, s40
	s_nop 0
	global_load_lds_dwordx4 v[192:193], off
	v_lshl_add_u64 v[192:193], s[68:69], 0, v[202:203]
	s_add_i32 m0, s40, 0x2000
	s_nop 0
	global_load_lds_dwordx4 v[192:193], off
	v_lshl_add_u64 v[192:193], v[196:197], 0, s[30:31]
	s_mov_b32 m0, s86
	s_nop 0
	global_load_lds_dwordx4 v[192:193], off
	v_lshl_add_u64 v[192:193], v[198:199], 0, s[30:31]
	s_mov_b32 m0, s87
	s_nop 0
	global_load_lds_dwordx4 v[192:193], off
	s_waitcnt vmcnt(8)
	s_waitcnt lgkmcnt(0)
	s_barrier
	v_mfma_f32_16x16x32_bf16 v[60:63], v[128:131], v[160:163], v[60:63]
	v_mfma_f32_16x16x32_bf16 v[56:59], v[136:139], v[160:163], v[56:59]
	v_mfma_f32_16x16x32_bf16 v[44:47], v[128:131], v[168:171], v[44:47]
	v_mfma_f32_16x16x32_bf16 v[40:43], v[136:139], v[168:171], v[40:43]
	v_mfma_f32_16x16x32_bf16 v[28:31], v[128:131], v[176:179], v[28:31]
	v_mfma_f32_16x16x32_bf16 v[24:27], v[136:139], v[176:179], v[24:27]
	v_mfma_f32_16x16x32_bf16 v[12:15], v[128:131], v[184:187], v[12:15]
	v_mfma_f32_16x16x32_bf16 v[8:11], v[136:139], v[184:187], v[8:11]
	v_mfma_f32_16x16x32_bf16 v[52:55], v[144:147], v[160:163], v[52:55]
	v_mfma_f32_16x16x32_bf16 v[48:51], v[152:155], v[160:163], v[48:51]
	v_mfma_f32_16x16x32_bf16 v[36:39], v[144:147], v[168:171], v[36:39]
	v_mfma_f32_16x16x32_bf16 v[32:35], v[152:155], v[168:171], v[32:35]
	v_mfma_f32_16x16x32_bf16 v[20:23], v[144:147], v[176:179], v[20:23]
	v_mfma_f32_16x16x32_bf16 v[16:19], v[152:155], v[176:179], v[16:19]
	v_mfma_f32_16x16x32_bf16 v[4:7], v[144:147], v[184:187], v[4:7]
	v_mfma_f32_16x16x32_bf16 v[0:3], v[152:155], v[184:187], v[0:3]
	v_mfma_f32_16x16x32_bf16 v[60:63], v[132:135], v[164:167], v[60:63]
	v_mfma_f32_16x16x32_bf16 v[56:59], v[140:143], v[164:167], v[56:59]
	v_mfma_f32_16x16x32_bf16 v[44:47], v[132:135], v[172:175], v[44:47]
	v_mfma_f32_16x16x32_bf16 v[40:43], v[140:143], v[172:175], v[40:43]
	v_mfma_f32_16x16x32_bf16 v[28:31], v[132:135], v[180:183], v[28:31]
	v_mfma_f32_16x16x32_bf16 v[24:27], v[140:143], v[180:183], v[24:27]
	v_mfma_f32_16x16x32_bf16 v[12:15], v[132:135], v[188:191], v[12:15]
	v_mfma_f32_16x16x32_bf16 v[8:11], v[140:143], v[188:191], v[8:11]
	v_mfma_f32_16x16x32_bf16 v[52:55], v[148:151], v[164:167], v[52:55]
	v_mfma_f32_16x16x32_bf16 v[48:51], v[156:159], v[164:167], v[48:51]
	v_mfma_f32_16x16x32_bf16 v[36:39], v[148:151], v[172:175], v[36:39]
	v_mfma_f32_16x16x32_bf16 v[32:35], v[156:159], v[172:175], v[32:35]
	v_mfma_f32_16x16x32_bf16 v[20:23], v[148:151], v[180:183], v[20:23]
	v_mfma_f32_16x16x32_bf16 v[16:19], v[156:159], v[180:183], v[16:19]
	v_mfma_f32_16x16x32_bf16 v[4:7], v[148:151], v[188:191], v[4:7]
	v_mfma_f32_16x16x32_bf16 v[0:3], v[156:159], v[188:191], v[0:3]
	s_barrier
	s_add_i32 s55, s55, 2
	s_add_u32 s6, s6, 0x100
	s_addc_u32 s7, s7, 0
	s_add_u32 s42, s42, 0x100
	s_addc_u32 s43, s43, 0
	s_cmp_gt_u32 s55, 29
	s_cbranch_scc0 .LBB0_132

; #define PG8_STAGE(bufoff, gbase, voff) do { _Pragma("unroll") for (int _i = 0; _i < 2; ++_i) \
;         __builtin_amdgcn_global_load_lds((const unsigned*)((const char*)(gbase) + (voff)[_i]), (PG8_LAS unsigned*)(lds + (bufoff) + ldsw + _i * 8192), 16, 0, 0); } while (0)
; #define PG8_LDA(dst, b, h) do { _Pragma("unroll") for (int m = 0; m < 4; ++m) _Pragma("unroll") for (int k = 0; k < 2; ++k) dst[m][k] = *(const PG8_LAS bf16x8*)(lds + PG8_SA(b, h) + aoff + m * 2048 + k * 1024); } while (0)
; #define PG8_LDB(dst, b, h) do { _Pragma("unroll") for (int n = 0; n < 2; ++n) _Pragma("unroll") for (int k = 0; k < 2; ++k) dst[n][k] = *(const PG8_LAS bf16x8*)(lds + PG8_SB(b, h) + boff + n * 2048 + k * 1024); } while (0)
; #define PG8_MMA(ai, bj, At, Bt) do { _Pragma("unroll") for (int m = 0; m < 4; ++m) _Pragma("unroll") for (int n = 0; n < 2; ++n) _Pragma("unroll") for (int k = 0; k < 2; ++k) \
;         acc[ai][bj][m][n] = __builtin_amdgcn_mfma_f32_16x16x32_bf16(Bt[n][k], At[m][k], acc[ai][bj][m][n], 0, 0, 0); } while (0)
; #define PG8_BAR __builtin_amdgcn_s_barrier()
; template <class Epi, class Sched, bool ALIGN_EPI = false, bool SP2 = false>
; __device__ __forceinline__ void gemm_phase(PG8_LAS unsigned char* lds, const Gemm g, const Sched& S, const Epi& E, const int wave_id_in) {
;     ...
;         for (int t = 0; t < nt; t += 2) {
;             const bool last = (t == nt - 2);
;             const char* a1 = cA + (size_t)(t + 1) * kstep;
;             const char* a2 = last ? nA : cA + (size_t)(t + 2) * kstep; const char* b2 = last ? nB : cB + (size_t)(t + 2) * kstep;
;             const char* a3 = a2 + kstep; const char* b3 = b2 + kstep;
;             if (last && has_next) S.a_ready(nxt);
;             if constexpr (SP2) {
;             PG8_LDB(B0, 0, 0); PG8_LDB(B1, 0, 1); PG8_SCHED; PG8_LDA(At, 0, 0); PG8_STAGE(PG8_SA(1, 1), a1 + hstep, voffA);
;             PG8_WAIT_V(8); PG8_WAIT_L(0); PG8_BAR; __builtin_amdgcn_s_setprio(1); PG8_MMA(0, 0, At, B0); PG8_MMA(0, 1, At, B1); __builtin_amdgcn_s_setprio(0); PG8_BAR; PG8_SCHED;
;             PG8_LDA(At, 0, 1); PG8_STAGE(PG8_SB(0, 0), b2, voffB); PG8_STAGE(PG8_SB(0, 1), b2 + hstep, voffB); PG8_STAGE(PG8_SA(0, 0), a2, voffA);
;             PG8_WAIT_V(8); PG8_WAIT_L(0); PG8_BAR; __builtin_amdgcn_s_setprio(1); PG8_MMA(1, 0, At, B0); PG8_MMA(1, 1, At, B1); __builtin_amdgcn_s_setprio(0); PG8_BAR; PG8_SCHED;
.LBB0_594:
.LBB0_595:
	s_lshl_b32 s40, s72, 7
	s_add_u32 s40, s34, s40
	s_addc_u32 s41, s35, 0
	s_add_i32 s73, s72, 2
	v_add_u32_e32 v140, s64, v180
	v_add_u32_e32 v156, s65, v180
	s_lshl_b32 s74, s73, 7
	ds_read_b128 v[128:131], v140
	ds_read_b128 v[132:135], v140 offset:1024
	ds_read_b128 v[136:139], v140 offset:2048
	ds_read_b128 v[140:143], v140 offset:3072
	ds_read_b128 v[144:147], v156
	ds_read_b128 v[148:151], v156 offset:1024
	ds_read_b128 v[152:155], v156 offset:2048
	ds_read_b128 v[156:159], v156 offset:3072
	s_add_u32 s75, s34, s74
	s_addc_u32 s78, s35, 0
	s_and_b64 s[52:53], s[50:51], exec
	s_cselect_b32 s53, s27, s78
	s_cselect_b32 s52, s70, s75
	s_add_u32 s74, s46, s74
	s_addc_u32 s75, s47, 0
	s_and_b64 s[50:51], s[50:51], exec
	s_cselect_b32 s51, s25, s75
	s_cselect_b32 s50, s71, s74
	s_add_u32 s74, s40, 0x40080
	s_addc_u32 s75, s41, 0
	v_lshl_add_u64 v[206:207], s[74:75], 0, v[168:169]
	s_add_i32 m0, s37, 0xc000
	ds_read_b128 v[160:163], v181
	ds_read_b128 v[164:167], v181 offset:1024
	ds_read_b128 v[182:185], v181 offset:2048
	ds_read_b128 v[186:189], v181 offset:3072
	ds_read_b128 v[190:193], v181 offset:4096
	ds_read_b128 v[194:197], v181 offset:5120
	ds_read_b128 v[198:201], v181 offset:6144
	ds_read_b128 v[202:205], v181 offset:7168
	global_load_lds_dwordx4 v[206:207], off
	v_lshl_add_u64 v[206:207], s[74:75], 0, v[172:173]
	s_add_i32 m0, s37, 0xe000
	s_nop 0
	global_load_lds_dwordx4 v[206:207], off
	s_waitcnt vmcnt(8)
	s_waitcnt lgkmcnt(0)
	s_barrier
	v_mfma_f32_16x16x32_bf16 v[124:127], v[128:131], v[160:163], v[124:127]
	v_mfma_f32_16x16x32_bf16 v[120:123], v[136:139], v[160:163], v[120:123]
	v_mfma_f32_16x16x32_bf16 v[116:119], v[128:131], v[182:185], v[116:119]
	v_mfma_f32_16x16x32_bf16 v[112:115], v[136:139], v[182:185], v[112:115]
	v_mfma_f32_16x16x32_bf16 v[108:111], v[128:131], v[190:193], v[108:111]
	v_mfma_f32_16x16x32_bf16 v[104:107], v[136:139], v[190:193], v[104:107]
	v_mfma_f32_16x16x32_bf16 v[100:103], v[128:131], v[198:201], v[100:103]
	v_mfma_f32_16x16x32_bf16 v[96:99], v[136:139], v[198:201], v[96:99]
	v_mfma_f32_16x16x32_bf16 v[92:95], v[144:147], v[160:163], v[92:95]
	v_mfma_f32_16x16x32_bf16 v[88:91], v[152:155], v[160:163], v[88:91]
	v_mfma_f32_16x16x32_bf16 v[84:87], v[144:147], v[182:185], v[84:87]
	v_mfma_f32_16x16x32_bf16 v[80:83], v[152:155], v[182:185], v[80:83]
	v_mfma_f32_16x16x32_bf16 v[76:79], v[144:147], v[190:193], v[76:79]
	v_mfma_f32_16x16x32_bf16 v[72:75], v[152:155], v[190:193], v[72:75]
	v_mfma_f32_16x16x32_bf16 v[68:71], v[144:147], v[198:201], v[68:71]
	v_mfma_f32_16x16x32_bf16 v[64:67], v[152:155], v[198:201], v[64:67]
	v_mfma_f32_16x16x32_bf16 v[124:127], v[132:135], v[164:167], v[124:127]
	v_mfma_f32_16x16x32_bf16 v[120:123], v[140:143], v[164:167], v[120:123]
	v_mfma_f32_16x16x32_bf16 v[116:119], v[132:135], v[186:189], v[116:119]
	v_mfma_f32_16x16x32_bf16 v[112:115], v[140:143], v[186:189], v[112:115]
	v_mfma_f32_16x16x32_bf16 v[108:111], v[132:135], v[194:197], v[108:111]
	v_mfma_f32_16x16x32_bf16 v[104:107], v[140:143], v[194:197], v[104:107]
	v_mfma_f32_16x16x32_bf16 v[100:103], v[132:135], v[202:205], v[100:103]
	v_mfma_f32_16x16x32_bf16 v[96:99], v[140:143], v[202:205], v[96:99]
	v_mfma_f32_16x16x32_bf16 v[92:95], v[148:151], v[164:167], v[92:95]
	v_mfma_f32_16x16x32_bf16 v[88:91], v[156:159], v[164:167], v[88:91]
	v_mfma_f32_16x16x32_bf16 v[84:87], v[148:151], v[186:189], v[84:87]
	v_mfma_f32_16x16x32_bf16 v[80:83], v[156:159], v[186:189], v[80:83]
	v_mfma_f32_16x16x32_bf16 v[76:79], v[148:151], v[194:197], v[76:79]
	v_mfma_f32_16x16x32_bf16 v[72:75], v[156:159], v[194:197], v[72:75]
	v_mfma_f32_16x16x32_bf16 v[68:71], v[148:151], v[202:205], v[68:71]
	v_mfma_f32_16x16x32_bf16 v[64:67], v[156:159], v[202:205], v[64:67]
	s_barrier
	s_add_i32 s40, s64, s43
	v_lshl_add_u64 v[206:207], s[50:51], 0, v[170:171]
	s_mov_b32 m0, s40
	ds_read_b128 v[160:163], v181 offset:16384
	ds_read_b128 v[164:167], v181 offset:17408
	ds_read_b128 v[182:185], v181 offset:18432
	ds_read_b128 v[186:189], v181 offset:19456
	ds_read_b128 v[190:193], v181 offset:20480
	ds_read_b128 v[194:197], v181 offset:21504
	ds_read_b128 v[198:201], v181 offset:22528
	ds_read_b128 v[202:205], v181 offset:23552
	global_load_lds_dwordx4 v[206:207], off
	s_add_i32 m0, s40, 0x2000
	s_add_u32 s74, s50, 0x40000
	v_lshl_add_u64 v[208:209], s[50:51], 0, v[174:175]
	s_addc_u32 s75, s51, 0
	s_add_i32 s40, s65, s43
	global_load_lds_dwordx4 v[208:209], off
	v_lshl_add_u64 v[210:211], s[74:75], 0, v[170:171]
	s_mov_b32 m0, s40
	v_lshl_add_u64 v[212:213], s[52:53], 0, v[172:173]
	global_load_lds_dwordx4 v[210:211], off
	v_lshl_add_u64 v[210:211], s[74:75], 0, v[174:175]
	s_add_i32 m0, s40, 0x2000
	s_nop 0
	global_load_lds_dwordx4 v[210:211], off
	v_lshl_add_u64 v[210:211], s[52:53], 0, v[168:169]
	s_mov_b32 m0, s37
	s_nop 0
	global_load_lds_dwordx4 v[210:211], off
	s_mov_b32 m0, s44
	s_nop 0
	global_load_lds_dwordx4 v[212:213], off
	s_waitcnt vmcnt(8)
	s_waitcnt lgkmcnt(0)
	s_barrier
; #define PG8_STAGE(bufoff, gbase, voff) do { _Pragma("unroll") for (int _i = 0; _i < 2; ++_i) \
;         __builtin_amdgcn_global_load_lds((const unsigned*)((const char*)(gbase) + (voff)[_i]), (PG8_LAS unsigned*)(lds + (bufoff) + ldsw + _i * 8192), 16, 0, 0); } while (0)
; #define PG8_LDA(dst, b, h) do { _Pragma("unroll") for (int m = 0; m < 4; ++m) _Pragma("unroll") for (int k = 0; k < 2; ++k) dst[m][k] = *(const PG8_LAS bf16x8*)(lds + PG8_SA(b, h) + aoff + m * 2048 + k * 1024); } while (0)
; #define PG8_LDB(dst, b, h) do { _Pragma("unroll") for (int n = 0; n < 2; ++n) _Pragma("unroll") for (int k = 0; k < 2; ++k) dst[n][k] = *(const PG8_LAS bf16x8*)(lds + PG8_SB(b, h) + boff + n * 2048 + k * 1024); } while (0)
; #define PG8_MMA(ai, bj, At, Bt) do { _Pragma("unroll") for (int m = 0; m < 4; ++m) _Pragma("unroll") for (int n = 0; n < 2; ++n) _Pragma("unroll") for (int k = 0; k < 2; ++k) \
;         acc[ai][bj][m][n] = __builtin_amdgcn_mfma_f32_16x16x32_bf16(Bt[n][k], At[m][k], acc[ai][bj][m][n], 0, 0, 0); } while (0)
; #define PG8_WAIT_V(n) asm volatile("s_waitcnt vmcnt(" #n ")" ::: "memory")
; #define PG8_WAIT_L(n) asm volatile("s_waitcnt lgkmcnt(" #n ")" ::: "memory")
; #define PG8_BAR __builtin_amdgcn_s_barrier()
; #define PG8_SCHED __builtin_amdgcn_sched_barrier(0)
; template <class Epi, class Sched, bool ALIGN_EPI = false, bool SP2 = false>
; __device__ __forceinline__ void gemm_phase(PG8_LAS unsigned char* lds, const Gemm g, const Sched& S, const Epi& E, const int wave_id_in) {
;     ...
;             PG8_WAIT_V(8); PG8_WAIT_L(0); PG8_BAR; __builtin_amdgcn_s_setprio(1); PG8_MMA(1, 0, At, B0); PG8_MMA(1, 1, At, B1); __builtin_amdgcn_s_setprio(0); PG8_BAR; PG8_SCHED;
;             PG8_LDB(B0, 1, 0); PG8_LDB(B1, 1, 1); PG8_SCHED; PG8_LDA(At, 1, 0); PG8_STAGE(PG8_SA(0, 1), a2 + hstep, voffA);
;             PG8_WAIT_V(8); PG8_WAIT_L(0); PG8_BAR; __builtin_amdgcn_s_setprio(1); PG8_MMA(0, 0, At, B0); PG8_MMA(0, 1, At, B1); __builtin_amdgcn_s_setprio(0); PG8_BAR; PG8_SCHED;
	v_mfma_f32_16x16x32_bf16 v[60:63], v[128:131], v[160:163], v[60:63]
	v_mfma_f32_16x16x32_bf16 v[56:59], v[136:139], v[160:163], v[56:59]
	v_mfma_f32_16x16x32_bf16 v[52:55], v[128:131], v[182:185], v[52:55]
	v_mfma_f32_16x16x32_bf16 v[48:51], v[136:139], v[182:185], v[48:51]
	v_mfma_f32_16x16x32_bf16 v[44:47], v[128:131], v[190:193], v[44:47]
	v_mfma_f32_16x16x32_bf16 v[40:43], v[136:139], v[190:193], v[40:43]
	v_mfma_f32_16x16x32_bf16 v[36:39], v[128:131], v[198:201], v[36:39]
	v_mfma_f32_16x16x32_bf16 v[32:35], v[136:139], v[198:201], v[32:35]
	v_mfma_f32_16x16x32_bf16 v[28:31], v[144:147], v[160:163], v[28:31]
	v_mfma_f32_16x16x32_bf16 v[24:27], v[152:155], v[160:163], v[24:27]
	v_mfma_f32_16x16x32_bf16 v[20:23], v[144:147], v[182:185], v[20:23]
	v_mfma_f32_16x16x32_bf16 v[16:19], v[152:155], v[182:185], v[16:19]
	v_mfma_f32_16x16x32_bf16 v[12:15], v[144:147], v[190:193], v[12:15]
	v_mfma_f32_16x16x32_bf16 v[8:11], v[152:155], v[190:193], v[8:11]
	v_mfma_f32_16x16x32_bf16 v[4:7], v[144:147], v[198:201], v[4:7]
	v_mfma_f32_16x16x32_bf16 v[0:3], v[152:155], v[198:201], v[0:3]
	v_mfma_f32_16x16x32_bf16 v[60:63], v[132:135], v[164:167], v[60:63]
	v_mfma_f32_16x16x32_bf16 v[56:59], v[140:143], v[164:167], v[56:59]
	v_mfma_f32_16x16x32_bf16 v[52:55], v[132:135], v[186:189], v[52:55]
	v_mfma_f32_16x16x32_bf16 v[48:51], v[140:143], v[186:189], v[48:51]
	v_mfma_f32_16x16x32_bf16 v[44:47], v[132:135], v[194:197], v[44:47]
	v_mfma_f32_16x16x32_bf16 v[40:43], v[140:143], v[194:197], v[40:43]
	v_mfma_f32_16x16x32_bf16 v[36:39], v[132:135], v[202:205], v[36:39]
	v_mfma_f32_16x16x32_bf16 v[32:35], v[140:143], v[202:205], v[32:35]
	v_mfma_f32_16x16x32_bf16 v[28:31], v[148:151], v[164:167], v[28:31]
	v_mfma_f32_16x16x32_bf16 v[24:27], v[156:159], v[164:167], v[24:27]
	v_mfma_f32_16x16x32_bf16 v[20:23], v[148:151], v[186:189], v[20:23]
	v_mfma_f32_16x16x32_bf16 v[16:19], v[156:159], v[186:189], v[16:19]
	v_mfma_f32_16x16x32_bf16 v[12:15], v[148:151], v[194:197], v[12:15]
	v_mfma_f32_16x16x32_bf16 v[8:11], v[156:159], v[194:197], v[8:11]
	v_mfma_f32_16x16x32_bf16 v[4:7], v[148:151], v[202:205], v[4:7]
	v_mfma_f32_16x16x32_bf16 v[0:3], v[156:159], v[202:205], v[0:3]
	s_barrier
	s_add_i32 s40, 0, 0x18000
	s_add_i32 s41, 0, 0x1c000
	v_add_u32_e32 v140, s40, v180
	v_add_u32_e32 v156, s41, v180
	ds_read_b128 v[128:131], v140
	ds_read_b128 v[132:135], v140 offset:1024
	ds_read_b128 v[136:139], v140 offset:2048
	ds_read_b128 v[140:143], v140 offset:3072
	ds_read_b128 v[144:147], v156
	ds_read_b128 v[148:151], v156 offset:1024
	ds_read_b128 v[152:155], v156 offset:2048
	ds_read_b128 v[156:159], v156 offset:3072
	s_add_u32 s52, s52, 0x40000
	s_addc_u32 s53, s53, 0
	s_mov_b32 m0, s45
	v_lshl_add_u64 v[214:215], s[52:53], 0, v[168:169]
	ds_read_b128 v[160:163], v181 offset:32768
	ds_read_b128 v[164:167], v181 offset:33792
	ds_read_b128 v[182:185], v181 offset:34816
	ds_read_b128 v[186:189], v181 offset:35840
	ds_read_b128 v[190:193], v181 offset:36864
	ds_read_b128 v[194:197], v181 offset:37888
	ds_read_b128 v[198:201], v181 offset:38912
	ds_read_b128 v[202:205], v181 offset:39936
	global_load_lds_dwordx4 v[214:215], off
	v_lshl_add_u64 v[214:215], s[52:53], 0, v[172:173]
	s_mov_b32 m0, s54
	s_nop 0
	global_load_lds_dwordx4 v[214:215], off
	s_waitcnt vmcnt(8)
	s_waitcnt lgkmcnt(0)
	s_barrier
	v_mfma_f32_16x16x32_bf16 v[124:127], v[128:131], v[160:163], v[124:127]
	v_mfma_f32_16x16x32_bf16 v[120:123], v[136:139], v[160:163], v[120:123]
	v_mfma_f32_16x16x32_bf16 v[116:119], v[128:131], v[182:185], v[116:119]
	v_mfma_f32_16x16x32_bf16 v[112:115], v[136:139], v[182:185], v[112:115]
	v_mfma_f32_16x16x32_bf16 v[108:111], v[128:131], v[190:193], v[108:111]
	v_mfma_f32_16x16x32_bf16 v[104:107], v[136:139], v[190:193], v[104:107]
	v_mfma_f32_16x16x32_bf16 v[100:103], v[128:131], v[198:201], v[100:103]
	v_mfma_f32_16x16x32_bf16 v[96:99], v[136:139], v[198:201], v[96:99]
	v_mfma_f32_16x16x32_bf16 v[92:95], v[144:147], v[160:163], v[92:95]
	v_mfma_f32_16x16x32_bf16 v[88:91], v[152:155], v[160:163], v[88:91]
	v_mfma_f32_16x16x32_bf16 v[84:87], v[144:147], v[182:185], v[84:87]
	v_mfma_f32_16x16x32_bf16 v[80:83], v[152:155], v[182:185], v[80:83]
	v_mfma_f32_16x16x32_bf16 v[76:79], v[144:147], v[190:193], v[76:79]
	v_mfma_f32_16x16x32_bf16 v[72:75], v[152:155], v[190:193], v[72:75]
	v_mfma_f32_16x16x32_bf16 v[68:71], v[144:147], v[198:201], v[68:71]
	v_mfma_f32_16x16x32_bf16 v[64:67], v[152:155], v[198:201], v[64:67]
	v_mfma_f32_16x16x32_bf16 v[124:127], v[132:135], v[164:167], v[124:127]
	v_mfma_f32_16x16x32_bf16 v[120:123], v[140:143], v[164:167], v[120:123]
	v_mfma_f32_16x16x32_bf16 v[116:119], v[132:135], v[186:189], v[116:119]
	v_mfma_f32_16x16x32_bf16 v[112:115], v[140:143], v[186:189], v[112:115]
	v_mfma_f32_16x16x32_bf16 v[108:111], v[132:135], v[194:197], v[108:111]
	v_mfma_f32_16x16x32_bf16 v[104:107], v[140:143], v[194:197], v[104:107]
	v_mfma_f32_16x16x32_bf16 v[100:103], v[132:135], v[202:205], v[100:103]
	v_mfma_f32_16x16x32_bf16 v[96:99], v[140:143], v[202:205], v[96:99]
	v_mfma_f32_16x16x32_bf16 v[92:95], v[148:151], v[164:167], v[92:95]
	v_mfma_f32_16x16x32_bf16 v[88:91], v[156:159], v[164:167], v[88:91]
	v_mfma_f32_16x16x32_bf16 v[84:87], v[148:151], v[186:189], v[84:87]
	v_mfma_f32_16x16x32_bf16 v[80:83], v[156:159], v[186:189], v[80:83]
	v_mfma_f32_16x16x32_bf16 v[76:79], v[148:151], v[194:197], v[76:79]
	v_mfma_f32_16x16x32_bf16 v[72:75], v[156:159], v[194:197], v[72:75]
	v_mfma_f32_16x16x32_bf16 v[68:71], v[148:151], v[202:205], v[68:71]
	v_mfma_f32_16x16x32_bf16 v[64:67], v[156:159], v[202:205], v[64:67]
	s_barrier
; #define PG8_STAGE(bufoff, gbase, voff) do { _Pragma("unroll") for (int _i = 0; _i < 2; ++_i) \
;         __builtin_amdgcn_global_load_lds((const unsigned*)((const char*)(gbase) + (voff)[_i]), (PG8_LAS unsigned*)(lds + (bufoff) + ldsw + _i * 8192), 16, 0, 0); } while (0)
; #define PG8_LDA(dst, b, h) do { _Pragma("unroll") for (int m = 0; m < 4; ++m) _Pragma("unroll") for (int k = 0; k < 2; ++k) dst[m][k] = *(const PG8_LAS bf16x8*)(lds + PG8_SA(b, h) + aoff + m * 2048 + k * 1024); } while (0)
; #define PG8_MMA(ai, bj, At, Bt) do { _Pragma("unroll") for (int m = 0; m < 4; ++m) _Pragma("unroll") for (int n = 0; n < 2; ++n) _Pragma("unroll") for (int k = 0; k < 2; ++k) \
;         acc[ai][bj][m][n] = __builtin_amdgcn_mfma_f32_16x16x32_bf16(Bt[n][k], At[m][k], acc[ai][bj][m][n], 0, 0, 0); } while (0)
; #define PG8_WAIT_V(n) asm volatile("s_waitcnt vmcnt(" #n ")" ::: "memory")
; #define PG8_WAIT_L(n) asm volatile("s_waitcnt lgkmcnt(" #n ")" ::: "memory")
; #define PG8_BAR __builtin_amdgcn_s_barrier()
; #define PG8_SCHED __builtin_amdgcn_sched_barrier(0)
; template <class Epi, class Sched, bool ALIGN_EPI = false, bool SP2 = false>
; __device__ __forceinline__ void gemm_phase(PG8_LAS unsigned char* lds, const Gemm g, const Sched& S, const Epi& E, const int wave_id_in) {
;     ...
;             PG8_LDA(At, 1, 1); PG8_STAGE(PG8_SB(1, 0), b3, voffB); PG8_STAGE(PG8_SB(1, 1), b3 + hstep, voffB); PG8_STAGE(PG8_SA(1, 0), a3, voffA);
;             PG8_WAIT_V(8); PG8_WAIT_L(0); PG8_BAR; __builtin_amdgcn_s_setprio(1); PG8_MMA(1, 0, At, B0); PG8_MMA(1, 1, At, B1); __builtin_amdgcn_s_setprio(0); PG8_BAR; PG8_SCHED;
	s_add_i32 s40, s40, s43
	v_lshl_add_u64 v[206:207], v[206:207], 0, s[16:17]
	s_mov_b32 m0, s40
	ds_read_b128 v[160:163], v181 offset:49152
	ds_read_b128 v[164:167], v181 offset:50176
	ds_read_b128 v[182:185], v181 offset:51200
	ds_read_b128 v[186:189], v181 offset:52224
	ds_read_b128 v[190:193], v181 offset:53248
	ds_read_b128 v[194:197], v181 offset:54272
	ds_read_b128 v[198:201], v181 offset:55296
	ds_read_b128 v[202:205], v181 offset:56320
	global_load_lds_dwordx4 v[206:207], off
	s_add_i32 m0, s40, 0x2000
	s_add_u32 s50, s50, 0x40080
	v_lshl_add_u64 v[206:207], v[208:209], 0, s[16:17]
	s_addc_u32 s51, s51, 0
	s_add_i32 s40, s41, s43
	global_load_lds_dwordx4 v[206:207], off
	v_lshl_add_u64 v[206:207], s[50:51], 0, v[170:171]
	s_mov_b32 m0, s40
	s_nop 0
	global_load_lds_dwordx4 v[206:207], off
	v_lshl_add_u64 v[206:207], s[50:51], 0, v[174:175]
	s_add_i32 m0, s40, 0x2000
	s_nop 0
	global_load_lds_dwordx4 v[206:207], off
	v_lshl_add_u64 v[206:207], v[210:211], 0, s[16:17]
	s_mov_b32 m0, s60
	s_nop 0
	global_load_lds_dwordx4 v[206:207], off
	v_lshl_add_u64 v[206:207], v[212:213], 0, s[16:17]
	s_mov_b32 m0, s61
	s_nop 0
	global_load_lds_dwordx4 v[206:207], off
	s_waitcnt vmcnt(8)
	s_waitcnt lgkmcnt(0)
	s_barrier
	v_mfma_f32_16x16x32_bf16 v[60:63], v[128:131], v[160:163], v[60:63]
	v_mfma_f32_16x16x32_bf16 v[56:59], v[136:139], v[160:163], v[56:59]
	v_mfma_f32_16x16x32_bf16 v[52:55], v[128:131], v[182:185], v[52:55]
	v_mfma_f32_16x16x32_bf16 v[48:51], v[136:139], v[182:185], v[48:51]
	v_mfma_f32_16x16x32_bf16 v[44:47], v[128:131], v[190:193], v[44:47]
	v_mfma_f32_16x16x32_bf16 v[40:43], v[136:139], v[190:193], v[40:43]
	v_mfma_f32_16x16x32_bf16 v[36:39], v[128:131], v[198:201], v[36:39]
	v_mfma_f32_16x16x32_bf16 v[32:35], v[136:139], v[198:201], v[32:35]
	v_mfma_f32_16x16x32_bf16 v[28:31], v[144:147], v[160:163], v[28:31]
	v_mfma_f32_16x16x32_bf16 v[24:27], v[152:155], v[160:163], v[24:27]
	v_mfma_f32_16x16x32_bf16 v[20:23], v[144:147], v[182:185], v[20:23]
	v_mfma_f32_16x16x32_bf16 v[16:19], v[152:155], v[182:185], v[16:19]
	v_mfma_f32_16x16x32_bf16 v[12:15], v[144:147], v[190:193], v[12:15]
	v_mfma_f32_16x16x32_bf16 v[8:11], v[152:155], v[190:193], v[8:11]
	v_mfma_f32_16x16x32_bf16 v[4:7], v[144:147], v[198:201], v[4:7]
	v_mfma_f32_16x16x32_bf16 v[0:3], v[152:155], v[198:201], v[0:3]
	v_mfma_f32_16x16x32_bf16 v[60:63], v[132:135], v[164:167], v[60:63]
	v_mfma_f32_16x16x32_bf16 v[56:59], v[140:143], v[164:167], v[56:59]
	v_mfma_f32_16x16x32_bf16 v[52:55], v[132:135], v[186:189], v[52:55]
	v_mfma_f32_16x16x32_bf16 v[48:51], v[140:143], v[186:189], v[48:51]
	v_mfma_f32_16x16x32_bf16 v[44:47], v[132:135], v[194:197], v[44:47]
	v_mfma_f32_16x16x32_bf16 v[40:43], v[140:143], v[194:197], v[40:43]
	v_mfma_f32_16x16x32_bf16 v[36:39], v[132:135], v[202:205], v[36:39]
	v_mfma_f32_16x16x32_bf16 v[32:35], v[140:143], v[202:205], v[32:35]
	v_mfma_f32_16x16x32_bf16 v[28:31], v[148:151], v[164:167], v[28:31]
	v_mfma_f32_16x16x32_bf16 v[24:27], v[156:159], v[164:167], v[24:27]
	v_mfma_f32_16x16x32_bf16 v[20:23], v[148:151], v[186:189], v[20:23]
	v_mfma_f32_16x16x32_bf16 v[16:19], v[156:159], v[186:189], v[16:19]
	v_mfma_f32_16x16x32_bf16 v[12:15], v[148:151], v[194:197], v[12:15]
	v_mfma_f32_16x16x32_bf16 v[8:11], v[156:159], v[194:197], v[8:11]
	v_mfma_f32_16x16x32_bf16 v[4:7], v[148:151], v[202:205], v[4:7]
	v_mfma_f32_16x16x32_bf16 v[0:3], v[156:159], v[202:205], v[0:3]
	s_barrier
	s_cmp_gt_u32 s72, 13
	s_cbranch_scc1 .LBB0_597
	s_mov_b32 s72, s73
	s_branch .LBB0_591

; #define PG8_STAGE(bufoff, gbase, voff) do { _Pragma("unroll") for (int _i = 0; _i < 2; ++_i) \
;         __builtin_amdgcn_global_load_lds((const unsigned*)((const char*)(gbase) + (voff)[_i]), (PG8_LAS unsigned*)(lds + (bufoff) + ldsw + _i * 8192), 16, 0, 0); } while (0)
; #define PG8_LDA(dst, b, h) do { _Pragma("unroll") for (int m = 0; m < 4; ++m) _Pragma("unroll") for (int k = 0; k < 2; ++k) dst[m][k] = *(const PG8_LAS bf16x8*)(lds + PG8_SA(b, h) + aoff + m * 2048 + k * 1024); } while (0)
; #define PG8_LDB(dst, b, h) do { _Pragma("unroll") for (int n = 0; n < 2; ++n) _Pragma("unroll") for (int k = 0; k < 2; ++k) dst[n][k] = *(const PG8_LAS bf16x8*)(lds + PG8_SB(b, h) + boff + n * 2048 + k * 1024); } while (0)
; #define PG8_MMA(ai, bj, At, Bt) do { _Pragma("unroll") for (int m = 0; m < 4; ++m) _Pragma("unroll") for (int n = 0; n < 2; ++n) _Pragma("unroll") for (int k = 0; k < 2; ++k) \
;         acc[ai][bj][m][n] = __builtin_amdgcn_mfma_f32_16x16x32_bf16(Bt[n][k], At[m][k], acc[ai][bj][m][n], 0, 0, 0); } while (0)
; #define PG8_WAIT_V(n) asm volatile("s_waitcnt vmcnt(" #n ")" ::: "memory")
; #define PG8_WAIT_L(n) asm volatile("s_waitcnt lgkmcnt(" #n ")" ::: "memory")
; #define PG8_BAR __builtin_amdgcn_s_barrier()
; #define PG8_SCHED __builtin_amdgcn_sched_barrier(0)
; template <class Epi, class Sched, bool ALIGN_EPI = false, bool SP2 = false>
; __device__ __forceinline__ void gemm_phase(PG8_LAS unsigned char* lds, const Gemm g, const Sched& S, const Epi& E, const int wave_id_in) {
;     ...
;             PG8_LDB(B0, 0, 0); PG8_LDB(B1, 0, 1); PG8_SCHED; PG8_LDA(At, 0, 0); PG8_STAGE(PG8_SA(1, 1), a1 + hstep, voffA);
;             PG8_WAIT_V(8); PG8_WAIT_L(0); PG8_BAR; __builtin_amdgcn_s_setprio(1); PG8_MMA(0, 0, At, B0); PG8_MMA(0, 1, At, B1); __builtin_amdgcn_s_setprio(0); PG8_BAR; PG8_SCHED;
;             PG8_LDA(At, 0, 1); PG8_STAGE(PG8_SB(0, 0), b2, voffB); PG8_STAGE(PG8_SB(0, 1), b2 + hstep, voffB); PG8_STAGE(PG8_SA(0, 0), a2, voffA);
;             PG8_WAIT_V(8); PG8_WAIT_L(0); PG8_BAR; __builtin_amdgcn_s_setprio(1); PG8_MMA(1, 0, At, B0); PG8_MMA(1, 1, At, B1); __builtin_amdgcn_s_setprio(0); PG8_BAR; PG8_SCHED;
.LBB0_680:
	ds_read_b128 v[128:131], v211
	ds_read_b128 v[132:135], v211 offset:1024
	ds_read_b128 v[136:139], v211 offset:2048
	ds_read_b128 v[140:143], v211 offset:3072
	ds_read_b128 v[144:147], v212
	ds_read_b128 v[148:151], v212 offset:1024
	ds_read_b128 v[152:155], v212 offset:2048
	ds_read_b128 v[156:159], v212 offset:3072
	s_add_u32 s40, s36, 0xfff80080
	s_addc_u32 s41, s37, -1
	s_cmp_eq_u32 s64, 28
	s_cselect_b32 s49, s25, s41
	s_cselect_b32 s48, s31, s40
	s_cselect_b32 s47, s23, s63
	s_cselect_b32 s46, s61, s62
	v_lshl_add_u64 v[208:209], s[36:37], 0, v[200:201]
	s_add_i32 m0, s35, 0xc000
	ds_read_b128 v[160:163], v213
	ds_read_b128 v[164:167], v213 offset:1024
	ds_read_b128 v[168:171], v213 offset:2048
	ds_read_b128 v[172:175], v213 offset:3072
	ds_read_b128 v[176:179], v213 offset:4096
	ds_read_b128 v[180:183], v213 offset:5120
	ds_read_b128 v[184:187], v213 offset:6144
	ds_read_b128 v[188:191], v213 offset:7168
	global_load_lds_dwordx4 v[208:209], off
	v_lshl_add_u64 v[208:209], s[36:37], 0, v[202:203]
	s_add_i32 m0, s35, 0xe000
	s_nop 0
	global_load_lds_dwordx4 v[208:209], off
	s_waitcnt vmcnt(8)
	s_waitcnt lgkmcnt(0)
	s_barrier
	v_mfma_f32_16x16x32_bf16 v[124:127], v[128:131], v[160:163], v[124:127]
	v_mfma_f32_16x16x32_bf16 v[120:123], v[136:139], v[160:163], v[120:123]
	v_mfma_f32_16x16x32_bf16 v[116:119], v[128:131], v[168:171], v[116:119]
	v_mfma_f32_16x16x32_bf16 v[112:115], v[136:139], v[168:171], v[112:115]
	v_mfma_f32_16x16x32_bf16 v[108:111], v[128:131], v[176:179], v[108:111]
	v_mfma_f32_16x16x32_bf16 v[104:107], v[136:139], v[176:179], v[104:107]
	v_mfma_f32_16x16x32_bf16 v[100:103], v[128:131], v[184:187], v[100:103]
	v_mfma_f32_16x16x32_bf16 v[96:99], v[136:139], v[184:187], v[96:99]
	v_mfma_f32_16x16x32_bf16 v[60:63], v[144:147], v[160:163], v[60:63]
	v_mfma_f32_16x16x32_bf16 v[56:59], v[152:155], v[160:163], v[56:59]
	v_mfma_f32_16x16x32_bf16 v[52:55], v[144:147], v[168:171], v[52:55]
	v_mfma_f32_16x16x32_bf16 v[48:51], v[152:155], v[168:171], v[48:51]
	v_mfma_f32_16x16x32_bf16 v[44:47], v[144:147], v[176:179], v[44:47]
	v_mfma_f32_16x16x32_bf16 v[40:43], v[152:155], v[176:179], v[40:43]
	v_mfma_f32_16x16x32_bf16 v[36:39], v[144:147], v[184:187], v[36:39]
	v_mfma_f32_16x16x32_bf16 v[32:35], v[152:155], v[184:187], v[32:35]
	v_mfma_f32_16x16x32_bf16 v[124:127], v[132:135], v[164:167], v[124:127]
	v_mfma_f32_16x16x32_bf16 v[120:123], v[140:143], v[164:167], v[120:123]
	v_mfma_f32_16x16x32_bf16 v[116:119], v[132:135], v[172:175], v[116:119]
	v_mfma_f32_16x16x32_bf16 v[112:115], v[140:143], v[172:175], v[112:115]
	v_mfma_f32_16x16x32_bf16 v[108:111], v[132:135], v[180:183], v[108:111]
	v_mfma_f32_16x16x32_bf16 v[104:107], v[140:143], v[180:183], v[104:107]
	v_mfma_f32_16x16x32_bf16 v[100:103], v[132:135], v[188:191], v[100:103]
	v_mfma_f32_16x16x32_bf16 v[96:99], v[140:143], v[188:191], v[96:99]
	v_mfma_f32_16x16x32_bf16 v[60:63], v[148:151], v[164:167], v[60:63]
	v_mfma_f32_16x16x32_bf16 v[56:59], v[156:159], v[164:167], v[56:59]
	v_mfma_f32_16x16x32_bf16 v[52:55], v[148:151], v[172:175], v[52:55]
	v_mfma_f32_16x16x32_bf16 v[48:51], v[156:159], v[172:175], v[48:51]
	v_mfma_f32_16x16x32_bf16 v[44:47], v[148:151], v[180:183], v[44:47]
	v_mfma_f32_16x16x32_bf16 v[40:43], v[156:159], v[180:183], v[40:43]
	v_mfma_f32_16x16x32_bf16 v[36:39], v[148:151], v[188:191], v[36:39]
	v_mfma_f32_16x16x32_bf16 v[32:35], v[156:159], v[188:191], v[32:35]
	s_barrier
	s_add_i32 s40, s59, s42
	v_lshl_add_u64 v[208:209], s[46:47], 0, v[194:195]
	s_mov_b32 m0, s40
	ds_read_b128 v[160:163], v213 offset:16384
	ds_read_b128 v[164:167], v213 offset:17408
	ds_read_b128 v[168:171], v213 offset:18432
	ds_read_b128 v[172:175], v213 offset:19456
	ds_read_b128 v[176:179], v213 offset:20480
	ds_read_b128 v[180:183], v213 offset:21504
	ds_read_b128 v[184:187], v213 offset:22528
	ds_read_b128 v[188:191], v213 offset:23552
	global_load_lds_dwordx4 v[208:209], off
	s_add_i32 m0, s40, 0x2000
	s_add_u32 s66, s46, 0x80000
	v_lshl_add_u64 v[220:221], s[46:47], 0, v[198:199]
	s_addc_u32 s67, s47, 0
	s_add_i32 s40, s60, s42
	global_load_lds_dwordx4 v[220:221], off
	v_lshl_add_u64 v[222:223], s[66:67], 0, v[194:195]
	s_mov_b32 m0, s40
	v_lshl_add_u64 v[224:225], s[48:49], 0, v[196:197]
	global_load_lds_dwordx4 v[222:223], off
	v_lshl_add_u64 v[222:223], s[66:67], 0, v[198:199]
	s_add_i32 m0, s40, 0x2000
	s_nop 0
	global_load_lds_dwordx4 v[222:223], off
	v_lshl_add_u64 v[222:223], s[48:49], 0, v[192:193]
	s_mov_b32 m0, s35
	s_nop 0
	global_load_lds_dwordx4 v[222:223], off
	s_mov_b32 m0, s43
	s_nop 0
	global_load_lds_dwordx4 v[224:225], off
	s_waitcnt vmcnt(8)
	s_waitcnt lgkmcnt(0)
	s_barrier
; #define PG8_STAGE(bufoff, gbase, voff) do { _Pragma("unroll") for (int _i = 0; _i < 2; ++_i) \
;         __builtin_amdgcn_global_load_lds((const unsigned*)((const char*)(gbase) + (voff)[_i]), (PG8_LAS unsigned*)(lds + (bufoff) + ldsw + _i * 8192), 16, 0, 0); } while (0)
; #define PG8_LDA(dst, b, h) do { _Pragma("unroll") for (int m = 0; m < 4; ++m) _Pragma("unroll") for (int k = 0; k < 2; ++k) dst[m][k] = *(const PG8_LAS bf16x8*)(lds + PG8_SA(b, h) + aoff + m * 2048 + k * 1024); } while (0)
; #define PG8_LDB(dst, b, h) do { _Pragma("unroll") for (int n = 0; n < 2; ++n) _Pragma("unroll") for (int k = 0; k < 2; ++k) dst[n][k] = *(const PG8_LAS bf16x8*)(lds + PG8_SB(b, h) + boff + n * 2048 + k * 1024); } while (0)
; #define PG8_MMA(ai, bj, At, Bt) do { _Pragma("unroll") for (int m = 0; m < 4; ++m) _Pragma("unroll") for (int n = 0; n < 2; ++n) _Pragma("unroll") for (int k = 0; k < 2; ++k) \
;         acc[ai][bj][m][n] = __builtin_amdgcn_mfma_f32_16x16x32_bf16(Bt[n][k], At[m][k], acc[ai][bj][m][n], 0, 0, 0); } while (0)
; #define PG8_WAIT_V(n) asm volatile("s_waitcnt vmcnt(" #n ")" ::: "memory")
; #define PG8_WAIT_L(n) asm volatile("s_waitcnt lgkmcnt(" #n ")" ::: "memory")
; #define PG8_BAR __builtin_amdgcn_s_barrier()
; #define PG8_SCHED __builtin_amdgcn_sched_barrier(0)
; template <class Epi, class Sched, bool ALIGN_EPI = false, bool SP2 = false>
; __device__ __forceinline__ void gemm_phase(PG8_LAS unsigned char* lds, const Gemm g, const Sched& S, const Epi& E, const int wave_id_in) {
;     ...
;             PG8_WAIT_V(8); PG8_WAIT_L(0); PG8_BAR; __builtin_amdgcn_s_setprio(1); PG8_MMA(1, 0, At, B0); PG8_MMA(1, 1, At, B1); __builtin_amdgcn_s_setprio(0); PG8_BAR; PG8_SCHED;
;             PG8_LDB(B0, 1, 0); PG8_LDB(B1, 1, 1); PG8_SCHED; PG8_LDA(At, 1, 0); PG8_STAGE(PG8_SA(0, 1), a2 + hstep, voffA);
;             PG8_WAIT_V(8); PG8_WAIT_L(0); PG8_BAR; __builtin_amdgcn_s_setprio(1); PG8_MMA(0, 0, At, B0); PG8_MMA(0, 1, At, B1); __builtin_amdgcn_s_setprio(0); PG8_BAR; PG8_SCHED;
	v_mfma_f32_16x16x32_bf16 v[92:95], v[128:131], v[160:163], v[92:95]
	v_mfma_f32_16x16x32_bf16 v[88:91], v[136:139], v[160:163], v[88:91]
	v_mfma_f32_16x16x32_bf16 v[84:87], v[128:131], v[168:171], v[84:87]
	v_mfma_f32_16x16x32_bf16 v[80:83], v[136:139], v[168:171], v[80:83]
	v_mfma_f32_16x16x32_bf16 v[76:79], v[128:131], v[176:179], v[76:79]
	v_mfma_f32_16x16x32_bf16 v[72:75], v[136:139], v[176:179], v[72:75]
	v_mfma_f32_16x16x32_bf16 v[68:71], v[128:131], v[184:187], v[68:71]
	v_mfma_f32_16x16x32_bf16 v[64:67], v[136:139], v[184:187], v[64:67]
	v_mfma_f32_16x16x32_bf16 v[28:31], v[144:147], v[160:163], v[28:31]
	v_mfma_f32_16x16x32_bf16 v[24:27], v[152:155], v[160:163], v[24:27]
	v_mfma_f32_16x16x32_bf16 v[20:23], v[144:147], v[168:171], v[20:23]
	v_mfma_f32_16x16x32_bf16 v[16:19], v[152:155], v[168:171], v[16:19]
	v_mfma_f32_16x16x32_bf16 v[12:15], v[144:147], v[176:179], v[12:15]
	v_mfma_f32_16x16x32_bf16 v[8:11], v[152:155], v[176:179], v[8:11]
	v_mfma_f32_16x16x32_bf16 v[4:7], v[144:147], v[184:187], v[4:7]
	v_mfma_f32_16x16x32_bf16 v[0:3], v[152:155], v[184:187], v[0:3]
	v_mfma_f32_16x16x32_bf16 v[92:95], v[132:135], v[164:167], v[92:95]
	v_mfma_f32_16x16x32_bf16 v[88:91], v[140:143], v[164:167], v[88:91]
	v_mfma_f32_16x16x32_bf16 v[84:87], v[132:135], v[172:175], v[84:87]
	v_mfma_f32_16x16x32_bf16 v[80:83], v[140:143], v[172:175], v[80:83]
	v_mfma_f32_16x16x32_bf16 v[76:79], v[132:135], v[180:183], v[76:79]
	v_mfma_f32_16x16x32_bf16 v[72:75], v[140:143], v[180:183], v[72:75]
	v_mfma_f32_16x16x32_bf16 v[68:71], v[132:135], v[188:191], v[68:71]
	v_mfma_f32_16x16x32_bf16 v[64:67], v[140:143], v[188:191], v[64:67]
	v_mfma_f32_16x16x32_bf16 v[28:31], v[148:151], v[164:167], v[28:31]
	v_mfma_f32_16x16x32_bf16 v[24:27], v[156:159], v[164:167], v[24:27]
	v_mfma_f32_16x16x32_bf16 v[20:23], v[148:151], v[172:175], v[20:23]
	v_mfma_f32_16x16x32_bf16 v[16:19], v[156:159], v[172:175], v[16:19]
	v_mfma_f32_16x16x32_bf16 v[12:15], v[148:151], v[180:183], v[12:15]
	v_mfma_f32_16x16x32_bf16 v[8:11], v[156:159], v[180:183], v[8:11]
	v_mfma_f32_16x16x32_bf16 v[4:7], v[148:151], v[188:191], v[4:7]
	v_mfma_f32_16x16x32_bf16 v[0:3], v[156:159], v[188:191], v[0:3]
	s_barrier
	s_add_i32 s40, 0, 0x18000
	s_add_i32 s41, 0, 0x1c000
	v_add_u32_e32 v140, s40, v210
	v_add_u32_e32 v156, s41, v210
	ds_read_b128 v[128:131], v140
	ds_read_b128 v[132:135], v140 offset:1024
	ds_read_b128 v[136:139], v140 offset:2048
	ds_read_b128 v[140:143], v140 offset:3072
	ds_read_b128 v[144:147], v156
	ds_read_b128 v[148:151], v156 offset:1024
	ds_read_b128 v[152:155], v156 offset:2048
	ds_read_b128 v[156:159], v156 offset:3072
	s_add_u32 s48, s48, 0x80000
	s_addc_u32 s49, s49, 0
	s_mov_b32 m0, s44
	v_lshl_add_u64 v[226:227], s[48:49], 0, v[192:193]
	ds_read_b128 v[160:163], v213 offset:32768
	ds_read_b128 v[164:167], v213 offset:33792
	ds_read_b128 v[168:171], v213 offset:34816
	ds_read_b128 v[172:175], v213 offset:35840
	ds_read_b128 v[176:179], v213 offset:36864
	ds_read_b128 v[180:183], v213 offset:37888
	ds_read_b128 v[184:187], v213 offset:38912
	ds_read_b128 v[188:191], v213 offset:39936
	global_load_lds_dwordx4 v[226:227], off
	v_lshl_add_u64 v[226:227], s[48:49], 0, v[196:197]
	s_mov_b32 m0, s45
	s_nop 0
	global_load_lds_dwordx4 v[226:227], off
	s_waitcnt vmcnt(8)
	s_waitcnt lgkmcnt(0)
	s_barrier
	v_mfma_f32_16x16x32_bf16 v[124:127], v[128:131], v[160:163], v[124:127]
	v_mfma_f32_16x16x32_bf16 v[120:123], v[136:139], v[160:163], v[120:123]
	v_mfma_f32_16x16x32_bf16 v[116:119], v[128:131], v[168:171], v[116:119]
	v_mfma_f32_16x16x32_bf16 v[112:115], v[136:139], v[168:171], v[112:115]
	v_mfma_f32_16x16x32_bf16 v[108:111], v[128:131], v[176:179], v[108:111]
	v_mfma_f32_16x16x32_bf16 v[104:107], v[136:139], v[176:179], v[104:107]
	v_mfma_f32_16x16x32_bf16 v[100:103], v[128:131], v[184:187], v[100:103]
	v_mfma_f32_16x16x32_bf16 v[96:99], v[136:139], v[184:187], v[96:99]
	v_mfma_f32_16x16x32_bf16 v[60:63], v[144:147], v[160:163], v[60:63]
	v_mfma_f32_16x16x32_bf16 v[56:59], v[152:155], v[160:163], v[56:59]
	v_mfma_f32_16x16x32_bf16 v[52:55], v[144:147], v[168:171], v[52:55]
	v_mfma_f32_16x16x32_bf16 v[48:51], v[152:155], v[168:171], v[48:51]
	v_mfma_f32_16x16x32_bf16 v[44:47], v[144:147], v[176:179], v[44:47]
	v_mfma_f32_16x16x32_bf16 v[40:43], v[152:155], v[176:179], v[40:43]
	v_mfma_f32_16x16x32_bf16 v[36:39], v[144:147], v[184:187], v[36:39]
	v_mfma_f32_16x16x32_bf16 v[32:35], v[152:155], v[184:187], v[32:35]
	v_mfma_f32_16x16x32_bf16 v[124:127], v[132:135], v[164:167], v[124:127]
	v_mfma_f32_16x16x32_bf16 v[120:123], v[140:143], v[164:167], v[120:123]
	v_mfma_f32_16x16x32_bf16 v[116:119], v[132:135], v[172:175], v[116:119]
	v_mfma_f32_16x16x32_bf16 v[112:115], v[140:143], v[172:175], v[112:115]
	v_mfma_f32_16x16x32_bf16 v[108:111], v[132:135], v[180:183], v[108:111]
	v_mfma_f32_16x16x32_bf16 v[104:107], v[140:143], v[180:183], v[104:107]
	v_mfma_f32_16x16x32_bf16 v[100:103], v[132:135], v[188:191], v[100:103]
	v_mfma_f32_16x16x32_bf16 v[96:99], v[140:143], v[188:191], v[96:99]
	v_mfma_f32_16x16x32_bf16 v[60:63], v[148:151], v[164:167], v[60:63]
	v_mfma_f32_16x16x32_bf16 v[56:59], v[156:159], v[164:167], v[56:59]
	v_mfma_f32_16x16x32_bf16 v[52:55], v[148:151], v[172:175], v[52:55]
	v_mfma_f32_16x16x32_bf16 v[48:51], v[156:159], v[172:175], v[48:51]
	v_mfma_f32_16x16x32_bf16 v[44:47], v[148:151], v[180:183], v[44:47]
	v_mfma_f32_16x16x32_bf16 v[40:43], v[156:159], v[180:183], v[40:43]
	v_mfma_f32_16x16x32_bf16 v[36:39], v[148:151], v[188:191], v[36:39]
	v_mfma_f32_16x16x32_bf16 v[32:35], v[156:159], v[188:191], v[32:35]
	s_barrier
; #define PG8_STAGE(bufoff, gbase, voff) do { _Pragma("unroll") for (int _i = 0; _i < 2; ++_i) \
;         __builtin_amdgcn_global_load_lds((const unsigned*)((const char*)(gbase) + (voff)[_i]), (PG8_LAS unsigned*)(lds + (bufoff) + ldsw + _i * 8192), 16, 0, 0); } while (0)
; #define PG8_LDA(dst, b, h) do { _Pragma("unroll") for (int m = 0; m < 4; ++m) _Pragma("unroll") for (int k = 0; k < 2; ++k) dst[m][k] = *(const PG8_LAS bf16x8*)(lds + PG8_SA(b, h) + aoff + m * 2048 + k * 1024); } while (0)
; #define PG8_MMA(ai, bj, At, Bt) do { _Pragma("unroll") for (int m = 0; m < 4; ++m) _Pragma("unroll") for (int n = 0; n < 2; ++n) _Pragma("unroll") for (int k = 0; k < 2; ++k) \
;         acc[ai][bj][m][n] = __builtin_amdgcn_mfma_f32_16x16x32_bf16(Bt[n][k], At[m][k], acc[ai][bj][m][n], 0, 0, 0); } while (0)
; #define PG8_WAIT_V(n) asm volatile("s_waitcnt vmcnt(" #n ")" ::: "memory")
; #define PG8_WAIT_L(n) asm volatile("s_waitcnt lgkmcnt(" #n ")" ::: "memory")
; #define PG8_BAR __builtin_amdgcn_s_barrier()
; #define PG8_SCHED __builtin_amdgcn_sched_barrier(0)
; template <class Epi, class Sched, bool ALIGN_EPI = false, bool SP2 = false>
; __device__ __forceinline__ void gemm_phase(PG8_LAS unsigned char* lds, const Gemm g, const Sched& S, const Epi& E, const int wave_id_in) {
;     ...
;         for (int t = 0; t < nt; t += 2) {
;             const bool last = (t == nt - 2);
;             const char* a1 = cA + (size_t)(t + 1) * kstep;
;             const char* a2 = last ? nA : cA + (size_t)(t + 2) * kstep; const char* b2 = last ? nB : cB + (size_t)(t + 2) * kstep;
;             const char* a3 = a2 + kstep; const char* b3 = b2 + kstep;
;     ...
;             PG8_LDA(At, 1, 1); PG8_STAGE(PG8_SB(1, 0), b3, voffB); PG8_STAGE(PG8_SB(1, 1), b3 + hstep, voffB); PG8_STAGE(PG8_SA(1, 0), a3, voffA);
;             PG8_WAIT_V(8); PG8_WAIT_L(0); PG8_BAR; __builtin_amdgcn_s_setprio(1); PG8_MMA(1, 0, At, B0); PG8_MMA(1, 1, At, B1); __builtin_amdgcn_s_setprio(0); PG8_BAR; PG8_SCHED;
	s_add_i32 s40, s40, s42
	v_lshl_add_u64 v[208:209], v[208:209], 0, s[12:13]
	s_mov_b32 m0, s40
	ds_read_b128 v[160:163], v213 offset:49152
	ds_read_b128 v[164:167], v213 offset:50176
	ds_read_b128 v[168:171], v213 offset:51200
	ds_read_b128 v[172:175], v213 offset:52224
	ds_read_b128 v[176:179], v213 offset:53248
	ds_read_b128 v[180:183], v213 offset:54272
	ds_read_b128 v[184:187], v213 offset:55296
	ds_read_b128 v[188:191], v213 offset:56320
	global_load_lds_dwordx4 v[208:209], off
	s_add_i32 m0, s40, 0x2000
	s_add_u32 s46, s46, 0x80080
	v_lshl_add_u64 v[208:209], v[220:221], 0, s[12:13]
	s_addc_u32 s47, s47, 0
	s_add_i32 s40, s41, s42
	global_load_lds_dwordx4 v[208:209], off
	v_lshl_add_u64 v[208:209], s[46:47], 0, v[194:195]
	s_mov_b32 m0, s40
	s_nop 0
	global_load_lds_dwordx4 v[208:209], off
	v_lshl_add_u64 v[208:209], s[46:47], 0, v[198:199]
	s_add_i32 m0, s40, 0x2000
	s_nop 0
	global_load_lds_dwordx4 v[208:209], off
	v_lshl_add_u64 v[208:209], v[222:223], 0, s[12:13]
	s_mov_b32 m0, s53
	s_nop 0
	global_load_lds_dwordx4 v[208:209], off
	v_lshl_add_u64 v[208:209], v[224:225], 0, s[12:13]
	s_mov_b32 m0, s54
	s_nop 0
	global_load_lds_dwordx4 v[208:209], off
	s_waitcnt vmcnt(8)
	s_waitcnt lgkmcnt(0)
	s_barrier
	v_mfma_f32_16x16x32_bf16 v[92:95], v[128:131], v[160:163], v[92:95]
	v_mfma_f32_16x16x32_bf16 v[88:91], v[136:139], v[160:163], v[88:91]
	v_mfma_f32_16x16x32_bf16 v[84:87], v[128:131], v[168:171], v[84:87]
	v_mfma_f32_16x16x32_bf16 v[80:83], v[136:139], v[168:171], v[80:83]
	v_mfma_f32_16x16x32_bf16 v[76:79], v[128:131], v[176:179], v[76:79]
	v_mfma_f32_16x16x32_bf16 v[72:75], v[136:139], v[176:179], v[72:75]
	v_mfma_f32_16x16x32_bf16 v[68:71], v[128:131], v[184:187], v[68:71]
	v_mfma_f32_16x16x32_bf16 v[64:67], v[136:139], v[184:187], v[64:67]
	v_mfma_f32_16x16x32_bf16 v[28:31], v[144:147], v[160:163], v[28:31]
	v_mfma_f32_16x16x32_bf16 v[24:27], v[152:155], v[160:163], v[24:27]
	v_mfma_f32_16x16x32_bf16 v[20:23], v[144:147], v[168:171], v[20:23]
	v_mfma_f32_16x16x32_bf16 v[16:19], v[152:155], v[168:171], v[16:19]
	v_mfma_f32_16x16x32_bf16 v[12:15], v[144:147], v[176:179], v[12:15]
	v_mfma_f32_16x16x32_bf16 v[8:11], v[152:155], v[176:179], v[8:11]
	v_mfma_f32_16x16x32_bf16 v[4:7], v[144:147], v[184:187], v[4:7]
	v_mfma_f32_16x16x32_bf16 v[0:3], v[152:155], v[184:187], v[0:3]
	v_mfma_f32_16x16x32_bf16 v[92:95], v[132:135], v[164:167], v[92:95]
	v_mfma_f32_16x16x32_bf16 v[88:91], v[140:143], v[164:167], v[88:91]
	v_mfma_f32_16x16x32_bf16 v[84:87], v[132:135], v[172:175], v[84:87]
	v_mfma_f32_16x16x32_bf16 v[80:83], v[140:143], v[172:175], v[80:83]
	v_mfma_f32_16x16x32_bf16 v[76:79], v[132:135], v[180:183], v[76:79]
	v_mfma_f32_16x16x32_bf16 v[72:75], v[140:143], v[180:183], v[72:75]
	v_mfma_f32_16x16x32_bf16 v[68:71], v[132:135], v[188:191], v[68:71]
	v_mfma_f32_16x16x32_bf16 v[64:67], v[140:143], v[188:191], v[64:67]
	v_mfma_f32_16x16x32_bf16 v[28:31], v[148:151], v[164:167], v[28:31]
	v_mfma_f32_16x16x32_bf16 v[24:27], v[156:159], v[164:167], v[24:27]
	v_mfma_f32_16x16x32_bf16 v[20:23], v[148:151], v[172:175], v[20:23]
	v_mfma_f32_16x16x32_bf16 v[16:19], v[156:159], v[172:175], v[16:19]
	v_mfma_f32_16x16x32_bf16 v[12:15], v[148:151], v[180:183], v[12:15]
	v_mfma_f32_16x16x32_bf16 v[8:11], v[156:159], v[180:183], v[8:11]
	v_mfma_f32_16x16x32_bf16 v[4:7], v[148:151], v[188:191], v[4:7]
	v_mfma_f32_16x16x32_bf16 v[0:3], v[156:159], v[188:191], v[0:3]
	s_barrier
	s_add_i32 s64, s64, 2
	s_add_u32 s36, s36, 0x100
	s_addc_u32 s37, s37, 0
	s_add_u32 s62, s62, 0x100
	s_addc_u32 s63, s63, 0
	s_cmp_gt_u32 s64, 29
	s_cbranch_scc0 .LBB0_680
	s_and_b64 vcc, exec, s[14:15]
	s_cbranch_vccz .LBB0_683
	s_barrier

; #define PG8_STAGE(bufoff, gbase, voff) do { _Pragma("unroll") for (int _i = 0; _i < 2; ++_i) \
;         __builtin_amdgcn_global_load_lds((const unsigned*)((const char*)(gbase) + (voff)[_i]), (PG8_LAS unsigned*)(lds + (bufoff) + ldsw + _i * 8192), 16, 0, 0); } while (0)
; #define PG8_LDA(dst, b, h) do { _Pragma("unroll") for (int m = 0; m < 4; ++m) _Pragma("unroll") for (int k = 0; k < 2; ++k) dst[m][k] = *(const PG8_LAS bf16x8*)(lds + PG8_SA(b, h) + aoff + m * 2048 + k * 1024); } while (0)
; #define PG8_LDB(dst, b, h) do { _Pragma("unroll") for (int n = 0; n < 2; ++n) _Pragma("unroll") for (int k = 0; k < 2; ++k) dst[n][k] = *(const PG8_LAS bf16x8*)(lds + PG8_SB(b, h) + boff + n * 2048 + k * 1024); } while (0)
; #define PG8_MMA(ai, bj, At, Bt) do { _Pragma("unroll") for (int m = 0; m < 4; ++m) _Pragma("unroll") for (int n = 0; n < 2; ++n) _Pragma("unroll") for (int k = 0; k < 2; ++k) \
;         acc[ai][bj][m][n] = __builtin_amdgcn_mfma_f32_16x16x32_bf16(Bt[n][k], At[m][k], acc[ai][bj][m][n], 0, 0, 0); } while (0)
; #define PG8_WAIT_V(n) asm volatile("s_waitcnt vmcnt(" #n ")" ::: "memory")
; #define PG8_WAIT_L(n) asm volatile("s_waitcnt lgkmcnt(" #n ")" ::: "memory")
; #define PG8_BAR __builtin_amdgcn_s_barrier()
; #define PG8_SCHED __builtin_amdgcn_sched_barrier(0)
; template <class Epi>
; __device__ __forceinline__ void gemm_half_phase(PG8_LAS unsigned char* lds, const Gemm g, const Unit cur, const Epi& E, const int wave_id_in) {
;     ...
;         PG8_LDB(B0, 0, 0); PG8_LDB(B1, 0, 1); PG8_SCHED; PG8_LDA(At, 0, 0);
;         PG8_WAIT_V(6); PG8_WAIT_L(0); PG8_BAR; __builtin_amdgcn_s_setprio(1); PG8_MMA(0, 0, At, B0); __builtin_amdgcn_s_setprio(0); PG8_BAR; PG8_SCHED;
;         PG8_STAGE(PG8_SB(0, 0), b2, voffB); PG8_STAGE(PG8_SB(0, 1), b2 + hstep, voffB); PG8_STAGE(PG8_SA(0, 0), a2, voffA);
;         PG8_WAIT_V(6); PG8_BAR; __builtin_amdgcn_s_setprio(1); PG8_MMA(0, 1, At, B1); __builtin_amdgcn_s_setprio(0); PG8_BAR; PG8_SCHED;
.LBB0_769:
	ds_read_b128 v[44:47], v32
	ds_read_b128 v[52:55], v32 offset:1024
	ds_read_b128 v[56:59], v32 offset:2048
	ds_read_b128 v[64:67], v32 offset:3072
	ds_read_b128 v[88:91], v33
	ds_read_b128 v[92:95], v33 offset:1024
	ds_read_b128 v[104:107], v33 offset:2048
	ds_read_b128 v[108:111], v33 offset:3072
	s_cmp_eq_u32 s43, 28
	s_cselect_b32 s55, s7, s42
	s_cselect_b32 s54, s6, s39
	s_cselect_b32 s29, s9, s31
	s_cselect_b32 s28, s8, s30
	ds_read_b128 v[112:115], v34
	ds_read_b128 v[116:119], v34 offset:1024
	ds_read_b128 v[120:123], v34 offset:2048
	ds_read_b128 v[124:127], v34 offset:3072
	ds_read_b128 v[128:131], v34 offset:4096
	ds_read_b128 v[132:135], v34 offset:5120
	ds_read_b128 v[136:139], v34 offset:6144
	ds_read_b128 v[140:143], v34 offset:7168
	s_waitcnt vmcnt(6)
	s_waitcnt lgkmcnt(0)
	s_barrier
	v_mfma_f32_16x16x32_bf16 v[20:23], v[44:47], v[112:115], v[20:23]
	v_mfma_f32_16x16x32_bf16 v[16:19], v[56:59], v[112:115], v[16:19]
	v_mfma_f32_16x16x32_bf16 v[100:103], v[44:47], v[120:123], v[100:103]
	v_mfma_f32_16x16x32_bf16 v[96:99], v[56:59], v[120:123], v[96:99]
	v_mfma_f32_16x16x32_bf16 v[84:87], v[44:47], v[128:131], v[84:87]
	v_mfma_f32_16x16x32_bf16 v[80:83], v[56:59], v[128:131], v[80:83]
	v_mfma_f32_16x16x32_bf16 v[12:15], v[44:47], v[136:139], v[12:15]
	v_mfma_f32_16x16x32_bf16 v[8:11], v[56:59], v[136:139], v[8:11]
	v_mfma_f32_16x16x32_bf16 v[20:23], v[52:55], v[116:119], v[20:23]
	v_mfma_f32_16x16x32_bf16 v[16:19], v[64:67], v[116:119], v[16:19]
	v_mfma_f32_16x16x32_bf16 v[100:103], v[52:55], v[124:127], v[100:103]
	v_mfma_f32_16x16x32_bf16 v[96:99], v[64:67], v[124:127], v[96:99]
	v_mfma_f32_16x16x32_bf16 v[84:87], v[52:55], v[132:135], v[84:87]
	v_mfma_f32_16x16x32_bf16 v[80:83], v[64:67], v[132:135], v[80:83]
	v_mfma_f32_16x16x32_bf16 v[12:15], v[52:55], v[140:143], v[12:15]
	v_mfma_f32_16x16x32_bf16 v[8:11], v[64:67], v[140:143], v[8:11]
	s_barrier
	s_mov_b32 m0, s46
	v_lshl_add_u64 v[144:145], s[28:29], 0, v[26:27]
	s_add_u32 s56, s28, 0x80000
	global_load_lds_dwordx4 v[144:145], off
	v_lshl_add_u64 v[146:147], s[28:29], 0, v[30:31]
	s_mov_b32 m0, s47
	s_addc_u32 s57, s29, 0
	global_load_lds_dwordx4 v[146:147], off
	v_lshl_add_u64 v[38:39], s[56:57], 0, v[26:27]
	s_mov_b32 m0, s48
	v_lshl_add_u64 v[148:149], s[54:55], 0, v[24:25]
	global_load_lds_dwordx4 v[38:39], off
	v_lshl_add_u64 v[38:39], s[56:57], 0, v[30:31]
	s_mov_b32 m0, s49
	v_lshl_add_u64 v[150:151], s[54:55], 0, v[28:29]
	global_load_lds_dwordx4 v[38:39], off
	s_mov_b32 m0, s35
	s_nop 0
	global_load_lds_dwordx4 v[148:149], off
	s_mov_b32 m0, s36
	s_nop 0
	global_load_lds_dwordx4 v[150:151], off
	s_waitcnt vmcnt(6)
	s_barrier
	v_mfma_f32_16x16x32_bf16 v[38:41], v[88:91], v[112:115], v[40:43]
	v_mfma_f32_16x16x32_bf16 v[42:45], v[104:107], v[112:115], v[48:51]
	v_mfma_f32_16x16x32_bf16 v[48:51], v[88:91], v[120:123], v[76:79]
	v_mfma_f32_16x16x32_bf16 v[52:55], v[92:95], v[124:127], v[48:51]
	v_mfma_f32_16x16x32_bf16 v[48:51], v[104:107], v[120:123], v[72:75]
	v_mfma_f32_16x16x32_bf16 v[56:59], v[108:111], v[124:127], v[48:51]
	v_mfma_f32_16x16x32_bf16 v[48:51], v[88:91], v[128:131], v[68:71]
	v_mfma_f32_16x16x32_bf16 v[64:67], v[92:95], v[132:135], v[48:51]
	v_mfma_f32_16x16x32_bf16 v[48:51], v[104:107], v[128:131], v[60:63]
	v_mfma_f32_16x16x32_bf16 v[4:7], v[88:91], v[136:139], v[4:7]
	v_mfma_f32_16x16x32_bf16 v[0:3], v[104:107], v[136:139], v[0:3]
	v_mfma_f32_16x16x32_bf16 v[38:41], v[92:95], v[116:119], v[38:41]
	v_mfma_f32_16x16x32_bf16 v[60:63], v[108:111], v[132:135], v[48:51]
	v_mfma_f32_16x16x32_bf16 v[4:7], v[92:95], v[140:143], v[4:7]
	v_mfma_f32_16x16x32_bf16 v[0:3], v[108:111], v[140:143], v[0:3]
	v_mfma_f32_16x16x32_bf16 v[44:47], v[108:111], v[116:119], v[42:45]
	s_barrier
; #define PG8_STAGE(bufoff, gbase, voff) do { _Pragma("unroll") for (int _i = 0; _i < 2; ++_i) \
;         __builtin_amdgcn_global_load_lds((const unsigned*)((const char*)(gbase) + (voff)[_i]), (PG8_LAS unsigned*)(lds + (bufoff) + ldsw + _i * 8192), 16, 0, 0); } while (0)
; #define PG8_LDA(dst, b, h) do { _Pragma("unroll") for (int m = 0; m < 4; ++m) _Pragma("unroll") for (int k = 0; k < 2; ++k) dst[m][k] = *(const PG8_LAS bf16x8*)(lds + PG8_SA(b, h) + aoff + m * 2048 + k * 1024); } while (0)
; #define PG8_LDB(dst, b, h) do { _Pragma("unroll") for (int n = 0; n < 2; ++n) _Pragma("unroll") for (int k = 0; k < 2; ++k) dst[n][k] = *(const PG8_LAS bf16x8*)(lds + PG8_SB(b, h) + boff + n * 2048 + k * 1024); } while (0)
; #define PG8_MMA(ai, bj, At, Bt) do { _Pragma("unroll") for (int m = 0; m < 4; ++m) _Pragma("unroll") for (int n = 0; n < 2; ++n) _Pragma("unroll") for (int k = 0; k < 2; ++k) \
;         acc[ai][bj][m][n] = __builtin_amdgcn_mfma_f32_16x16x32_bf16(Bt[n][k], At[m][k], acc[ai][bj][m][n], 0, 0, 0); } while (0)
; #define PG8_WAIT_V(n) asm volatile("s_waitcnt vmcnt(" #n ")" ::: "memory")
; #define PG8_WAIT_L(n) asm volatile("s_waitcnt lgkmcnt(" #n ")" ::: "memory")
; #define PG8_BAR __builtin_amdgcn_s_barrier()
; #define PG8_SCHED __builtin_amdgcn_sched_barrier(0)
; template <class Epi>
; __device__ __forceinline__ void gemm_half_phase(PG8_LAS unsigned char* lds, const Gemm g, const Unit cur, const Epi& E, const int wave_id_in) {
;     ...
;         PG8_LDB(B0, 1, 0); PG8_LDB(B1, 1, 1); PG8_SCHED; PG8_LDA(At, 1, 0);
;         PG8_WAIT_V(6); PG8_WAIT_L(0); PG8_BAR; __builtin_amdgcn_s_setprio(1); PG8_MMA(0, 0, At, B0); __builtin_amdgcn_s_setprio(0); PG8_BAR; PG8_SCHED;
;         PG8_STAGE(PG8_SB(1, 0), b3, voffB); PG8_STAGE(PG8_SB(1, 1), b3 + hstep, voffB); PG8_STAGE(PG8_SA(1, 0), a3, voffA);
;         PG8_WAIT_V(6); PG8_BAR; __builtin_amdgcn_s_setprio(1); PG8_MMA(0, 1, At, B1); __builtin_amdgcn_s_setprio(0); PG8_BAR; PG8_SCHED;
;     }
	ds_read_b128 v[48:51], v35
	ds_read_b128 v[68:71], v35 offset:1024
	ds_read_b128 v[72:75], v35 offset:2048
	ds_read_b128 v[76:79], v35 offset:3072
	ds_read_b128 v[88:91], v36
	ds_read_b128 v[92:95], v36 offset:1024
	ds_read_b128 v[104:107], v36 offset:2048
	ds_read_b128 v[108:111], v36 offset:3072
	ds_read_b128 v[112:115], v34 offset:32768
	ds_read_b128 v[116:119], v34 offset:33792
	ds_read_b128 v[120:123], v34 offset:34816
	ds_read_b128 v[124:127], v34 offset:35840
	ds_read_b128 v[128:131], v34 offset:36864
	ds_read_b128 v[132:135], v34 offset:37888
	ds_read_b128 v[136:139], v34 offset:38912
	ds_read_b128 v[140:143], v34 offset:39936
	s_waitcnt vmcnt(6)
	s_waitcnt lgkmcnt(0)
	s_barrier
	v_mfma_f32_16x16x32_bf16 v[20:23], v[48:51], v[112:115], v[20:23]
	v_mfma_f32_16x16x32_bf16 v[16:19], v[72:75], v[112:115], v[16:19]
	v_mfma_f32_16x16x32_bf16 v[100:103], v[48:51], v[120:123], v[100:103]
	v_mfma_f32_16x16x32_bf16 v[96:99], v[72:75], v[120:123], v[96:99]
	v_mfma_f32_16x16x32_bf16 v[84:87], v[48:51], v[128:131], v[84:87]
	v_mfma_f32_16x16x32_bf16 v[80:83], v[72:75], v[128:131], v[80:83]
	v_mfma_f32_16x16x32_bf16 v[12:15], v[48:51], v[136:139], v[12:15]
	v_mfma_f32_16x16x32_bf16 v[8:11], v[72:75], v[136:139], v[8:11]
	v_mfma_f32_16x16x32_bf16 v[20:23], v[68:71], v[116:119], v[20:23]
	v_mfma_f32_16x16x32_bf16 v[16:19], v[76:79], v[116:119], v[16:19]
	v_mfma_f32_16x16x32_bf16 v[100:103], v[68:71], v[124:127], v[100:103]
	v_mfma_f32_16x16x32_bf16 v[96:99], v[76:79], v[124:127], v[96:99]
	v_mfma_f32_16x16x32_bf16 v[84:87], v[68:71], v[132:135], v[84:87]
	v_mfma_f32_16x16x32_bf16 v[80:83], v[76:79], v[132:135], v[80:83]
	v_mfma_f32_16x16x32_bf16 v[12:15], v[68:71], v[140:143], v[12:15]
	v_mfma_f32_16x16x32_bf16 v[8:11], v[76:79], v[140:143], v[8:11]
	s_barrier
	s_mov_b32 m0, s50
	v_lshl_add_u64 v[42:43], v[144:145], 0, s[10:11]
	s_add_u32 s28, s28, 0x80080
	global_load_lds_dwordx4 v[42:43], off
	v_lshl_add_u64 v[42:43], v[146:147], 0, s[10:11]
	s_mov_b32 m0, s51
	s_addc_u32 s29, s29, 0
	global_load_lds_dwordx4 v[42:43], off
	v_lshl_add_u64 v[42:43], s[28:29], 0, v[26:27]
	s_mov_b32 m0, s52
	s_nop 0
	global_load_lds_dwordx4 v[42:43], off
	v_lshl_add_u64 v[42:43], s[28:29], 0, v[30:31]
	s_mov_b32 m0, s53
	s_nop 0
	global_load_lds_dwordx4 v[42:43], off
	v_lshl_add_u64 v[42:43], v[148:149], 0, s[10:11]
	s_mov_b32 m0, s37
	s_nop 0
	global_load_lds_dwordx4 v[42:43], off
	v_lshl_add_u64 v[42:43], v[150:151], 0, s[10:11]
	s_mov_b32 m0, s38
	s_nop 0
	global_load_lds_dwordx4 v[42:43], off
	s_waitcnt vmcnt(6)
	s_barrier
	v_mfma_f32_16x16x32_bf16 v[44:47], v[104:107], v[112:115], v[44:47]
	v_mfma_f32_16x16x32_bf16 v[48:51], v[108:111], v[116:119], v[44:47]
	v_mfma_f32_16x16x32_bf16 v[44:47], v[88:91], v[120:123], v[52:55]
	v_mfma_f32_16x16x32_bf16 v[76:79], v[92:95], v[124:127], v[44:47]
	v_mfma_f32_16x16x32_bf16 v[44:47], v[104:107], v[120:123], v[56:59]
	v_mfma_f32_16x16x32_bf16 v[72:75], v[108:111], v[124:127], v[44:47]
	v_mfma_f32_16x16x32_bf16 v[44:47], v[88:91], v[128:131], v[64:67]
	v_mfma_f32_16x16x32_bf16 v[38:41], v[88:91], v[112:115], v[38:41]
	v_mfma_f32_16x16x32_bf16 v[68:71], v[92:95], v[132:135], v[44:47]
	v_mfma_f32_16x16x32_bf16 v[44:47], v[104:107], v[128:131], v[60:63]
	v_mfma_f32_16x16x32_bf16 v[4:7], v[88:91], v[136:139], v[4:7]
	v_mfma_f32_16x16x32_bf16 v[0:3], v[104:107], v[136:139], v[0:3]
	v_mfma_f32_16x16x32_bf16 v[40:43], v[92:95], v[116:119], v[38:41]
	v_mfma_f32_16x16x32_bf16 v[60:63], v[108:111], v[132:135], v[44:47]
	v_mfma_f32_16x16x32_bf16 v[4:7], v[92:95], v[140:143], v[4:7]
	v_mfma_f32_16x16x32_bf16 v[0:3], v[108:111], v[140:143], v[0:3]
	s_barrier
	s_add_i32 s43, s43, 2
	s_add_u32 s39, s39, 0x100
	s_addc_u32 s42, s42, 0
	s_add_u32 s30, s30, 0x100
	s_addc_u32 s31, s31, 0
	s_cmp_gt_u32 s43, 29
	s_cbranch_scc0 .LBB0_769
	s_cmpk_lt_u32 s34, 0x100
	s_cselect_b64 s[28:29], -1, 0
	s_and_b64 vcc, exec, s[28:29]
	s_cbranch_vccz .LBB0_772
	s_barrier

;     __host__ __device__ bool next(int i, Unit& u) const { const long L = (long)i * G + c; if (L >= maxL) return false; return unit_of(L, u); }
;     __device__ __forceinline__ const char* a_base(const Gemm& g, const Unit& u, size_t tstep) const { return (const char*)g.A + (size_t)u.pm * tstep; }
;     __device__ __forceinline__ const char* b_base(const Gemm& g, const Unit& u, size_t tstep) const { return (const char*)g.Bt + (size_t)u.pn * tstep; }
; #define PG8_STAGE(bufoff, gbase, voff) do { _Pragma("unroll") for (int _i = 0; _i < 2; ++_i) \
;         __builtin_amdgcn_global_load_lds((const unsigned*)((const char*)(gbase) + (voff)[_i]), (PG8_LAS unsigned*)(lds + (bufoff) + ldsw + _i * 8192), 16, 0, 0); } while (0)
; #define PG8_WAIT_V(n) asm volatile("s_waitcnt vmcnt(" #n ")" ::: "memory")
; #define PG8_WAIT_L(n) asm volatile("s_waitcnt lgkmcnt(" #n ")" ::: "memory")
; template <class Epi, class Sched, bool ALIGN_EPI = false, bool SP2 = false>
; __device__ __forceinline__ void gemm_phase(PG8_LAS unsigned char* lds, const Gemm g, const Sched& S, const Epi& E, const int wave_id_in) {
;     ...
;         const bool has_next = S.next(ui + 1, nxt);
;         const char* nA = has_next ? S.a_base(g, nxt, tstep) : cA; const char* nB = has_next ? S.b_base(g, nxt, tstep) : cB;
;         for (int t = 0; t < nt; t += 2) {
;             const bool last = (t == nt - 2);
;             const char* a1 = cA + (size_t)(t + 1) * kstep;
;             const char* a2 = last ? nA : cA + (size_t)(t + 2) * kstep; const char* b2 = last ? nB : cB + (size_t)(t + 2) * kstep;
;             const char* a3 = a2 + kstep; const char* b3 = b2 + kstep;
;             if (last && has_next) S.a_ready(nxt);
;             if constexpr (SP2) {
;             PG8_LDB(B0, 0, 0); PG8_LDB(B1, 0, 1); PG8_SCHED; PG8_LDA(At, 0, 0); PG8_STAGE(PG8_SA(1, 1), a1 + hstep, voffA);
;             PG8_WAIT_V(8); PG8_WAIT_L(0); PG8_BAR; __builtin_amdgcn_s_setprio(1); PG8_MMA(0, 0, At, B0); PG8_MMA(0, 1, At, B1); __builtin_amdgcn_s_setprio(0); PG8_BAR; PG8_SCHED;
;             PG8_LDA(At, 0, 1); PG8_STAGE(PG8_SB(0, 0), b2, voffB); PG8_STAGE(PG8_SB(0, 1), b2 + hstep, voffB); PG8_STAGE(PG8_SA(0, 0), a2, voffA);
;             PG8_WAIT_V(8); PG8_WAIT_L(0); PG8_BAR; __builtin_amdgcn_s_setprio(1); PG8_MMA(1, 0, At, B0); PG8_MMA(1, 1, At, B1); __builtin_amdgcn_s_setprio(0); PG8_BAR; PG8_SCHED;
.LBB0_818:
	s_ashr_i32 s67, s66, 31
	s_lshl_b64 s[68:69], s[66:67], 20
	s_add_u32 s68, s78, s68
	s_addc_u32 s69, s79, s69
	s_and_b64 s[70:71], s[6:7], exec
	s_cselect_b32 s9, s69, s11
	s_cselect_b32 s27, s68, s10
	s_ashr_i32 s65, s64, 31
	s_lshl_b64 s[70:71], s[64:65], 20
	s_add_u32 s70, s44, s70
	s_addc_u32 s71, s45, s71
	s_and_b64 s[72:73], s[6:7], exec
	s_cselect_b32 s65, s71, s13
	s_cselect_b32 s74, s70, s12
	s_add_u32 s10, s10, 0x80080
	s_addc_u32 s11, s11, 0
	s_add_u32 s75, s12, 0x100
	s_addc_u32 vcc_lo, s13, 0
	s_mov_b32 vcc_hi, -2
	s_waitcnt lgkmcnt(0)
	ds_read_b128 v[44:47], v221
	ds_read_b128 v[48:51], v221 offset:1024
	ds_read_b128 v[56:59], v221 offset:2048
	s_waitcnt lgkmcnt(0)
	ds_read_b128 v[60:63], v221 offset:3072
	ds_read_b128 v[68:71], v222
	ds_read_b128 v[72:75], v222 offset:1024
	ds_read_b128 v[76:79], v222 offset:2048
	ds_read_b128 v[84:87], v222 offset:3072
	s_add_u32 s12, s10, 0xfff80080
	s_addc_u32 s13, s11, -1
	s_cmp_eq_u32 vcc_hi, 28
	s_cselect_b32 s73, s9, s13
	s_cselect_b32 s72, s27, s12
	s_cselect_b32 s13, s65, vcc_lo
	s_cselect_b32 s12, s74, s75
	v_lshl_add_u64 v[208:209], s[10:11], 0, v[194:195]
	s_add_i32 m0, s81, 0xc000
	ds_read_b128 v[92:95], v223
	ds_read_b128 v[96:99], v223 offset:1024
	ds_read_b128 v[120:123], v223 offset:2048
	ds_read_b128 v[124:127], v223 offset:3072
	ds_read_b128 v[168:171], v223 offset:4096
	ds_read_b128 v[180:183], v223 offset:5120
	ds_read_b128 v[200:203], v223 offset:6144
	ds_read_b128 v[204:207], v223 offset:7168
	global_load_lds_dwordx4 v[208:209], off
	v_lshl_add_u64 v[208:209], s[10:11], 0, v[196:197]
	s_add_i32 m0, s81, 0xe000
	s_nop 0
	global_load_lds_dwordx4 v[208:209], off
	s_waitcnt vmcnt(8)
	s_waitcnt lgkmcnt(0)
	s_barrier
	v_mfma_f32_16x16x32_bf16 v[40:43], v[44:47], v[92:95], 0
	v_mfma_f32_16x16x32_bf16 v[36:39], v[56:59], v[92:95], 0
	v_mfma_f32_16x16x32_bf16 v[104:107], v[68:71], v[92:95], 0
	v_mfma_f32_16x16x32_bf16 v[92:95], v[76:79], v[92:95], 0
	v_mfma_f32_16x16x32_bf16 v[108:111], v[76:79], v[120:123], 0
	v_mfma_f32_16x16x32_bf16 v[40:43], v[48:51], v[96:99], v[40:43]
	v_mfma_f32_16x16x32_bf16 v[36:39], v[60:63], v[96:99], v[36:39]
	v_mfma_f32_16x16x32_bf16 v[172:175], v[44:47], v[120:123], 0
	v_mfma_f32_16x16x32_bf16 v[164:167], v[56:59], v[120:123], 0
	v_mfma_f32_16x16x32_bf16 v[104:107], v[72:75], v[96:99], v[104:107]
	v_mfma_f32_16x16x32_bf16 v[92:95], v[84:87], v[96:99], v[92:95]
	v_mfma_f32_16x16x32_bf16 v[96:99], v[68:71], v[120:123], 0
	v_mfma_f32_16x16x32_bf16 v[120:123], v[84:87], v[124:127], v[108:111]
	v_mfma_f32_16x16x32_bf16 v[108:111], v[68:71], v[168:171], 0
	v_mfma_f32_16x16x32_bf16 v[172:175], v[48:51], v[124:127], v[172:175]
	v_mfma_f32_16x16x32_bf16 v[164:167], v[60:63], v[124:127], v[164:167]
	v_mfma_f32_16x16x32_bf16 v[96:99], v[72:75], v[124:127], v[96:99]
	v_mfma_f32_16x16x32_bf16 v[124:127], v[72:75], v[180:183], v[108:111]
	v_mfma_f32_16x16x32_bf16 v[108:111], v[76:79], v[168:171], 0
	v_mfma_f32_16x16x32_bf16 v[136:139], v[84:87], v[180:183], v[108:111]
	v_mfma_f32_16x16x32_bf16 v[108:111], v[68:71], v[200:203], 0
	v_mfma_f32_16x16x32_bf16 v[156:159], v[44:47], v[168:171], 0
	v_mfma_f32_16x16x32_bf16 v[152:155], v[56:59], v[168:171], 0
	v_mfma_f32_16x16x32_bf16 v[160:163], v[44:47], v[200:203], 0
	v_mfma_f32_16x16x32_bf16 v[132:135], v[56:59], v[200:203], 0
	v_mfma_f32_16x16x32_bf16 v[116:119], v[72:75], v[204:207], v[108:111]
	v_mfma_f32_16x16x32_bf16 v[108:111], v[76:79], v[200:203], 0
	v_mfma_f32_16x16x32_bf16 v[156:159], v[48:51], v[180:183], v[156:159]
	v_mfma_f32_16x16x32_bf16 v[152:155], v[60:63], v[180:183], v[152:155]
	v_mfma_f32_16x16x32_bf16 v[160:163], v[48:51], v[204:207], v[160:163]
	v_mfma_f32_16x16x32_bf16 v[132:135], v[60:63], v[204:207], v[132:135]
	v_mfma_f32_16x16x32_bf16 v[112:115], v[84:87], v[204:207], v[108:111]
	s_barrier
	s_add_i32 s40, s5, s80
	v_lshl_add_u64 v[216:217], s[12:13], 0, v[186:187]
	s_mov_b32 m0, s40
	ds_read_b128 v[108:111], v223 offset:16384
	ds_read_b128 v[140:143], v223 offset:17408
	ds_read_b128 v[144:147], v223 offset:18432
	ds_read_b128 v[148:151], v223 offset:19456
	ds_read_b128 v[168:171], v223 offset:20480
	ds_read_b128 v[180:183], v223 offset:21504
	ds_read_b128 v[200:203], v223 offset:22528
	ds_read_b128 v[204:207], v223 offset:23552
	global_load_lds_dwordx4 v[216:217], off
	s_add_i32 m0, s40, 0x2000
	s_add_u32 s40, s12, 0x80000
	v_lshl_add_u64 v[218:219], s[12:13], 0, v[190:191]
	s_addc_u32 s41, s13, 0
	s_add_i32 s77, s28, s80
	global_load_lds_dwordx4 v[218:219], off
	v_lshl_add_u64 v[208:209], s[40:41], 0, v[186:187]
	s_mov_b32 m0, s77
	v_lshl_add_u64 v[226:227], s[72:73], 0, v[184:185]
	global_load_lds_dwordx4 v[208:209], off
	v_lshl_add_u64 v[208:209], s[40:41], 0, v[190:191]
	s_add_i32 m0, s77, 0x2000
	v_lshl_add_u64 v[228:229], s[72:73], 0, v[188:189]
	global_load_lds_dwordx4 v[208:209], off
	s_mov_b32 m0, s81
	s_nop 0
	global_load_lds_dwordx4 v[226:227], off
	s_mov_b32 m0, s82
	s_nop 0
	global_load_lds_dwordx4 v[228:229], off
	s_waitcnt vmcnt(8)
	s_waitcnt lgkmcnt(0)
	s_barrier
; #define PG8_STAGE(bufoff, gbase, voff) do { _Pragma("unroll") for (int _i = 0; _i < 2; ++_i) \
;         __builtin_amdgcn_global_load_lds((const unsigned*)((const char*)(gbase) + (voff)[_i]), (PG8_LAS unsigned*)(lds + (bufoff) + ldsw + _i * 8192), 16, 0, 0); } while (0)
; #define PG8_LDA(dst, b, h) do { _Pragma("unroll") for (int m = 0; m < 4; ++m) _Pragma("unroll") for (int k = 0; k < 2; ++k) dst[m][k] = *(const PG8_LAS bf16x8*)(lds + PG8_SA(b, h) + aoff + m * 2048 + k * 1024); } while (0)
; #define PG8_LDB(dst, b, h) do { _Pragma("unroll") for (int n = 0; n < 2; ++n) _Pragma("unroll") for (int k = 0; k < 2; ++k) dst[n][k] = *(const PG8_LAS bf16x8*)(lds + PG8_SB(b, h) + boff + n * 2048 + k * 1024); } while (0)
; #define PG8_MMA(ai, bj, At, Bt) do { _Pragma("unroll") for (int m = 0; m < 4; ++m) _Pragma("unroll") for (int n = 0; n < 2; ++n) _Pragma("unroll") for (int k = 0; k < 2; ++k) \
;         acc[ai][bj][m][n] = __builtin_amdgcn_mfma_f32_16x16x32_bf16(Bt[n][k], At[m][k], acc[ai][bj][m][n], 0, 0, 0); } while (0)
; #define PG8_WAIT_V(n) asm volatile("s_waitcnt vmcnt(" #n ")" ::: "memory")
; #define PG8_WAIT_L(n) asm volatile("s_waitcnt lgkmcnt(" #n ")" ::: "memory")
; #define PG8_BAR __builtin_amdgcn_s_barrier()
; #define PG8_SCHED __builtin_amdgcn_sched_barrier(0)
; template <class Epi, class Sched, bool ALIGN_EPI = false, bool SP2 = false>
; __device__ __forceinline__ void gemm_phase(PG8_LAS unsigned char* lds, const Gemm g, const Sched& S, const Epi& E, const int wave_id_in) {
;     ...
;             PG8_WAIT_V(8); PG8_WAIT_L(0); PG8_BAR; __builtin_amdgcn_s_setprio(1); PG8_MMA(1, 0, At, B0); PG8_MMA(1, 1, At, B1); __builtin_amdgcn_s_setprio(0); PG8_BAR; PG8_SCHED;
;             PG8_LDB(B0, 1, 0); PG8_LDB(B1, 1, 1); PG8_SCHED; PG8_LDA(At, 1, 0); PG8_STAGE(PG8_SA(0, 1), a2 + hstep, voffA);
;             PG8_WAIT_V(8); PG8_WAIT_L(0); PG8_BAR; __builtin_amdgcn_s_setprio(1); PG8_MMA(0, 0, At, B0); PG8_MMA(0, 1, At, B1); __builtin_amdgcn_s_setprio(0); PG8_BAR; PG8_SCHED;
	v_mfma_f32_16x16x32_bf16 v[128:131], v[44:47], v[108:111], 0
	v_mfma_f32_16x16x32_bf16 v[64:67], v[56:59], v[108:111], 0
	v_mfma_f32_16x16x32_bf16 v[100:103], v[44:47], v[144:147], 0
	v_mfma_f32_16x16x32_bf16 v[88:91], v[56:59], v[144:147], 0
	v_mfma_f32_16x16x32_bf16 v[28:31], v[44:47], v[168:171], 0
	v_mfma_f32_16x16x32_bf16 v[24:27], v[56:59], v[168:171], 0
	v_mfma_f32_16x16x32_bf16 v[44:47], v[44:47], v[200:203], 0
	v_mfma_f32_16x16x32_bf16 v[32:35], v[76:79], v[108:111], 0
	v_mfma_f32_16x16x32_bf16 v[20:23], v[68:71], v[144:147], 0
	v_mfma_f32_16x16x32_bf16 v[16:19], v[76:79], v[144:147], 0
	v_mfma_f32_16x16x32_bf16 v[12:15], v[68:71], v[168:171], 0
	v_mfma_f32_16x16x32_bf16 v[8:11], v[76:79], v[168:171], 0
	v_mfma_f32_16x16x32_bf16 v[4:7], v[68:71], v[200:203], 0
	v_mfma_f32_16x16x32_bf16 v[0:3], v[76:79], v[200:203], 0
	v_mfma_f32_16x16x32_bf16 v[128:131], v[48:51], v[140:143], v[128:131]
	v_mfma_f32_16x16x32_bf16 v[64:67], v[60:63], v[140:143], v[64:67]
	v_mfma_f32_16x16x32_bf16 v[100:103], v[48:51], v[148:151], v[100:103]
	v_mfma_f32_16x16x32_bf16 v[88:91], v[60:63], v[148:151], v[88:91]
	v_mfma_f32_16x16x32_bf16 v[28:31], v[48:51], v[180:183], v[28:31]
	v_mfma_f32_16x16x32_bf16 v[24:27], v[60:63], v[180:183], v[24:27]
	v_mfma_f32_16x16x32_bf16 v[44:47], v[48:51], v[204:207], v[44:47]
	v_mfma_f32_16x16x32_bf16 v[48:51], v[56:59], v[200:203], 0
	v_mfma_f32_16x16x32_bf16 v[52:55], v[68:71], v[108:111], 0
	v_mfma_f32_16x16x32_bf16 v[32:35], v[84:87], v[140:143], v[32:35]
	v_mfma_f32_16x16x32_bf16 v[20:23], v[72:75], v[148:151], v[20:23]
	v_mfma_f32_16x16x32_bf16 v[16:19], v[84:87], v[148:151], v[16:19]
	v_mfma_f32_16x16x32_bf16 v[12:15], v[72:75], v[180:183], v[12:15]
	v_mfma_f32_16x16x32_bf16 v[8:11], v[84:87], v[180:183], v[8:11]
	v_mfma_f32_16x16x32_bf16 v[4:7], v[72:75], v[204:207], v[4:7]
	v_mfma_f32_16x16x32_bf16 v[0:3], v[84:87], v[204:207], v[0:3]
	v_mfma_f32_16x16x32_bf16 v[48:51], v[60:63], v[204:207], v[48:51]
	v_mfma_f32_16x16x32_bf16 v[56:59], v[72:75], v[140:143], v[52:55]
	s_barrier
	s_add_i32 s77, 0, 0x18000
	s_add_i32 s76, 0, 0x1c000
	v_add_u32_e32 v72, s77, v220
	v_add_u32_e32 v80, s76, v220
	ds_read_b128 v[52:55], v72
	ds_read_b128 v[60:63], v72 offset:1024
	ds_read_b128 v[68:71], v72 offset:2048
	ds_read_b128 v[72:75], v72 offset:3072
	ds_read_b128 v[76:79], v80
	ds_read_b128 v[84:87], v80 offset:1024
	ds_read_b128 v[168:171], v80 offset:2048
	ds_read_b128 v[180:183], v80 offset:3072
	s_add_u32 s40, s72, 0x80000
	s_addc_u32 s41, s73, 0
	s_mov_b32 m0, s83
	v_lshl_add_u64 v[148:149], s[40:41], 0, v[184:185]
	ds_read_b128 v[80:83], v223 offset:32768
	ds_read_b128 v[108:111], v223 offset:33792
	ds_read_b128 v[140:143], v223 offset:34816
	ds_read_b128 v[144:147], v223 offset:35840
	ds_read_b128 v[176:179], v223 offset:36864
	ds_read_b128 v[200:203], v223 offset:37888
	ds_read_b128 v[204:207], v223 offset:38912
	ds_read_b128 v[208:211], v223 offset:39936
	global_load_lds_dwordx4 v[148:149], off
	v_lshl_add_u64 v[148:149], s[40:41], 0, v[188:189]
	s_mov_b32 m0, s84
	s_nop 0
	global_load_lds_dwordx4 v[148:149], off
	s_waitcnt vmcnt(8)
	s_waitcnt lgkmcnt(0)
	s_barrier
	v_mfma_f32_16x16x32_bf16 v[148:151], v[52:55], v[140:143], v[172:175]
	v_mfma_f32_16x16x32_bf16 v[172:175], v[60:63], v[144:147], v[148:151]
	v_mfma_f32_16x16x32_bf16 v[148:151], v[68:71], v[140:143], v[164:167]
	v_mfma_f32_16x16x32_bf16 v[164:167], v[72:75], v[144:147], v[148:151]
	v_mfma_f32_16x16x32_bf16 v[148:151], v[52:55], v[176:179], v[156:159]
	v_mfma_f32_16x16x32_bf16 v[40:43], v[52:55], v[80:83], v[40:43]
	v_mfma_f32_16x16x32_bf16 v[36:39], v[68:71], v[80:83], v[36:39]
	v_mfma_f32_16x16x32_bf16 v[156:159], v[60:63], v[200:203], v[148:151]
	v_mfma_f32_16x16x32_bf16 v[148:151], v[68:71], v[176:179], v[152:155]
	v_mfma_f32_16x16x32_bf16 v[104:107], v[76:79], v[80:83], v[104:107]
	v_mfma_f32_16x16x32_bf16 v[80:83], v[168:171], v[80:83], v[92:95]
	v_mfma_f32_16x16x32_bf16 v[40:43], v[60:63], v[108:111], v[40:43]
	v_mfma_f32_16x16x32_bf16 v[36:39], v[72:75], v[108:111], v[36:39]
	v_mfma_f32_16x16x32_bf16 v[152:155], v[72:75], v[200:203], v[148:151]
	v_mfma_f32_16x16x32_bf16 v[148:151], v[52:55], v[204:207], v[160:163]
	v_mfma_f32_16x16x32_bf16 v[104:107], v[84:87], v[108:111], v[104:107]
	v_mfma_f32_16x16x32_bf16 v[108:111], v[180:183], v[108:111], v[80:83]
	v_mfma_f32_16x16x32_bf16 v[80:83], v[76:79], v[140:143], v[96:99]
	v_mfma_f32_16x16x32_bf16 v[160:163], v[60:63], v[208:211], v[148:151]
	v_mfma_f32_16x16x32_bf16 v[148:151], v[84:87], v[144:147], v[80:83]
	v_mfma_f32_16x16x32_bf16 v[80:83], v[168:171], v[140:143], v[120:123]
	v_mfma_f32_16x16x32_bf16 v[144:147], v[180:183], v[144:147], v[80:83]
	v_mfma_f32_16x16x32_bf16 v[80:83], v[76:79], v[176:179], v[124:127]
	v_mfma_f32_16x16x32_bf16 v[140:143], v[84:87], v[200:203], v[80:83]
	v_mfma_f32_16x16x32_bf16 v[80:83], v[168:171], v[176:179], v[136:139]
	v_mfma_f32_16x16x32_bf16 v[136:139], v[180:183], v[200:203], v[80:83]
	v_mfma_f32_16x16x32_bf16 v[80:83], v[76:79], v[204:207], v[116:119]
	v_mfma_f32_16x16x32_bf16 v[132:135], v[68:71], v[204:207], v[132:135]
	v_mfma_f32_16x16x32_bf16 v[116:119], v[84:87], v[208:211], v[80:83]
	v_mfma_f32_16x16x32_bf16 v[80:83], v[168:171], v[204:207], v[112:115]
	v_mfma_f32_16x16x32_bf16 v[132:135], v[72:75], v[208:211], v[132:135]
	v_mfma_f32_16x16x32_bf16 v[112:115], v[180:183], v[208:211], v[80:83]
	s_barrier
; #define PG8_STAGE(bufoff, gbase, voff) do { _Pragma("unroll") for (int _i = 0; _i < 2; ++_i) \
;         __builtin_amdgcn_global_load_lds((const unsigned*)((const char*)(gbase) + (voff)[_i]), (PG8_LAS unsigned*)(lds + (bufoff) + ldsw + _i * 8192), 16, 0, 0); } while (0)
; #define PG8_LDA(dst, b, h) do { _Pragma("unroll") for (int m = 0; m < 4; ++m) _Pragma("unroll") for (int k = 0; k < 2; ++k) dst[m][k] = *(const PG8_LAS bf16x8*)(lds + PG8_SA(b, h) + aoff + m * 2048 + k * 1024); } while (0)
; #define PG8_LDB(dst, b, h) do { _Pragma("unroll") for (int n = 0; n < 2; ++n) _Pragma("unroll") for (int k = 0; k < 2; ++k) dst[n][k] = *(const PG8_LAS bf16x8*)(lds + PG8_SB(b, h) + boff + n * 2048 + k * 1024); } while (0)
; #define PG8_MMA(ai, bj, At, Bt) do { _Pragma("unroll") for (int m = 0; m < 4; ++m) _Pragma("unroll") for (int n = 0; n < 2; ++n) _Pragma("unroll") for (int k = 0; k < 2; ++k) \
;         acc[ai][bj][m][n] = __builtin_amdgcn_mfma_f32_16x16x32_bf16(Bt[n][k], At[m][k], acc[ai][bj][m][n], 0, 0, 0); } while (0)
; #define PG8_WAIT_V(n) asm volatile("s_waitcnt vmcnt(" #n ")" ::: "memory")
; #define PG8_WAIT_L(n) asm volatile("s_waitcnt lgkmcnt(" #n ")" ::: "memory")
; #define PG8_BAR __builtin_amdgcn_s_barrier()
; #define PG8_SCHED __builtin_amdgcn_sched_barrier(0)
; template <class Epi, class Sched, bool ALIGN_EPI = false, bool SP2 = false>
; __device__ __forceinline__ void gemm_phase(PG8_LAS unsigned char* lds, const Gemm g, const Sched& S, const Epi& E, const int wave_id_in) {
;     ...
;             PG8_LDB(B0, 0, 0); PG8_LDB(B1, 0, 1); PG8_SCHED; PG8_LDA(At, 0, 0); PG8_STAGE(PG8_SA(1, 1), a1 + hstep, voffA);
;             PG8_WAIT_V(8); PG8_WAIT_L(0); PG8_BAR; __builtin_amdgcn_s_setprio(1); PG8_MMA(0, 0, At, B0); PG8_MMA(0, 1, At, B1); __builtin_amdgcn_s_setprio(0); PG8_BAR; PG8_SCHED;
;             PG8_LDA(At, 0, 1); PG8_STAGE(PG8_SB(0, 0), b2, voffB); PG8_STAGE(PG8_SB(0, 1), b2 + hstep, voffB); PG8_STAGE(PG8_SA(0, 0), a2, voffA);
;     ...
;             PG8_LDA(At, 1, 1); PG8_STAGE(PG8_SB(1, 0), b3, voffB); PG8_STAGE(PG8_SB(1, 1), b3 + hstep, voffB); PG8_STAGE(PG8_SA(1, 0), a3, voffA);
;             PG8_WAIT_V(8); PG8_WAIT_L(0); PG8_BAR; __builtin_amdgcn_s_setprio(1); PG8_MMA(1, 0, At, B0); PG8_MMA(1, 1, At, B1); __builtin_amdgcn_s_setprio(0); PG8_BAR; PG8_SCHED;
	s_add_i32 s40, s77, s80
	s_nop 2
	v_lshl_add_u64 v[80:81], v[216:217], 0, s[34:35]
	s_mov_b32 m0, s40
	ds_read_b128 v[92:95], v223 offset:49152
	ds_read_b128 v[96:99], v223 offset:50176
	ds_read_b128 v[120:123], v223 offset:51200
	ds_read_b128 v[124:127], v223 offset:52224
	ds_read_b128 v[200:203], v223 offset:53248
	ds_read_b128 v[204:207], v223 offset:54272
	ds_read_b128 v[208:211], v223 offset:55296
	ds_read_b128 v[212:215], v223 offset:56320
	global_load_lds_dwordx4 v[80:81], off
	s_add_i32 m0, s40, 0x2000
	s_add_u32 s12, s12, 0x80080
	v_lshl_add_u64 v[80:81], v[218:219], 0, s[34:35]
	s_addc_u32 s13, s13, 0
	s_add_i32 s40, s76, s80
	global_load_lds_dwordx4 v[80:81], off
	v_lshl_add_u64 v[80:81], s[12:13], 0, v[186:187]
	s_mov_b32 m0, s40
	s_nop 0
	global_load_lds_dwordx4 v[80:81], off
	v_lshl_add_u64 v[80:81], s[12:13], 0, v[190:191]
	s_add_i32 m0, s40, 0x2000
	s_nop 0
	global_load_lds_dwordx4 v[80:81], off
	v_lshl_add_u64 v[80:81], v[226:227], 0, s[34:35]
	s_mov_b32 m0, s87
	s_nop 0
	global_load_lds_dwordx4 v[80:81], off
	v_lshl_add_u64 v[80:81], v[228:229], 0, s[34:35]
	s_mov_b32 m0, s88
	s_nop 0
	global_load_lds_dwordx4 v[80:81], off
	s_waitcnt vmcnt(8)
	s_waitcnt lgkmcnt(0)
	s_barrier
	v_mfma_f32_16x16x32_bf16 v[80:83], v[52:55], v[92:95], v[128:131]
	v_mfma_f32_16x16x32_bf16 v[44:47], v[52:55], v[208:211], v[44:47]
	v_mfma_f32_16x16x32_bf16 v[128:131], v[60:63], v[96:99], v[80:83]
	v_mfma_f32_16x16x32_bf16 v[80:83], v[52:55], v[120:123], v[100:103]
	v_mfma_f32_16x16x32_bf16 v[176:179], v[60:63], v[212:215], v[44:47]
	v_mfma_f32_16x16x32_bf16 v[44:47], v[68:71], v[208:211], v[48:51]
	v_mfma_f32_16x16x32_bf16 v[64:67], v[68:71], v[92:95], v[64:67]
	v_mfma_f32_16x16x32_bf16 v[100:103], v[60:63], v[124:127], v[80:83]
	v_mfma_f32_16x16x32_bf16 v[80:83], v[68:71], v[120:123], v[88:91]
	v_mfma_f32_16x16x32_bf16 v[28:31], v[52:55], v[200:203], v[28:31]
	v_mfma_f32_16x16x32_bf16 v[24:27], v[68:71], v[200:203], v[24:27]
	v_mfma_f32_16x16x32_bf16 v[52:55], v[72:75], v[212:215], v[44:47]
	v_mfma_f32_16x16x32_bf16 v[44:47], v[76:79], v[92:95], v[56:59]
	v_mfma_f32_16x16x32_bf16 v[32:35], v[168:171], v[92:95], v[32:35]
	v_mfma_f32_16x16x32_bf16 v[20:23], v[76:79], v[120:123], v[20:23]
	v_mfma_f32_16x16x32_bf16 v[16:19], v[168:171], v[120:123], v[16:19]
	v_mfma_f32_16x16x32_bf16 v[12:15], v[76:79], v[200:203], v[12:15]
	v_mfma_f32_16x16x32_bf16 v[8:11], v[168:171], v[200:203], v[8:11]
	v_mfma_f32_16x16x32_bf16 v[4:7], v[76:79], v[208:211], v[4:7]
	v_mfma_f32_16x16x32_bf16 v[0:3], v[168:171], v[208:211], v[0:3]
	v_mfma_f32_16x16x32_bf16 v[64:67], v[72:75], v[96:99], v[64:67]
	v_mfma_f32_16x16x32_bf16 v[88:91], v[72:75], v[124:127], v[80:83]
	v_mfma_f32_16x16x32_bf16 v[28:31], v[60:63], v[204:207], v[28:31]
	v_mfma_f32_16x16x32_bf16 v[24:27], v[72:75], v[204:207], v[24:27]
	v_mfma_f32_16x16x32_bf16 v[80:83], v[84:87], v[96:99], v[44:47]
	v_mfma_f32_16x16x32_bf16 v[32:35], v[180:183], v[96:99], v[32:35]
	v_mfma_f32_16x16x32_bf16 v[20:23], v[84:87], v[124:127], v[20:23]
	v_mfma_f32_16x16x32_bf16 v[16:19], v[180:183], v[124:127], v[16:19]
	v_mfma_f32_16x16x32_bf16 v[12:15], v[84:87], v[204:207], v[12:15]
	v_mfma_f32_16x16x32_bf16 v[8:11], v[180:183], v[204:207], v[8:11]
	v_mfma_f32_16x16x32_bf16 v[4:7], v[84:87], v[212:215], v[4:7]
	v_mfma_f32_16x16x32_bf16 v[0:3], v[180:183], v[212:215], v[0:3]
	s_barrier
	s_add_i32 vcc_hi, vcc_hi, 2
	s_add_u32 s10, s10, 0x100
	s_addc_u32 s11, s11, 0
	s_add_u32 s75, s75, 0x100
	s_addc_u32 vcc_lo, vcc_lo, 0
	s_cmp_gt_u32 vcc_hi, 29
	s_cbranch_scc0 .LBB0_819
	s_branch .Lpeel_exit_ffnup
.LBB0_819:
	ds_read_b128 v[44:47], v221
	ds_read_b128 v[48:51], v221 offset:1024
	ds_read_b128 v[56:59], v221 offset:2048
	s_waitcnt lgkmcnt(0)
	ds_read_b128 v[60:63], v221 offset:3072
	ds_read_b128 v[68:71], v222
	ds_read_b128 v[72:75], v222 offset:1024
	ds_read_b128 v[76:79], v222 offset:2048
	ds_read_b128 v[84:87], v222 offset:3072
	s_add_u32 s12, s10, 0xfff80080
	s_addc_u32 s13, s11, -1
	s_cmp_eq_u32 vcc_hi, 28
	s_cselect_b32 s73, s9, s13
	s_cselect_b32 s72, s27, s12
	s_cselect_b32 s13, s65, vcc_lo
	s_cselect_b32 s12, s74, s75
	v_lshl_add_u64 v[208:209], s[10:11], 0, v[194:195]
	s_add_i32 m0, s81, 0xc000
	ds_read_b128 v[92:95], v223
	ds_read_b128 v[96:99], v223 offset:1024
	ds_read_b128 v[120:123], v223 offset:2048
	ds_read_b128 v[124:127], v223 offset:3072
	ds_read_b128 v[168:171], v223 offset:4096
	ds_read_b128 v[180:183], v223 offset:5120
	ds_read_b128 v[200:203], v223 offset:6144
	ds_read_b128 v[204:207], v223 offset:7168
	global_load_lds_dwordx4 v[208:209], off
	v_lshl_add_u64 v[208:209], s[10:11], 0, v[196:197]
	s_add_i32 m0, s81, 0xe000
	s_nop 0
	global_load_lds_dwordx4 v[208:209], off
	s_waitcnt vmcnt(8)
	s_waitcnt lgkmcnt(0)
	s_barrier
; #define PG8_STAGE(bufoff, gbase, voff) do { _Pragma("unroll") for (int _i = 0; _i < 2; ++_i) \
;         __builtin_amdgcn_global_load_lds((const unsigned*)((const char*)(gbase) + (voff)[_i]), (PG8_LAS unsigned*)(lds + (bufoff) + ldsw + _i * 8192), 16, 0, 0); } while (0)
; #define PG8_LDA(dst, b, h) do { _Pragma("unroll") for (int m = 0; m < 4; ++m) _Pragma("unroll") for (int k = 0; k < 2; ++k) dst[m][k] = *(const PG8_LAS bf16x8*)(lds + PG8_SA(b, h) + aoff + m * 2048 + k * 1024); } while (0)
; #define PG8_MMA(ai, bj, At, Bt) do { _Pragma("unroll") for (int m = 0; m < 4; ++m) _Pragma("unroll") for (int n = 0; n < 2; ++n) _Pragma("unroll") for (int k = 0; k < 2; ++k) \
;         acc[ai][bj][m][n] = __builtin_amdgcn_mfma_f32_16x16x32_bf16(Bt[n][k], At[m][k], acc[ai][bj][m][n], 0, 0, 0); } while (0)
; #define PG8_WAIT_V(n) asm volatile("s_waitcnt vmcnt(" #n ")" ::: "memory")
; #define PG8_WAIT_L(n) asm volatile("s_waitcnt lgkmcnt(" #n ")" ::: "memory")
; #define PG8_BAR __builtin_amdgcn_s_barrier()
; #define PG8_SCHED __builtin_amdgcn_sched_barrier(0)
; template <class Epi, class Sched, bool ALIGN_EPI = false, bool SP2 = false>
; __device__ __forceinline__ void gemm_phase(PG8_LAS unsigned char* lds, const Gemm g, const Sched& S, const Epi& E, const int wave_id_in) {
;     ...
;             PG8_WAIT_V(8); PG8_WAIT_L(0); PG8_BAR; __builtin_amdgcn_s_setprio(1); PG8_MMA(0, 0, At, B0); PG8_MMA(0, 1, At, B1); __builtin_amdgcn_s_setprio(0); PG8_BAR; PG8_SCHED;
;             PG8_LDA(At, 0, 1); PG8_STAGE(PG8_SB(0, 0), b2, voffB); PG8_STAGE(PG8_SB(0, 1), b2 + hstep, voffB); PG8_STAGE(PG8_SA(0, 0), a2, voffA);
;             PG8_WAIT_V(8); PG8_WAIT_L(0); PG8_BAR; __builtin_amdgcn_s_setprio(1); PG8_MMA(1, 0, At, B0); PG8_MMA(1, 1, At, B1); __builtin_amdgcn_s_setprio(0); PG8_BAR; PG8_SCHED;
	v_mfma_f32_16x16x32_bf16 v[40:43], v[44:47], v[92:95], v[40:43]
	v_mfma_f32_16x16x32_bf16 v[36:39], v[56:59], v[92:95], v[36:39]
	v_mfma_f32_16x16x32_bf16 v[104:107], v[68:71], v[92:95], v[104:107]
	v_mfma_f32_16x16x32_bf16 v[92:95], v[76:79], v[92:95], v[108:111]
	v_mfma_f32_16x16x32_bf16 v[108:111], v[76:79], v[120:123], v[144:147]
	v_mfma_f32_16x16x32_bf16 v[40:43], v[48:51], v[96:99], v[40:43]
	v_mfma_f32_16x16x32_bf16 v[36:39], v[60:63], v[96:99], v[36:39]
	v_mfma_f32_16x16x32_bf16 v[172:175], v[44:47], v[120:123], v[172:175]
	v_mfma_f32_16x16x32_bf16 v[164:167], v[56:59], v[120:123], v[164:167]
	v_mfma_f32_16x16x32_bf16 v[104:107], v[72:75], v[96:99], v[104:107]
	v_mfma_f32_16x16x32_bf16 v[92:95], v[84:87], v[96:99], v[92:95]
	v_mfma_f32_16x16x32_bf16 v[96:99], v[68:71], v[120:123], v[148:151]
	v_mfma_f32_16x16x32_bf16 v[120:123], v[84:87], v[124:127], v[108:111]
	v_mfma_f32_16x16x32_bf16 v[108:111], v[68:71], v[168:171], v[140:143]
	v_mfma_f32_16x16x32_bf16 v[172:175], v[48:51], v[124:127], v[172:175]
	v_mfma_f32_16x16x32_bf16 v[164:167], v[60:63], v[124:127], v[164:167]
	v_mfma_f32_16x16x32_bf16 v[96:99], v[72:75], v[124:127], v[96:99]
	v_mfma_f32_16x16x32_bf16 v[124:127], v[72:75], v[180:183], v[108:111]
	v_mfma_f32_16x16x32_bf16 v[108:111], v[76:79], v[168:171], v[136:139]
	v_mfma_f32_16x16x32_bf16 v[136:139], v[84:87], v[180:183], v[108:111]
	v_mfma_f32_16x16x32_bf16 v[108:111], v[68:71], v[200:203], v[116:119]
	v_mfma_f32_16x16x32_bf16 v[156:159], v[44:47], v[168:171], v[156:159]
	v_mfma_f32_16x16x32_bf16 v[152:155], v[56:59], v[168:171], v[152:155]
	v_mfma_f32_16x16x32_bf16 v[160:163], v[44:47], v[200:203], v[160:163]
	v_mfma_f32_16x16x32_bf16 v[132:135], v[56:59], v[200:203], v[132:135]
	v_mfma_f32_16x16x32_bf16 v[116:119], v[72:75], v[204:207], v[108:111]
	v_mfma_f32_16x16x32_bf16 v[108:111], v[76:79], v[200:203], v[112:115]
	v_mfma_f32_16x16x32_bf16 v[156:159], v[48:51], v[180:183], v[156:159]
	v_mfma_f32_16x16x32_bf16 v[152:155], v[60:63], v[180:183], v[152:155]
	v_mfma_f32_16x16x32_bf16 v[160:163], v[48:51], v[204:207], v[160:163]
	v_mfma_f32_16x16x32_bf16 v[132:135], v[60:63], v[204:207], v[132:135]
	v_mfma_f32_16x16x32_bf16 v[112:115], v[84:87], v[204:207], v[108:111]
	s_barrier
	s_add_i32 s40, s5, s80
	v_lshl_add_u64 v[216:217], s[12:13], 0, v[186:187]
	s_mov_b32 m0, s40
	ds_read_b128 v[108:111], v223 offset:16384
	ds_read_b128 v[140:143], v223 offset:17408
	ds_read_b128 v[144:147], v223 offset:18432
	ds_read_b128 v[148:151], v223 offset:19456
	ds_read_b128 v[168:171], v223 offset:20480
	ds_read_b128 v[180:183], v223 offset:21504
	ds_read_b128 v[200:203], v223 offset:22528
	ds_read_b128 v[204:207], v223 offset:23552
	global_load_lds_dwordx4 v[216:217], off
	s_add_i32 m0, s40, 0x2000
	s_add_u32 s40, s12, 0x80000
	v_lshl_add_u64 v[218:219], s[12:13], 0, v[190:191]
	s_addc_u32 s41, s13, 0
	s_add_i32 s77, s28, s80
	global_load_lds_dwordx4 v[218:219], off
	v_lshl_add_u64 v[208:209], s[40:41], 0, v[186:187]
	s_mov_b32 m0, s77
	v_lshl_add_u64 v[226:227], s[72:73], 0, v[184:185]
	global_load_lds_dwordx4 v[208:209], off
	v_lshl_add_u64 v[208:209], s[40:41], 0, v[190:191]
	s_add_i32 m0, s77, 0x2000
	v_lshl_add_u64 v[228:229], s[72:73], 0, v[188:189]
	global_load_lds_dwordx4 v[208:209], off
	s_mov_b32 m0, s81
	s_nop 0
	global_load_lds_dwordx4 v[226:227], off
	s_mov_b32 m0, s82
	s_nop 0
	global_load_lds_dwordx4 v[228:229], off
	s_waitcnt vmcnt(8)
	s_waitcnt lgkmcnt(0)
	s_barrier
	v_mfma_f32_16x16x32_bf16 v[128:131], v[44:47], v[108:111], v[128:131]
	v_mfma_f32_16x16x32_bf16 v[64:67], v[56:59], v[108:111], v[64:67]
	v_mfma_f32_16x16x32_bf16 v[100:103], v[44:47], v[144:147], v[100:103]
	v_mfma_f32_16x16x32_bf16 v[88:91], v[56:59], v[144:147], v[88:91]
	v_mfma_f32_16x16x32_bf16 v[28:31], v[44:47], v[168:171], v[28:31]
	v_mfma_f32_16x16x32_bf16 v[24:27], v[56:59], v[168:171], v[24:27]
	v_mfma_f32_16x16x32_bf16 v[44:47], v[44:47], v[200:203], v[176:179]
	v_mfma_f32_16x16x32_bf16 v[32:35], v[76:79], v[108:111], v[32:35]
	v_mfma_f32_16x16x32_bf16 v[20:23], v[68:71], v[144:147], v[20:23]
	v_mfma_f32_16x16x32_bf16 v[16:19], v[76:79], v[144:147], v[16:19]
	v_mfma_f32_16x16x32_bf16 v[12:15], v[68:71], v[168:171], v[12:15]
	v_mfma_f32_16x16x32_bf16 v[8:11], v[76:79], v[168:171], v[8:11]
	v_mfma_f32_16x16x32_bf16 v[4:7], v[68:71], v[200:203], v[4:7]
	v_mfma_f32_16x16x32_bf16 v[0:3], v[76:79], v[200:203], v[0:3]
	v_mfma_f32_16x16x32_bf16 v[128:131], v[48:51], v[140:143], v[128:131]
	v_mfma_f32_16x16x32_bf16 v[64:67], v[60:63], v[140:143], v[64:67]
	v_mfma_f32_16x16x32_bf16 v[100:103], v[48:51], v[148:151], v[100:103]
	v_mfma_f32_16x16x32_bf16 v[88:91], v[60:63], v[148:151], v[88:91]
	v_mfma_f32_16x16x32_bf16 v[28:31], v[48:51], v[180:183], v[28:31]
	v_mfma_f32_16x16x32_bf16 v[24:27], v[60:63], v[180:183], v[24:27]
	v_mfma_f32_16x16x32_bf16 v[44:47], v[48:51], v[204:207], v[44:47]
	v_mfma_f32_16x16x32_bf16 v[48:51], v[56:59], v[200:203], v[52:55]
	v_mfma_f32_16x16x32_bf16 v[52:55], v[68:71], v[108:111], v[80:83]
	v_mfma_f32_16x16x32_bf16 v[32:35], v[84:87], v[140:143], v[32:35]
	v_mfma_f32_16x16x32_bf16 v[20:23], v[72:75], v[148:151], v[20:23]
	v_mfma_f32_16x16x32_bf16 v[16:19], v[84:87], v[148:151], v[16:19]
	v_mfma_f32_16x16x32_bf16 v[12:15], v[72:75], v[180:183], v[12:15]
	v_mfma_f32_16x16x32_bf16 v[8:11], v[84:87], v[180:183], v[8:11]
	v_mfma_f32_16x16x32_bf16 v[4:7], v[72:75], v[204:207], v[4:7]
	v_mfma_f32_16x16x32_bf16 v[0:3], v[84:87], v[204:207], v[0:3]
	v_mfma_f32_16x16x32_bf16 v[48:51], v[60:63], v[204:207], v[48:51]
	v_mfma_f32_16x16x32_bf16 v[56:59], v[72:75], v[140:143], v[52:55]
	s_barrier
; #define PG8_STAGE(bufoff, gbase, voff) do { _Pragma("unroll") for (int _i = 0; _i < 2; ++_i) \
;         __builtin_amdgcn_global_load_lds((const unsigned*)((const char*)(gbase) + (voff)[_i]), (PG8_LAS unsigned*)(lds + (bufoff) + ldsw + _i * 8192), 16, 0, 0); } while (0)
; #define PG8_LDA(dst, b, h) do { _Pragma("unroll") for (int m = 0; m < 4; ++m) _Pragma("unroll") for (int k = 0; k < 2; ++k) dst[m][k] = *(const PG8_LAS bf16x8*)(lds + PG8_SA(b, h) + aoff + m * 2048 + k * 1024); } while (0)
; #define PG8_LDB(dst, b, h) do { _Pragma("unroll") for (int n = 0; n < 2; ++n) _Pragma("unroll") for (int k = 0; k < 2; ++k) dst[n][k] = *(const PG8_LAS bf16x8*)(lds + PG8_SB(b, h) + boff + n * 2048 + k * 1024); } while (0)
; #define PG8_MMA(ai, bj, At, Bt) do { _Pragma("unroll") for (int m = 0; m < 4; ++m) _Pragma("unroll") for (int n = 0; n < 2; ++n) _Pragma("unroll") for (int k = 0; k < 2; ++k) \
;         acc[ai][bj][m][n] = __builtin_amdgcn_mfma_f32_16x16x32_bf16(Bt[n][k], At[m][k], acc[ai][bj][m][n], 0, 0, 0); } while (0)
; #define PG8_WAIT_V(n) asm volatile("s_waitcnt vmcnt(" #n ")" ::: "memory")
; #define PG8_WAIT_L(n) asm volatile("s_waitcnt lgkmcnt(" #n ")" ::: "memory")
; #define PG8_BAR __builtin_amdgcn_s_barrier()
; #define PG8_SCHED __builtin_amdgcn_sched_barrier(0)
; template <class Epi, class Sched, bool ALIGN_EPI = false, bool SP2 = false>
; __device__ __forceinline__ void gemm_phase(PG8_LAS unsigned char* lds, const Gemm g, const Sched& S, const Epi& E, const int wave_id_in) {
;     ...
;             PG8_LDB(B0, 1, 0); PG8_LDB(B1, 1, 1); PG8_SCHED; PG8_LDA(At, 1, 0); PG8_STAGE(PG8_SA(0, 1), a2 + hstep, voffA);
;             PG8_WAIT_V(8); PG8_WAIT_L(0); PG8_BAR; __builtin_amdgcn_s_setprio(1); PG8_MMA(0, 0, At, B0); PG8_MMA(0, 1, At, B1); __builtin_amdgcn_s_setprio(0); PG8_BAR; PG8_SCHED;
;             PG8_LDA(At, 1, 1); PG8_STAGE(PG8_SB(1, 0), b3, voffB); PG8_STAGE(PG8_SB(1, 1), b3 + hstep, voffB); PG8_STAGE(PG8_SA(1, 0), a3, voffA);
;             PG8_WAIT_V(8); PG8_WAIT_L(0); PG8_BAR; __builtin_amdgcn_s_setprio(1); PG8_MMA(1, 0, At, B0); PG8_MMA(1, 1, At, B1); __builtin_amdgcn_s_setprio(0); PG8_BAR; PG8_SCHED;
	s_add_i32 s77, 0, 0x18000
	s_add_i32 s76, 0, 0x1c000
	v_add_u32_e32 v72, s77, v220
	v_add_u32_e32 v80, s76, v220
	ds_read_b128 v[52:55], v72
	ds_read_b128 v[60:63], v72 offset:1024
	ds_read_b128 v[68:71], v72 offset:2048
	ds_read_b128 v[72:75], v72 offset:3072
	ds_read_b128 v[76:79], v80
	ds_read_b128 v[84:87], v80 offset:1024
	ds_read_b128 v[168:171], v80 offset:2048
	ds_read_b128 v[180:183], v80 offset:3072
	s_add_u32 s40, s72, 0x80000
	s_addc_u32 s41, s73, 0
	s_mov_b32 m0, s83
	v_lshl_add_u64 v[148:149], s[40:41], 0, v[184:185]
	ds_read_b128 v[80:83], v223 offset:32768
	ds_read_b128 v[108:111], v223 offset:33792
	ds_read_b128 v[140:143], v223 offset:34816
	ds_read_b128 v[144:147], v223 offset:35840
	ds_read_b128 v[176:179], v223 offset:36864
	ds_read_b128 v[200:203], v223 offset:37888
	ds_read_b128 v[204:207], v223 offset:38912
	ds_read_b128 v[208:211], v223 offset:39936
	global_load_lds_dwordx4 v[148:149], off
	v_lshl_add_u64 v[148:149], s[40:41], 0, v[188:189]
	s_mov_b32 m0, s84
	s_nop 0
	global_load_lds_dwordx4 v[148:149], off
	s_waitcnt vmcnt(8)
	s_waitcnt lgkmcnt(0)
	s_barrier
	v_mfma_f32_16x16x32_bf16 v[148:151], v[52:55], v[140:143], v[172:175]
	v_mfma_f32_16x16x32_bf16 v[172:175], v[60:63], v[144:147], v[148:151]
	v_mfma_f32_16x16x32_bf16 v[148:151], v[68:71], v[140:143], v[164:167]
	v_mfma_f32_16x16x32_bf16 v[164:167], v[72:75], v[144:147], v[148:151]
	v_mfma_f32_16x16x32_bf16 v[148:151], v[52:55], v[176:179], v[156:159]
	v_mfma_f32_16x16x32_bf16 v[40:43], v[52:55], v[80:83], v[40:43]
	v_mfma_f32_16x16x32_bf16 v[36:39], v[68:71], v[80:83], v[36:39]
	v_mfma_f32_16x16x32_bf16 v[156:159], v[60:63], v[200:203], v[148:151]
	v_mfma_f32_16x16x32_bf16 v[148:151], v[68:71], v[176:179], v[152:155]
	v_mfma_f32_16x16x32_bf16 v[104:107], v[76:79], v[80:83], v[104:107]
	v_mfma_f32_16x16x32_bf16 v[80:83], v[168:171], v[80:83], v[92:95]
	v_mfma_f32_16x16x32_bf16 v[40:43], v[60:63], v[108:111], v[40:43]
	v_mfma_f32_16x16x32_bf16 v[36:39], v[72:75], v[108:111], v[36:39]
	v_mfma_f32_16x16x32_bf16 v[152:155], v[72:75], v[200:203], v[148:151]
	v_mfma_f32_16x16x32_bf16 v[148:151], v[52:55], v[204:207], v[160:163]
	v_mfma_f32_16x16x32_bf16 v[104:107], v[84:87], v[108:111], v[104:107]
	v_mfma_f32_16x16x32_bf16 v[108:111], v[180:183], v[108:111], v[80:83]
	v_mfma_f32_16x16x32_bf16 v[80:83], v[76:79], v[140:143], v[96:99]
	v_mfma_f32_16x16x32_bf16 v[160:163], v[60:63], v[208:211], v[148:151]
	v_mfma_f32_16x16x32_bf16 v[148:151], v[84:87], v[144:147], v[80:83]
	v_mfma_f32_16x16x32_bf16 v[80:83], v[168:171], v[140:143], v[120:123]
	v_mfma_f32_16x16x32_bf16 v[144:147], v[180:183], v[144:147], v[80:83]
	v_mfma_f32_16x16x32_bf16 v[80:83], v[76:79], v[176:179], v[124:127]
	v_mfma_f32_16x16x32_bf16 v[140:143], v[84:87], v[200:203], v[80:83]
	v_mfma_f32_16x16x32_bf16 v[80:83], v[168:171], v[176:179], v[136:139]
	v_mfma_f32_16x16x32_bf16 v[136:139], v[180:183], v[200:203], v[80:83]
	v_mfma_f32_16x16x32_bf16 v[80:83], v[76:79], v[204:207], v[116:119]
	v_mfma_f32_16x16x32_bf16 v[132:135], v[68:71], v[204:207], v[132:135]
	v_mfma_f32_16x16x32_bf16 v[116:119], v[84:87], v[208:211], v[80:83]
	v_mfma_f32_16x16x32_bf16 v[80:83], v[168:171], v[204:207], v[112:115]
	v_mfma_f32_16x16x32_bf16 v[132:135], v[72:75], v[208:211], v[132:135]
	v_mfma_f32_16x16x32_bf16 v[112:115], v[180:183], v[208:211], v[80:83]
	s_barrier
	s_add_i32 s40, s77, s80
	s_nop 2
	v_lshl_add_u64 v[80:81], v[216:217], 0, s[34:35]
	s_mov_b32 m0, s40
	ds_read_b128 v[92:95], v223 offset:49152
	ds_read_b128 v[96:99], v223 offset:50176
	ds_read_b128 v[120:123], v223 offset:51200
	ds_read_b128 v[124:127], v223 offset:52224
	ds_read_b128 v[200:203], v223 offset:53248
	ds_read_b128 v[204:207], v223 offset:54272
	ds_read_b128 v[208:211], v223 offset:55296
	ds_read_b128 v[212:215], v223 offset:56320
	global_load_lds_dwordx4 v[80:81], off
	s_add_i32 m0, s40, 0x2000
	s_add_u32 s12, s12, 0x80080
	v_lshl_add_u64 v[80:81], v[218:219], 0, s[34:35]
	s_addc_u32 s13, s13, 0
	s_add_i32 s40, s76, s80
	global_load_lds_dwordx4 v[80:81], off
	v_lshl_add_u64 v[80:81], s[12:13], 0, v[186:187]
	s_mov_b32 m0, s40
	s_nop 0
	global_load_lds_dwordx4 v[80:81], off
	v_lshl_add_u64 v[80:81], s[12:13], 0, v[190:191]
	s_add_i32 m0, s40, 0x2000
	s_nop 0
	global_load_lds_dwordx4 v[80:81], off
	v_lshl_add_u64 v[80:81], v[226:227], 0, s[34:35]
	s_mov_b32 m0, s87
	s_nop 0
	global_load_lds_dwordx4 v[80:81], off
	v_lshl_add_u64 v[80:81], v[228:229], 0, s[34:35]
	s_mov_b32 m0, s88
	s_nop 0
	global_load_lds_dwordx4 v[80:81], off
	s_waitcnt vmcnt(8)
	s_waitcnt lgkmcnt(0)
	s_barrier
	v_mfma_f32_16x16x32_bf16 v[80:83], v[52:55], v[92:95], v[128:131]
	v_mfma_f32_16x16x32_bf16 v[44:47], v[52:55], v[208:211], v[44:47]
	v_mfma_f32_16x16x32_bf16 v[128:131], v[60:63], v[96:99], v[80:83]
	v_mfma_f32_16x16x32_bf16 v[80:83], v[52:55], v[120:123], v[100:103]
	v_mfma_f32_16x16x32_bf16 v[176:179], v[60:63], v[212:215], v[44:47]
	v_mfma_f32_16x16x32_bf16 v[44:47], v[68:71], v[208:211], v[48:51]
	v_mfma_f32_16x16x32_bf16 v[64:67], v[68:71], v[92:95], v[64:67]
	v_mfma_f32_16x16x32_bf16 v[100:103], v[60:63], v[124:127], v[80:83]
	v_mfma_f32_16x16x32_bf16 v[80:83], v[68:71], v[120:123], v[88:91]
	v_mfma_f32_16x16x32_bf16 v[28:31], v[52:55], v[200:203], v[28:31]
	v_mfma_f32_16x16x32_bf16 v[24:27], v[68:71], v[200:203], v[24:27]
	v_mfma_f32_16x16x32_bf16 v[52:55], v[72:75], v[212:215], v[44:47]
	v_mfma_f32_16x16x32_bf16 v[44:47], v[76:79], v[92:95], v[56:59]
	v_mfma_f32_16x16x32_bf16 v[32:35], v[168:171], v[92:95], v[32:35]
	v_mfma_f32_16x16x32_bf16 v[20:23], v[76:79], v[120:123], v[20:23]
	v_mfma_f32_16x16x32_bf16 v[16:19], v[168:171], v[120:123], v[16:19]
	v_mfma_f32_16x16x32_bf16 v[12:15], v[76:79], v[200:203], v[12:15]
	v_mfma_f32_16x16x32_bf16 v[8:11], v[168:171], v[200:203], v[8:11]
	v_mfma_f32_16x16x32_bf16 v[4:7], v[76:79], v[208:211], v[4:7]
	v_mfma_f32_16x16x32_bf16 v[0:3], v[168:171], v[208:211], v[0:3]
	v_mfma_f32_16x16x32_bf16 v[64:67], v[72:75], v[96:99], v[64:67]
	v_mfma_f32_16x16x32_bf16 v[88:91], v[72:75], v[124:127], v[80:83]
	v_mfma_f32_16x16x32_bf16 v[28:31], v[60:63], v[204:207], v[28:31]
	v_mfma_f32_16x16x32_bf16 v[24:27], v[72:75], v[204:207], v[24:27]
	v_mfma_f32_16x16x32_bf16 v[80:83], v[84:87], v[96:99], v[44:47]
	v_mfma_f32_16x16x32_bf16 v[32:35], v[180:183], v[96:99], v[32:35]
	v_mfma_f32_16x16x32_bf16 v[20:23], v[84:87], v[124:127], v[20:23]
	v_mfma_f32_16x16x32_bf16 v[16:19], v[180:183], v[124:127], v[16:19]
	v_mfma_f32_16x16x32_bf16 v[12:15], v[84:87], v[204:207], v[12:15]
	v_mfma_f32_16x16x32_bf16 v[8:11], v[180:183], v[204:207], v[8:11]
	v_mfma_f32_16x16x32_bf16 v[4:7], v[84:87], v[212:215], v[4:7]
	v_mfma_f32_16x16x32_bf16 v[0:3], v[180:183], v[212:215], v[0:3]
	s_barrier
	s_add_i32 vcc_hi, vcc_hi, 2
	s_add_u32 s10, s10, 0x100
	s_addc_u32 s11, s11, 0
	s_add_u32 s75, s75, 0x100
	s_addc_u32 vcc_lo, vcc_lo, 0
	s_cmp_gt_u32 vcc_hi, 29
	s_cbranch_scc0 .LBB0_819

; #define PG8_STAGE(bufoff, gbase, voff) do { _Pragma("unroll") for (int _i = 0; _i < 2; ++_i) \
;         __builtin_amdgcn_global_load_lds((const unsigned*)((const char*)(gbase) + (voff)[_i]), (PG8_LAS unsigned*)(lds + (bufoff) + ldsw + _i * 8192), 16, 0, 0); } while (0)
; #define PG8_LDA(dst, b, h) do { _Pragma("unroll") for (int m = 0; m < 4; ++m) _Pragma("unroll") for (int k = 0; k < 2; ++k) dst[m][k] = *(const PG8_LAS bf16x8*)(lds + PG8_SA(b, h) + aoff + m * 2048 + k * 1024); } while (0)
; #define PG8_LDB(dst, b, h) do { _Pragma("unroll") for (int n = 0; n < 2; ++n) _Pragma("unroll") for (int k = 0; k < 2; ++k) dst[n][k] = *(const PG8_LAS bf16x8*)(lds + PG8_SB(b, h) + boff + n * 2048 + k * 1024); } while (0)
; #define PG8_MMA(ai, bj, At, Bt) do { _Pragma("unroll") for (int m = 0; m < 4; ++m) _Pragma("unroll") for (int n = 0; n < 2; ++n) _Pragma("unroll") for (int k = 0; k < 2; ++k) \
;         acc[ai][bj][m][n] = __builtin_amdgcn_mfma_f32_16x16x32_bf16(Bt[n][k], At[m][k], acc[ai][bj][m][n], 0, 0, 0); } while (0)
; #define PG8_WAIT_V(n) asm volatile("s_waitcnt vmcnt(" #n ")" ::: "memory")
; #define PG8_WAIT_L(n) asm volatile("s_waitcnt lgkmcnt(" #n ")" ::: "memory")
; #define PG8_BAR __builtin_amdgcn_s_barrier()
; #define PG8_SCHED __builtin_amdgcn_sched_barrier(0)
; template <class Epi>
; __device__ __forceinline__ void gemm_half_phase(PG8_LAS unsigned char* lds, const Gemm g, const Unit cur, const Epi& E, const int wave_id_in) {
;     ...
;         PG8_LDB(B0, 0, 0); PG8_LDB(B1, 0, 1); PG8_SCHED; PG8_LDA(At, 0, 0);
;         PG8_WAIT_V(6); PG8_WAIT_L(0); PG8_BAR; __builtin_amdgcn_s_setprio(1); PG8_MMA(0, 0, At, B0); __builtin_amdgcn_s_setprio(0); PG8_BAR; PG8_SCHED;
;         PG8_STAGE(PG8_SB(0, 0), b2, voffB); PG8_STAGE(PG8_SB(0, 1), b2 + hstep, voffB); PG8_STAGE(PG8_SA(0, 0), a2, voffA);
;         PG8_WAIT_V(6); PG8_BAR; __builtin_amdgcn_s_setprio(1); PG8_MMA(0, 1, At, B1); __builtin_amdgcn_s_setprio(0); PG8_BAR; PG8_SCHED;
.LBB0_888:
	ds_read_b128 v[44:47], v32
	ds_read_b128 v[52:55], v32 offset:1024
	ds_read_b128 v[56:59], v32 offset:2048
	ds_read_b128 v[64:67], v32 offset:3072
	ds_read_b128 v[88:91], v33
	ds_read_b128 v[92:95], v33 offset:1024
	ds_read_b128 v[104:107], v33 offset:2048
	ds_read_b128 v[108:111], v33 offset:3072
	s_cmp_eq_u32 s38, 28
	s_cselect_b32 s41, s7, s37
	s_cselect_b32 s40, s6, s36
	s_cselect_b32 s27, s9, s29
	s_cselect_b32 s26, s8, s28
	ds_read_b128 v[112:115], v34
	ds_read_b128 v[116:119], v34 offset:1024
	ds_read_b128 v[120:123], v34 offset:2048
	ds_read_b128 v[124:127], v34 offset:3072
	ds_read_b128 v[128:131], v34 offset:4096
	ds_read_b128 v[132:135], v34 offset:5120
	ds_read_b128 v[136:139], v34 offset:6144
	ds_read_b128 v[140:143], v34 offset:7168
	s_waitcnt vmcnt(6)
	s_waitcnt lgkmcnt(0)
	s_barrier
	v_mfma_f32_16x16x32_bf16 v[20:23], v[44:47], v[112:115], v[20:23]
	v_mfma_f32_16x16x32_bf16 v[16:19], v[56:59], v[112:115], v[16:19]
	v_mfma_f32_16x16x32_bf16 v[100:103], v[44:47], v[120:123], v[100:103]
	v_mfma_f32_16x16x32_bf16 v[96:99], v[56:59], v[120:123], v[96:99]
	v_mfma_f32_16x16x32_bf16 v[84:87], v[44:47], v[128:131], v[84:87]
	v_mfma_f32_16x16x32_bf16 v[80:83], v[56:59], v[128:131], v[80:83]
	v_mfma_f32_16x16x32_bf16 v[12:15], v[44:47], v[136:139], v[12:15]
	v_mfma_f32_16x16x32_bf16 v[8:11], v[56:59], v[136:139], v[8:11]
	v_mfma_f32_16x16x32_bf16 v[20:23], v[52:55], v[116:119], v[20:23]
	v_mfma_f32_16x16x32_bf16 v[16:19], v[64:67], v[116:119], v[16:19]
	v_mfma_f32_16x16x32_bf16 v[100:103], v[52:55], v[124:127], v[100:103]
	v_mfma_f32_16x16x32_bf16 v[96:99], v[64:67], v[124:127], v[96:99]
	v_mfma_f32_16x16x32_bf16 v[84:87], v[52:55], v[132:135], v[84:87]
	v_mfma_f32_16x16x32_bf16 v[80:83], v[64:67], v[132:135], v[80:83]
	v_mfma_f32_16x16x32_bf16 v[12:15], v[52:55], v[140:143], v[12:15]
	v_mfma_f32_16x16x32_bf16 v[8:11], v[64:67], v[140:143], v[8:11]
	s_barrier
	s_mov_b32 m0, s39
	v_lshl_add_u64 v[144:145], s[26:27], 0, v[26:27]
	s_add_u32 s50, s26, 0x80000
	global_load_lds_dwordx4 v[144:145], off
	v_lshl_add_u64 v[146:147], s[26:27], 0, v[30:31]
	s_mov_b32 m0, s42
	s_addc_u32 s51, s27, 0
	global_load_lds_dwordx4 v[146:147], off
	v_lshl_add_u64 v[38:39], s[50:51], 0, v[26:27]
	s_mov_b32 m0, s43
	v_lshl_add_u64 v[148:149], s[40:41], 0, v[24:25]
	global_load_lds_dwordx4 v[38:39], off
	v_lshl_add_u64 v[38:39], s[50:51], 0, v[30:31]
	s_mov_b32 m0, s44
	v_lshl_add_u64 v[150:151], s[40:41], 0, v[28:29]
	global_load_lds_dwordx4 v[38:39], off
	s_mov_b32 m0, s23
	s_nop 0
	global_load_lds_dwordx4 v[148:149], off
	s_mov_b32 m0, s31
	s_nop 0
	global_load_lds_dwordx4 v[150:151], off
	s_waitcnt vmcnt(6)
	s_barrier
	v_mfma_f32_16x16x32_bf16 v[38:41], v[88:91], v[112:115], v[40:43]
	v_mfma_f32_16x16x32_bf16 v[42:45], v[104:107], v[112:115], v[48:51]
	v_mfma_f32_16x16x32_bf16 v[48:51], v[88:91], v[120:123], v[76:79]
	v_mfma_f32_16x16x32_bf16 v[52:55], v[92:95], v[124:127], v[48:51]
	v_mfma_f32_16x16x32_bf16 v[48:51], v[104:107], v[120:123], v[72:75]
	v_mfma_f32_16x16x32_bf16 v[56:59], v[108:111], v[124:127], v[48:51]
	v_mfma_f32_16x16x32_bf16 v[48:51], v[88:91], v[128:131], v[68:71]
	v_mfma_f32_16x16x32_bf16 v[64:67], v[92:95], v[132:135], v[48:51]
	v_mfma_f32_16x16x32_bf16 v[48:51], v[104:107], v[128:131], v[60:63]
	v_mfma_f32_16x16x32_bf16 v[4:7], v[88:91], v[136:139], v[4:7]
	v_mfma_f32_16x16x32_bf16 v[0:3], v[104:107], v[136:139], v[0:3]
	v_mfma_f32_16x16x32_bf16 v[38:41], v[92:95], v[116:119], v[38:41]
	v_mfma_f32_16x16x32_bf16 v[60:63], v[108:111], v[132:135], v[48:51]
	v_mfma_f32_16x16x32_bf16 v[4:7], v[92:95], v[140:143], v[4:7]
	v_mfma_f32_16x16x32_bf16 v[0:3], v[108:111], v[140:143], v[0:3]
	v_mfma_f32_16x16x32_bf16 v[44:47], v[108:111], v[116:119], v[42:45]
	s_barrier
; #define PG8_STAGE(bufoff, gbase, voff) do { _Pragma("unroll") for (int _i = 0; _i < 2; ++_i) \
;         __builtin_amdgcn_global_load_lds((const unsigned*)((const char*)(gbase) + (voff)[_i]), (PG8_LAS unsigned*)(lds + (bufoff) + ldsw + _i * 8192), 16, 0, 0); } while (0)
; #define PG8_LDA(dst, b, h) do { _Pragma("unroll") for (int m = 0; m < 4; ++m) _Pragma("unroll") for (int k = 0; k < 2; ++k) dst[m][k] = *(const PG8_LAS bf16x8*)(lds + PG8_SA(b, h) + aoff + m * 2048 + k * 1024); } while (0)
; #define PG8_LDB(dst, b, h) do { _Pragma("unroll") for (int n = 0; n < 2; ++n) _Pragma("unroll") for (int k = 0; k < 2; ++k) dst[n][k] = *(const PG8_LAS bf16x8*)(lds + PG8_SB(b, h) + boff + n * 2048 + k * 1024); } while (0)
; #define PG8_MMA(ai, bj, At, Bt) do { _Pragma("unroll") for (int m = 0; m < 4; ++m) _Pragma("unroll") for (int n = 0; n < 2; ++n) _Pragma("unroll") for (int k = 0; k < 2; ++k) \
;         acc[ai][bj][m][n] = __builtin_amdgcn_mfma_f32_16x16x32_bf16(Bt[n][k], At[m][k], acc[ai][bj][m][n], 0, 0, 0); } while (0)
; #define PG8_WAIT_V(n) asm volatile("s_waitcnt vmcnt(" #n ")" ::: "memory")
; #define PG8_WAIT_L(n) asm volatile("s_waitcnt lgkmcnt(" #n ")" ::: "memory")
; #define PG8_BAR __builtin_amdgcn_s_barrier()
; #define PG8_SCHED __builtin_amdgcn_sched_barrier(0)
; template <class Epi>
; __device__ __forceinline__ void gemm_half_phase(PG8_LAS unsigned char* lds, const Gemm g, const Unit cur, const Epi& E, const int wave_id_in) {
;     ...
;         PG8_LDB(B0, 1, 0); PG8_LDB(B1, 1, 1); PG8_SCHED; PG8_LDA(At, 1, 0);
;         PG8_WAIT_V(6); PG8_WAIT_L(0); PG8_BAR; __builtin_amdgcn_s_setprio(1); PG8_MMA(0, 0, At, B0); __builtin_amdgcn_s_setprio(0); PG8_BAR; PG8_SCHED;
;         PG8_STAGE(PG8_SB(1, 0), b3, voffB); PG8_STAGE(PG8_SB(1, 1), b3 + hstep, voffB); PG8_STAGE(PG8_SA(1, 0), a3, voffA);
;         PG8_WAIT_V(6); PG8_BAR; __builtin_amdgcn_s_setprio(1); PG8_MMA(0, 1, At, B1); __builtin_amdgcn_s_setprio(0); PG8_BAR; PG8_SCHED;
;     }
	ds_read_b128 v[48:51], v35
	ds_read_b128 v[68:71], v35 offset:1024
	ds_read_b128 v[72:75], v35 offset:2048
	ds_read_b128 v[76:79], v35 offset:3072
	ds_read_b128 v[88:91], v36
	ds_read_b128 v[92:95], v36 offset:1024
	ds_read_b128 v[104:107], v36 offset:2048
	ds_read_b128 v[108:111], v36 offset:3072
	ds_read_b128 v[112:115], v34 offset:32768
	ds_read_b128 v[116:119], v34 offset:33792
	ds_read_b128 v[120:123], v34 offset:34816
	ds_read_b128 v[124:127], v34 offset:35840
	ds_read_b128 v[128:131], v34 offset:36864
	ds_read_b128 v[132:135], v34 offset:37888
	ds_read_b128 v[136:139], v34 offset:38912
	ds_read_b128 v[140:143], v34 offset:39936
	s_waitcnt vmcnt(6)
	s_waitcnt lgkmcnt(0)
	s_barrier
	v_mfma_f32_16x16x32_bf16 v[20:23], v[48:51], v[112:115], v[20:23]
	v_mfma_f32_16x16x32_bf16 v[16:19], v[72:75], v[112:115], v[16:19]
	v_mfma_f32_16x16x32_bf16 v[100:103], v[48:51], v[120:123], v[100:103]
	v_mfma_f32_16x16x32_bf16 v[96:99], v[72:75], v[120:123], v[96:99]
	v_mfma_f32_16x16x32_bf16 v[84:87], v[48:51], v[128:131], v[84:87]
	v_mfma_f32_16x16x32_bf16 v[80:83], v[72:75], v[128:131], v[80:83]
	v_mfma_f32_16x16x32_bf16 v[12:15], v[48:51], v[136:139], v[12:15]
	v_mfma_f32_16x16x32_bf16 v[8:11], v[72:75], v[136:139], v[8:11]
	v_mfma_f32_16x16x32_bf16 v[20:23], v[68:71], v[116:119], v[20:23]
	v_mfma_f32_16x16x32_bf16 v[16:19], v[76:79], v[116:119], v[16:19]
	v_mfma_f32_16x16x32_bf16 v[100:103], v[68:71], v[124:127], v[100:103]
	v_mfma_f32_16x16x32_bf16 v[96:99], v[76:79], v[124:127], v[96:99]
	v_mfma_f32_16x16x32_bf16 v[84:87], v[68:71], v[132:135], v[84:87]
	v_mfma_f32_16x16x32_bf16 v[80:83], v[76:79], v[132:135], v[80:83]
	v_mfma_f32_16x16x32_bf16 v[12:15], v[68:71], v[140:143], v[12:15]
	v_mfma_f32_16x16x32_bf16 v[8:11], v[76:79], v[140:143], v[8:11]
	s_barrier
	s_mov_b32 m0, s45
	v_lshl_add_u64 v[42:43], v[144:145], 0, s[10:11]
	s_add_u32 s26, s26, 0x80080
	global_load_lds_dwordx4 v[42:43], off
	v_lshl_add_u64 v[42:43], v[146:147], 0, s[10:11]
	s_mov_b32 m0, s46
	s_addc_u32 s27, s27, 0
	global_load_lds_dwordx4 v[42:43], off
	v_lshl_add_u64 v[42:43], s[26:27], 0, v[26:27]
	s_mov_b32 m0, s47
	s_nop 0
	global_load_lds_dwordx4 v[42:43], off
	v_lshl_add_u64 v[42:43], s[26:27], 0, v[30:31]
	s_mov_b32 m0, s48
	s_nop 0
	global_load_lds_dwordx4 v[42:43], off
	v_lshl_add_u64 v[42:43], v[148:149], 0, s[10:11]
	s_mov_b32 m0, s34
	s_nop 0
	global_load_lds_dwordx4 v[42:43], off
	v_lshl_add_u64 v[42:43], v[150:151], 0, s[10:11]
	s_mov_b32 m0, s35
	s_nop 0
	global_load_lds_dwordx4 v[42:43], off
	s_waitcnt vmcnt(6)
	s_barrier
	v_mfma_f32_16x16x32_bf16 v[44:47], v[104:107], v[112:115], v[44:47]
	v_mfma_f32_16x16x32_bf16 v[48:51], v[108:111], v[116:119], v[44:47]
	v_mfma_f32_16x16x32_bf16 v[44:47], v[88:91], v[120:123], v[52:55]
	v_mfma_f32_16x16x32_bf16 v[76:79], v[92:95], v[124:127], v[44:47]
	v_mfma_f32_16x16x32_bf16 v[44:47], v[104:107], v[120:123], v[56:59]
	v_mfma_f32_16x16x32_bf16 v[72:75], v[108:111], v[124:127], v[44:47]
	v_mfma_f32_16x16x32_bf16 v[44:47], v[88:91], v[128:131], v[64:67]
	v_mfma_f32_16x16x32_bf16 v[38:41], v[88:91], v[112:115], v[38:41]
	v_mfma_f32_16x16x32_bf16 v[68:71], v[92:95], v[132:135], v[44:47]
	v_mfma_f32_16x16x32_bf16 v[44:47], v[104:107], v[128:131], v[60:63]
	v_mfma_f32_16x16x32_bf16 v[4:7], v[88:91], v[136:139], v[4:7]
	v_mfma_f32_16x16x32_bf16 v[0:3], v[104:107], v[136:139], v[0:3]
	v_mfma_f32_16x16x32_bf16 v[40:43], v[92:95], v[116:119], v[38:41]
	v_mfma_f32_16x16x32_bf16 v[60:63], v[108:111], v[132:135], v[44:47]
	v_mfma_f32_16x16x32_bf16 v[4:7], v[92:95], v[140:143], v[4:7]
	v_mfma_f32_16x16x32_bf16 v[0:3], v[108:111], v[140:143], v[0:3]
	s_barrier
	s_add_i32 s38, s38, 2
	s_add_u32 s36, s36, 0x100
	s_addc_u32 s37, s37, 0
	s_add_u32 s28, s28, 0x100
	s_addc_u32 s29, s29, 0
	s_cmp_gt_u32 s38, 29
	s_cbranch_scc0 .LBB0_888
	s_cmpk_lt_u32 s30, 0x100
	s_cselect_b64 s[26:27], -1, 0
	s_and_b64 vcc, exec, s[26:27]
	s_cbranch_vccz .LBB0_891
	s_barrier

; #define PG8_STAGE(bufoff, gbase, voff) do { _Pragma("unroll") for (int _i = 0; _i < 2; ++_i) \
;         __builtin_amdgcn_global_load_lds((const unsigned*)((const char*)(gbase) + (voff)[_i]), (PG8_LAS unsigned*)(lds + (bufoff) + ldsw + _i * 8192), 16, 0, 0); } while (0)
; #define PG8_LDA(dst, b, h) do { _Pragma("unroll") for (int m = 0; m < 4; ++m) _Pragma("unroll") for (int k = 0; k < 2; ++k) dst[m][k] = *(const PG8_LAS bf16x8*)(lds + PG8_SA(b, h) + aoff + m * 2048 + k * 1024); } while (0)
; #define PG8_LDB(dst, b, h) do { _Pragma("unroll") for (int n = 0; n < 2; ++n) _Pragma("unroll") for (int k = 0; k < 2; ++k) dst[n][k] = *(const PG8_LAS bf16x8*)(lds + PG8_SB(b, h) + boff + n * 2048 + k * 1024); } while (0)
; #define PG8_MMA(ai, bj, At, Bt) do { _Pragma("unroll") for (int m = 0; m < 4; ++m) _Pragma("unroll") for (int n = 0; n < 2; ++n) _Pragma("unroll") for (int k = 0; k < 2; ++k) \
;         acc[ai][bj][m][n] = __builtin_amdgcn_mfma_f32_16x16x32_bf16(Bt[n][k], At[m][k], acc[ai][bj][m][n], 0, 0, 0); } while (0)
; #define PG8_WAIT_V(n) asm volatile("s_waitcnt vmcnt(" #n ")" ::: "memory")
; #define PG8_WAIT_L(n) asm volatile("s_waitcnt lgkmcnt(" #n ")" ::: "memory")
; #define PG8_BAR __builtin_amdgcn_s_barrier()
; #define PG8_SCHED __builtin_amdgcn_sched_barrier(0)
; template <class Epi, class Sched, bool ALIGN_EPI = false, bool SP2 = false>
; __device__ __forceinline__ void gemm_phase(PG8_LAS unsigned char* lds, const Gemm g, const Sched& S, const Epi& E, const int wave_id_in) {
;     ...
;             PG8_LDB(B0, 0, 0); PG8_LDB(B1, 0, 1); PG8_SCHED; PG8_LDA(At, 0, 0); PG8_STAGE(PG8_SA(1, 1), a1 + hstep, voffA);
;             PG8_WAIT_V(8); PG8_WAIT_L(0); PG8_BAR; __builtin_amdgcn_s_setprio(1); PG8_MMA(0, 0, At, B0); PG8_MMA(0, 1, At, B1); __builtin_amdgcn_s_setprio(0); PG8_BAR; PG8_SCHED;
;             PG8_LDA(At, 0, 1); PG8_STAGE(PG8_SB(0, 0), b2, voffB); PG8_STAGE(PG8_SB(0, 1), b2 + hstep, voffB); PG8_STAGE(PG8_SA(0, 0), a2, voffA);
;             PG8_WAIT_V(8); PG8_WAIT_L(0); PG8_BAR; __builtin_amdgcn_s_setprio(1); PG8_MMA(1, 0, At, B0); PG8_MMA(1, 1, At, B1); __builtin_amdgcn_s_setprio(0); PG8_BAR; PG8_SCHED;
.LBB0_1022:
	ds_read_b128 v[128:131], v201
	ds_read_b128 v[132:135], v201 offset:1024
	ds_read_b128 v[136:139], v201 offset:2048
	ds_read_b128 v[140:143], v201 offset:3072
	ds_read_b128 v[144:147], v202
	ds_read_b128 v[148:151], v202 offset:1024
	ds_read_b128 v[152:155], v202 offset:2048
	ds_read_b128 v[156:159], v202 offset:3072
	s_add_u32 s24, s22, 0x100
	s_addc_u32 s25, s23, 0
	s_cmpk_eq_i32 s55, 0x54
	s_cselect_b32 s29, s5, s25
	s_cselect_b32 s28, s4, s24
	s_cselect_b32 s27, s21, s54
	s_cselect_b32 s26, s20, s53
	v_lshl_add_u64 v[212:213], s[22:23], 0, v[192:193]
	s_add_i32 m0, s35, 0xc000
	ds_read_b128 v[160:163], v203
	ds_read_b128 v[164:167], v203 offset:1024
	ds_read_b128 v[168:171], v203 offset:2048
	ds_read_b128 v[172:175], v203 offset:3072
	ds_read_b128 v[176:179], v203 offset:4096
	ds_read_b128 v[180:183], v203 offset:5120
	ds_read_b128 v[204:207], v203 offset:6144
	ds_read_b128 v[208:211], v203 offset:7168
	global_load_lds_dwordx4 v[212:213], off
	v_lshl_add_u64 v[212:213], s[22:23], 0, v[194:195]
	s_add_i32 m0, s35, 0xe000
	s_nop 0
	global_load_lds_dwordx4 v[212:213], off
	s_waitcnt vmcnt(8)
	s_waitcnt lgkmcnt(0)
	s_barrier
	v_mfma_f32_16x16x32_bf16 v[124:127], v[128:131], v[160:163], v[124:127]
	v_mfma_f32_16x16x32_bf16 v[120:123], v[136:139], v[160:163], v[120:123]
	v_mfma_f32_16x16x32_bf16 v[112:115], v[128:131], v[168:171], v[112:115]
	v_mfma_f32_16x16x32_bf16 v[104:107], v[136:139], v[168:171], v[104:107]
	v_mfma_f32_16x16x32_bf16 v[96:99], v[128:131], v[176:179], v[96:99]
	v_mfma_f32_16x16x32_bf16 v[88:91], v[136:139], v[176:179], v[88:91]
	v_mfma_f32_16x16x32_bf16 v[80:83], v[128:131], v[204:207], v[80:83]
	v_mfma_f32_16x16x32_bf16 v[72:75], v[136:139], v[204:207], v[72:75]
	v_mfma_f32_16x16x32_bf16 v[116:119], v[144:147], v[160:163], v[116:119]
	v_mfma_f32_16x16x32_bf16 v[108:111], v[152:155], v[160:163], v[108:111]
	v_mfma_f32_16x16x32_bf16 v[100:103], v[144:147], v[168:171], v[100:103]
	v_mfma_f32_16x16x32_bf16 v[92:95], v[152:155], v[168:171], v[92:95]
	v_mfma_f32_16x16x32_bf16 v[84:87], v[144:147], v[176:179], v[84:87]
	v_mfma_f32_16x16x32_bf16 v[76:79], v[152:155], v[176:179], v[76:79]
	v_mfma_f32_16x16x32_bf16 v[68:71], v[144:147], v[204:207], v[68:71]
	v_mfma_f32_16x16x32_bf16 v[64:67], v[152:155], v[204:207], v[64:67]
	v_mfma_f32_16x16x32_bf16 v[124:127], v[132:135], v[164:167], v[124:127]
	v_mfma_f32_16x16x32_bf16 v[120:123], v[140:143], v[164:167], v[120:123]
	v_mfma_f32_16x16x32_bf16 v[112:115], v[132:135], v[172:175], v[112:115]
	v_mfma_f32_16x16x32_bf16 v[104:107], v[140:143], v[172:175], v[104:107]
	v_mfma_f32_16x16x32_bf16 v[96:99], v[132:135], v[180:183], v[96:99]
	v_mfma_f32_16x16x32_bf16 v[88:91], v[140:143], v[180:183], v[88:91]
	v_mfma_f32_16x16x32_bf16 v[80:83], v[132:135], v[208:211], v[80:83]
	v_mfma_f32_16x16x32_bf16 v[72:75], v[140:143], v[208:211], v[72:75]
	v_mfma_f32_16x16x32_bf16 v[116:119], v[148:151], v[164:167], v[116:119]
	v_mfma_f32_16x16x32_bf16 v[108:111], v[156:159], v[164:167], v[108:111]
	v_mfma_f32_16x16x32_bf16 v[100:103], v[148:151], v[172:175], v[100:103]
	v_mfma_f32_16x16x32_bf16 v[92:95], v[156:159], v[172:175], v[92:95]
	v_mfma_f32_16x16x32_bf16 v[84:87], v[148:151], v[180:183], v[84:87]
	v_mfma_f32_16x16x32_bf16 v[76:79], v[156:159], v[180:183], v[76:79]
	v_mfma_f32_16x16x32_bf16 v[68:71], v[148:151], v[208:211], v[68:71]
	v_mfma_f32_16x16x32_bf16 v[64:67], v[156:159], v[208:211], v[64:67]
	s_barrier
	s_add_i32 s22, s45, s34
	v_lshl_add_u64 v[212:213], s[26:27], 0, v[186:187]
	s_mov_b32 m0, s22
	ds_read_b128 v[160:163], v203 offset:16384
	ds_read_b128 v[164:167], v203 offset:17408
	ds_read_b128 v[168:171], v203 offset:18432
	ds_read_b128 v[172:175], v203 offset:19456
	ds_read_b128 v[176:179], v203 offset:20480
	ds_read_b128 v[180:183], v203 offset:21504
	ds_read_b128 v[204:207], v203 offset:22528
	ds_read_b128 v[208:211], v203 offset:23552
	global_load_lds_dwordx4 v[212:213], off
	s_add_i32 m0, s22, 0x2000
	s_add_u32 s22, s26, 0x160000
	v_lshl_add_u64 v[214:215], s[26:27], 0, v[190:191]
	s_addc_u32 s23, s27, 0
	s_add_i32 s59, s46, s34
	global_load_lds_dwordx4 v[214:215], off
	v_lshl_add_u64 v[216:217], s[22:23], 0, v[186:187]
	s_mov_b32 m0, s59
	v_lshl_add_u64 v[218:219], s[28:29], 0, v[188:189]
	global_load_lds_dwordx4 v[216:217], off
	v_lshl_add_u64 v[216:217], s[22:23], 0, v[190:191]
	s_add_i32 m0, s59, 0x2000
	s_nop 0
	global_load_lds_dwordx4 v[216:217], off
	v_lshl_add_u64 v[216:217], s[28:29], 0, v[184:185]
	s_mov_b32 m0, s35
	s_nop 0
	global_load_lds_dwordx4 v[216:217], off
	s_mov_b32 m0, s36
	s_nop 0
	global_load_lds_dwordx4 v[218:219], off
	s_waitcnt vmcnt(8)
	s_waitcnt lgkmcnt(0)
	s_barrier
; #define PG8_STAGE(bufoff, gbase, voff) do { _Pragma("unroll") for (int _i = 0; _i < 2; ++_i) \
;         __builtin_amdgcn_global_load_lds((const unsigned*)((const char*)(gbase) + (voff)[_i]), (PG8_LAS unsigned*)(lds + (bufoff) + ldsw + _i * 8192), 16, 0, 0); } while (0)
; #define PG8_LDA(dst, b, h) do { _Pragma("unroll") for (int m = 0; m < 4; ++m) _Pragma("unroll") for (int k = 0; k < 2; ++k) dst[m][k] = *(const PG8_LAS bf16x8*)(lds + PG8_SA(b, h) + aoff + m * 2048 + k * 1024); } while (0)
; #define PG8_LDB(dst, b, h) do { _Pragma("unroll") for (int n = 0; n < 2; ++n) _Pragma("unroll") for (int k = 0; k < 2; ++k) dst[n][k] = *(const PG8_LAS bf16x8*)(lds + PG8_SB(b, h) + boff + n * 2048 + k * 1024); } while (0)
; #define PG8_MMA(ai, bj, At, Bt) do { _Pragma("unroll") for (int m = 0; m < 4; ++m) _Pragma("unroll") for (int n = 0; n < 2; ++n) _Pragma("unroll") for (int k = 0; k < 2; ++k) \
;         acc[ai][bj][m][n] = __builtin_amdgcn_mfma_f32_16x16x32_bf16(Bt[n][k], At[m][k], acc[ai][bj][m][n], 0, 0, 0); } while (0)
; #define PG8_WAIT_V(n) asm volatile("s_waitcnt vmcnt(" #n ")" ::: "memory")
; #define PG8_WAIT_L(n) asm volatile("s_waitcnt lgkmcnt(" #n ")" ::: "memory")
; #define PG8_BAR __builtin_amdgcn_s_barrier()
; #define PG8_SCHED __builtin_amdgcn_sched_barrier(0)
; template <class Epi, class Sched, bool ALIGN_EPI = false, bool SP2 = false>
; __device__ __forceinline__ void gemm_phase(PG8_LAS unsigned char* lds, const Gemm g, const Sched& S, const Epi& E, const int wave_id_in) {
;     ...
;             PG8_WAIT_V(8); PG8_WAIT_L(0); PG8_BAR; __builtin_amdgcn_s_setprio(1); PG8_MMA(1, 0, At, B0); PG8_MMA(1, 1, At, B1); __builtin_amdgcn_s_setprio(0); PG8_BAR; PG8_SCHED;
;             PG8_LDB(B0, 1, 0); PG8_LDB(B1, 1, 1); PG8_SCHED; PG8_LDA(At, 1, 0); PG8_STAGE(PG8_SA(0, 1), a2 + hstep, voffA);
;             PG8_WAIT_V(8); PG8_WAIT_L(0); PG8_BAR; __builtin_amdgcn_s_setprio(1); PG8_MMA(0, 0, At, B0); PG8_MMA(0, 1, At, B1); __builtin_amdgcn_s_setprio(0); PG8_BAR; PG8_SCHED;
	v_mfma_f32_16x16x32_bf16 v[60:63], v[128:131], v[160:163], v[60:63]
	v_mfma_f32_16x16x32_bf16 v[56:59], v[136:139], v[160:163], v[56:59]
	v_mfma_f32_16x16x32_bf16 v[48:51], v[128:131], v[168:171], v[48:51]
	v_mfma_f32_16x16x32_bf16 v[40:43], v[136:139], v[168:171], v[40:43]
	v_mfma_f32_16x16x32_bf16 v[32:35], v[128:131], v[176:179], v[32:35]
	v_mfma_f32_16x16x32_bf16 v[24:27], v[136:139], v[176:179], v[24:27]
	v_mfma_f32_16x16x32_bf16 v[16:19], v[128:131], v[204:207], v[16:19]
	v_mfma_f32_16x16x32_bf16 v[8:11], v[136:139], v[204:207], v[8:11]
	v_mfma_f32_16x16x32_bf16 v[52:55], v[144:147], v[160:163], v[52:55]
	v_mfma_f32_16x16x32_bf16 v[44:47], v[152:155], v[160:163], v[44:47]
	v_mfma_f32_16x16x32_bf16 v[36:39], v[144:147], v[168:171], v[36:39]
	v_mfma_f32_16x16x32_bf16 v[28:31], v[152:155], v[168:171], v[28:31]
	v_mfma_f32_16x16x32_bf16 v[20:23], v[144:147], v[176:179], v[20:23]
	v_mfma_f32_16x16x32_bf16 v[12:15], v[152:155], v[176:179], v[12:15]
	v_mfma_f32_16x16x32_bf16 v[4:7], v[144:147], v[204:207], v[4:7]
	v_mfma_f32_16x16x32_bf16 v[0:3], v[152:155], v[204:207], v[0:3]
	v_mfma_f32_16x16x32_bf16 v[60:63], v[132:135], v[164:167], v[60:63]
	v_mfma_f32_16x16x32_bf16 v[56:59], v[140:143], v[164:167], v[56:59]
	v_mfma_f32_16x16x32_bf16 v[48:51], v[132:135], v[172:175], v[48:51]
	v_mfma_f32_16x16x32_bf16 v[40:43], v[140:143], v[172:175], v[40:43]
	v_mfma_f32_16x16x32_bf16 v[32:35], v[132:135], v[180:183], v[32:35]
	v_mfma_f32_16x16x32_bf16 v[24:27], v[140:143], v[180:183], v[24:27]
	v_mfma_f32_16x16x32_bf16 v[16:19], v[132:135], v[208:211], v[16:19]
	v_mfma_f32_16x16x32_bf16 v[8:11], v[140:143], v[208:211], v[8:11]
	v_mfma_f32_16x16x32_bf16 v[52:55], v[148:151], v[164:167], v[52:55]
	v_mfma_f32_16x16x32_bf16 v[44:47], v[156:159], v[164:167], v[44:47]
	v_mfma_f32_16x16x32_bf16 v[36:39], v[148:151], v[172:175], v[36:39]
	v_mfma_f32_16x16x32_bf16 v[28:31], v[156:159], v[172:175], v[28:31]
	v_mfma_f32_16x16x32_bf16 v[20:23], v[148:151], v[180:183], v[20:23]
	v_mfma_f32_16x16x32_bf16 v[12:15], v[156:159], v[180:183], v[12:15]
	v_mfma_f32_16x16x32_bf16 v[4:7], v[148:151], v[208:211], v[4:7]
	v_mfma_f32_16x16x32_bf16 v[0:3], v[156:159], v[208:211], v[0:3]
	s_barrier
	s_add_i32 s59, 0, 0x18000
	s_add_i32 s60, 0, 0x1c000
	v_add_u32_e32 v140, s59, v200
	v_add_u32_e32 v156, s60, v200
	ds_read_b128 v[128:131], v140
	ds_read_b128 v[132:135], v140 offset:1024
	ds_read_b128 v[136:139], v140 offset:2048
	ds_read_b128 v[140:143], v140 offset:3072
	ds_read_b128 v[144:147], v156
	ds_read_b128 v[148:151], v156 offset:1024
	ds_read_b128 v[152:155], v156 offset:2048
	ds_read_b128 v[156:159], v156 offset:3072
	s_add_u32 s22, s28, 0x160000
	s_addc_u32 s23, s29, 0
	s_mov_b32 m0, s37
	v_lshl_add_u64 v[220:221], s[22:23], 0, v[184:185]
	ds_read_b128 v[160:163], v203 offset:32768
	ds_read_b128 v[164:167], v203 offset:33792
	ds_read_b128 v[168:171], v203 offset:34816
	ds_read_b128 v[172:175], v203 offset:35840
	ds_read_b128 v[176:179], v203 offset:36864
	ds_read_b128 v[180:183], v203 offset:37888
	ds_read_b128 v[204:207], v203 offset:38912
	ds_read_b128 v[208:211], v203 offset:39936
	global_load_lds_dwordx4 v[220:221], off
	v_lshl_add_u64 v[220:221], s[22:23], 0, v[188:189]
	s_mov_b32 m0, s38
	s_nop 0
	global_load_lds_dwordx4 v[220:221], off
	s_waitcnt vmcnt(8)
	s_waitcnt lgkmcnt(0)
	s_barrier
	v_mfma_f32_16x16x32_bf16 v[124:127], v[128:131], v[160:163], v[124:127]
	v_mfma_f32_16x16x32_bf16 v[120:123], v[136:139], v[160:163], v[120:123]
	v_mfma_f32_16x16x32_bf16 v[112:115], v[128:131], v[168:171], v[112:115]
	v_mfma_f32_16x16x32_bf16 v[104:107], v[136:139], v[168:171], v[104:107]
	v_mfma_f32_16x16x32_bf16 v[96:99], v[128:131], v[176:179], v[96:99]
	v_mfma_f32_16x16x32_bf16 v[88:91], v[136:139], v[176:179], v[88:91]
	v_mfma_f32_16x16x32_bf16 v[80:83], v[128:131], v[204:207], v[80:83]
	v_mfma_f32_16x16x32_bf16 v[72:75], v[136:139], v[204:207], v[72:75]
	v_mfma_f32_16x16x32_bf16 v[116:119], v[144:147], v[160:163], v[116:119]
	v_mfma_f32_16x16x32_bf16 v[108:111], v[152:155], v[160:163], v[108:111]
	v_mfma_f32_16x16x32_bf16 v[100:103], v[144:147], v[168:171], v[100:103]
	v_mfma_f32_16x16x32_bf16 v[92:95], v[152:155], v[168:171], v[92:95]
	v_mfma_f32_16x16x32_bf16 v[84:87], v[144:147], v[176:179], v[84:87]
	v_mfma_f32_16x16x32_bf16 v[76:79], v[152:155], v[176:179], v[76:79]
	v_mfma_f32_16x16x32_bf16 v[68:71], v[144:147], v[204:207], v[68:71]
	v_mfma_f32_16x16x32_bf16 v[64:67], v[152:155], v[204:207], v[64:67]
	v_mfma_f32_16x16x32_bf16 v[124:127], v[132:135], v[164:167], v[124:127]
	v_mfma_f32_16x16x32_bf16 v[120:123], v[140:143], v[164:167], v[120:123]
	v_mfma_f32_16x16x32_bf16 v[112:115], v[132:135], v[172:175], v[112:115]
	v_mfma_f32_16x16x32_bf16 v[104:107], v[140:143], v[172:175], v[104:107]
	v_mfma_f32_16x16x32_bf16 v[96:99], v[132:135], v[180:183], v[96:99]
	v_mfma_f32_16x16x32_bf16 v[88:91], v[140:143], v[180:183], v[88:91]
	v_mfma_f32_16x16x32_bf16 v[80:83], v[132:135], v[208:211], v[80:83]
	v_mfma_f32_16x16x32_bf16 v[72:75], v[140:143], v[208:211], v[72:75]
	v_mfma_f32_16x16x32_bf16 v[116:119], v[148:151], v[164:167], v[116:119]
	v_mfma_f32_16x16x32_bf16 v[108:111], v[156:159], v[164:167], v[108:111]
	v_mfma_f32_16x16x32_bf16 v[100:103], v[148:151], v[172:175], v[100:103]
	v_mfma_f32_16x16x32_bf16 v[92:95], v[156:159], v[172:175], v[92:95]
	v_mfma_f32_16x16x32_bf16 v[84:87], v[148:151], v[180:183], v[84:87]
	v_mfma_f32_16x16x32_bf16 v[76:79], v[156:159], v[180:183], v[76:79]
	v_mfma_f32_16x16x32_bf16 v[68:71], v[148:151], v[208:211], v[68:71]
	v_mfma_f32_16x16x32_bf16 v[64:67], v[156:159], v[208:211], v[64:67]
	s_barrier
; #define PG8_STAGE(bufoff, gbase, voff) do { _Pragma("unroll") for (int _i = 0; _i < 2; ++_i) \
;         __builtin_amdgcn_global_load_lds((const unsigned*)((const char*)(gbase) + (voff)[_i]), (PG8_LAS unsigned*)(lds + (bufoff) + ldsw + _i * 8192), 16, 0, 0); } while (0)
; #define PG8_LDA(dst, b, h) do { _Pragma("unroll") for (int m = 0; m < 4; ++m) _Pragma("unroll") for (int k = 0; k < 2; ++k) dst[m][k] = *(const PG8_LAS bf16x8*)(lds + PG8_SA(b, h) + aoff + m * 2048 + k * 1024); } while (0)
; #define PG8_MMA(ai, bj, At, Bt) do { _Pragma("unroll") for (int m = 0; m < 4; ++m) _Pragma("unroll") for (int n = 0; n < 2; ++n) _Pragma("unroll") for (int k = 0; k < 2; ++k) \
;         acc[ai][bj][m][n] = __builtin_amdgcn_mfma_f32_16x16x32_bf16(Bt[n][k], At[m][k], acc[ai][bj][m][n], 0, 0, 0); } while (0)
; #define PG8_WAIT_V(n) asm volatile("s_waitcnt vmcnt(" #n ")" ::: "memory")
; #define PG8_WAIT_L(n) asm volatile("s_waitcnt lgkmcnt(" #n ")" ::: "memory")
; #define PG8_BAR __builtin_amdgcn_s_barrier()
; #define PG8_SCHED __builtin_amdgcn_sched_barrier(0)
; template <class Epi, class Sched, bool ALIGN_EPI = false, bool SP2 = false>
; __device__ __forceinline__ void gemm_phase(PG8_LAS unsigned char* lds, const Gemm g, const Sched& S, const Epi& E, const int wave_id_in) {
;     ...
;         for (int t = 0; t < nt; t += 2) {
;             const bool last = (t == nt - 2);
;             const char* a1 = cA + (size_t)(t + 1) * kstep;
;             const char* a2 = last ? nA : cA + (size_t)(t + 2) * kstep; const char* b2 = last ? nB : cB + (size_t)(t + 2) * kstep;
;             const char* a3 = a2 + kstep; const char* b3 = b2 + kstep;
;     ...
;             PG8_LDA(At, 1, 1); PG8_STAGE(PG8_SB(1, 0), b3, voffB); PG8_STAGE(PG8_SB(1, 1), b3 + hstep, voffB); PG8_STAGE(PG8_SA(1, 0), a3, voffA);
;             PG8_WAIT_V(8); PG8_WAIT_L(0); PG8_BAR; __builtin_amdgcn_s_setprio(1); PG8_MMA(1, 0, At, B0); PG8_MMA(1, 1, At, B1); __builtin_amdgcn_s_setprio(0); PG8_BAR; PG8_SCHED;
	s_add_i32 s22, s59, s34
	v_lshl_add_u64 v[212:213], v[212:213], 0, s[8:9]
	s_mov_b32 m0, s22
	ds_read_b128 v[160:163], v203 offset:49152
	ds_read_b128 v[164:167], v203 offset:50176
	ds_read_b128 v[168:171], v203 offset:51200
	ds_read_b128 v[172:175], v203 offset:52224
	ds_read_b128 v[176:179], v203 offset:53248
	ds_read_b128 v[180:183], v203 offset:54272
	ds_read_b128 v[204:207], v203 offset:55296
	ds_read_b128 v[208:211], v203 offset:56320
	global_load_lds_dwordx4 v[212:213], off
	s_add_i32 m0, s22, 0x2000
	s_add_u32 s22, s26, 0x160080
	v_lshl_add_u64 v[212:213], v[214:215], 0, s[8:9]
	s_addc_u32 s23, s27, 0
	s_add_i32 s26, s60, s34
	global_load_lds_dwordx4 v[212:213], off
	v_lshl_add_u64 v[212:213], s[22:23], 0, v[186:187]
	s_mov_b32 m0, s26
	s_nop 0
	global_load_lds_dwordx4 v[212:213], off
	v_lshl_add_u64 v[212:213], s[22:23], 0, v[190:191]
	s_add_i32 m0, s26, 0x2000
	s_nop 0
	global_load_lds_dwordx4 v[212:213], off
	v_lshl_add_u64 v[212:213], v[216:217], 0, s[8:9]
	s_mov_b32 m0, s41
	s_nop 0
	global_load_lds_dwordx4 v[212:213], off
	v_lshl_add_u64 v[212:213], v[218:219], 0, s[8:9]
	s_mov_b32 m0, s42
	s_nop 0
	global_load_lds_dwordx4 v[212:213], off
	s_waitcnt vmcnt(8)
	s_waitcnt lgkmcnt(0)
	s_barrier
	v_mfma_f32_16x16x32_bf16 v[60:63], v[128:131], v[160:163], v[60:63]
	v_mfma_f32_16x16x32_bf16 v[56:59], v[136:139], v[160:163], v[56:59]
	v_mfma_f32_16x16x32_bf16 v[48:51], v[128:131], v[168:171], v[48:51]
	v_mfma_f32_16x16x32_bf16 v[40:43], v[136:139], v[168:171], v[40:43]
	v_mfma_f32_16x16x32_bf16 v[32:35], v[128:131], v[176:179], v[32:35]
	v_mfma_f32_16x16x32_bf16 v[24:27], v[136:139], v[176:179], v[24:27]
	v_mfma_f32_16x16x32_bf16 v[16:19], v[128:131], v[204:207], v[16:19]
	v_mfma_f32_16x16x32_bf16 v[8:11], v[136:139], v[204:207], v[8:11]
	v_mfma_f32_16x16x32_bf16 v[52:55], v[144:147], v[160:163], v[52:55]
	v_mfma_f32_16x16x32_bf16 v[44:47], v[152:155], v[160:163], v[44:47]
	v_mfma_f32_16x16x32_bf16 v[36:39], v[144:147], v[168:171], v[36:39]
	v_mfma_f32_16x16x32_bf16 v[28:31], v[152:155], v[168:171], v[28:31]
	v_mfma_f32_16x16x32_bf16 v[20:23], v[144:147], v[176:179], v[20:23]
	v_mfma_f32_16x16x32_bf16 v[12:15], v[152:155], v[176:179], v[12:15]
	v_mfma_f32_16x16x32_bf16 v[4:7], v[144:147], v[204:207], v[4:7]
	v_mfma_f32_16x16x32_bf16 v[0:3], v[152:155], v[204:207], v[0:3]
	v_mfma_f32_16x16x32_bf16 v[60:63], v[132:135], v[164:167], v[60:63]
	v_mfma_f32_16x16x32_bf16 v[56:59], v[140:143], v[164:167], v[56:59]
	v_mfma_f32_16x16x32_bf16 v[48:51], v[132:135], v[172:175], v[48:51]
	v_mfma_f32_16x16x32_bf16 v[40:43], v[140:143], v[172:175], v[40:43]
	v_mfma_f32_16x16x32_bf16 v[32:35], v[132:135], v[180:183], v[32:35]
	v_mfma_f32_16x16x32_bf16 v[24:27], v[140:143], v[180:183], v[24:27]
	v_mfma_f32_16x16x32_bf16 v[16:19], v[132:135], v[208:211], v[16:19]
	v_mfma_f32_16x16x32_bf16 v[8:11], v[140:143], v[208:211], v[8:11]
	v_mfma_f32_16x16x32_bf16 v[52:55], v[148:151], v[164:167], v[52:55]
	v_mfma_f32_16x16x32_bf16 v[44:47], v[156:159], v[164:167], v[44:47]
	v_mfma_f32_16x16x32_bf16 v[36:39], v[148:151], v[172:175], v[36:39]
	v_mfma_f32_16x16x32_bf16 v[28:31], v[156:159], v[172:175], v[28:31]
	v_mfma_f32_16x16x32_bf16 v[20:23], v[148:151], v[180:183], v[20:23]
	v_mfma_f32_16x16x32_bf16 v[12:15], v[156:159], v[180:183], v[12:15]
	v_mfma_f32_16x16x32_bf16 v[4:7], v[148:151], v[208:211], v[4:7]
	v_mfma_f32_16x16x32_bf16 v[0:3], v[156:159], v[208:211], v[0:3]
	s_barrier
	s_add_i32 s55, s55, 2
	s_add_u32 s53, s53, 0x100
	s_addc_u32 s54, s54, 0
	s_cmpk_gt_u32 s55, 0x55
	s_mov_b64 s[22:23], s[24:25]
	s_cbranch_scc0 .LBB0_1022
	s_and_b64 vcc, exec, s[10:11]
	s_cbranch_vccz .LBB0_1025
	s_barrier
